# 4-phase GEMM loops, stagings first, ph4 staging moved between M3 and M4 (earlier issue, lighter phase-3 load segment)
# baseline (speedup 1.0000x reference)
; #define PG8_STAGE(bufoff, gbase, voff) do { _Pragma("unroll") for (int _i = 0; _i < 2; ++_i) \
;         __builtin_amdgcn_global_load_lds((const unsigned*)((const char*)(gbase) + (voff)[_i]), (LAS unsigned*)(lds + (bufoff) + ldsw + _i * 8192), 16, 0, 0); } while (0)
; #define PG8_LDA(dst, b, h) do { _Pragma("unroll") for (int m = 0; m < 4; ++m) _Pragma("unroll") for (int k = 0; k < 2; ++k) dst[m][k] = *(const LAS bf16x8*)(lds + PG8_SA(b, h) + aoff + m * 2048 + k * 1024); } while (0)
; #define PG8_LDB(dst, b, h) do { _Pragma("unroll") for (int n = 0; n < 2; ++n) _Pragma("unroll") for (int k = 0; k < 2; ++k) dst[n][k] = *(const LAS bf16x8*)(lds + PG8_SB(b, h) + boff + n * 2048 + k * 1024); } while (0)
; #define PG8_MMA(ai, bj, At, Bt) do { __builtin_amdgcn_s_setprio(1); _Pragma("unroll") for (int m = 0; m < 4; ++m) _Pragma("unroll") for (int n = 0; n < 2; ++n) _Pragma("unroll") for (int k = 0; k < 2; ++k) \
;         acc[ai][bj][m][n] = __builtin_amdgcn_mfma_f32_16x16x32_bf16(Bt[n][k], At[m][k], acc[ai][bj][m][n], 0, 0, 0); __builtin_amdgcn_s_setprio(0); } while (0)
; #define PG8_WAIT_V(n) asm volatile("s_waitcnt vmcnt(" #n ")" ::: "memory")
; #define PG8_WAIT_L(n) asm volatile("s_waitcnt lgkmcnt(" #n ")" ::: "memory")
; template <class Epi, class Sched>
; __device__ __forceinline__ void gemm_phase(LAS unsigned char* lds, const Gemm g, const Sched& S, const Epi& E) {
;     ...
;         for (int t = 0; t < nt; t += 2) {
;             const bool last = (t == nt - 2);
;             const char* a1 = cA + (size_t)(t + 1) * kstep;
;             const char* a2 = last ? nA : cA + (size_t)(t + 2) * kstep; const char* b2 = last ? nB : cB + (size_t)(t + 2) * kstep;
;             const char* a3 = a2 + kstep; const char* b3 = b2 + kstep;
;             PG8_LDB(B0, 0, 0); PG8_SCHED; PG8_LDA(At, 0, 0); PG8_STAGE(PG8_SA(1, 1), a1 + hstep, voffA);
;             PG8_WAIT_L(8); PG8_BAR; PG8_WAIT_L(0); PG8_MMA(0, 0, At, B0); PG8_BAR; PG8_SCHED;
;             PG8_LDB(B1, 0, 1); PG8_STAGE(PG8_SB(0, 0), b2, voffB);
;             PG8_BAR; PG8_WAIT_L(0); PG8_MMA(0, 1, At, B1); PG8_BAR;
;             PG8_LDA(At, 0, 1); PG8_STAGE(PG8_SA(0, 0), a2, voffA);
;             PG8_BAR; PG8_WAIT_L(0); PG8_MMA(1, 0, At, B0); PG8_BAR; PG8_SCHED;
;             PG8_STAGE(PG8_SB(0, 1), b2 + hstep, voffB);
;             PG8_WAIT_V(6); PG8_BAR; PG8_MMA(1, 1, At, B1); PG8_BAR;
.LBB0_44:
	s_add_u32 s50, s28, 0x100
	s_addc_u32 s51, s29, 0
	s_cmpk_eq_i32 s75, 0x7c
	s_cselect_b32 s55, s27, s51
	s_cselect_b32 s54, s71, s50
	s_cselect_b32 s53, s25, s74
	s_cselect_b32 s52, s72, s73
	v_lshl_add_u64 v[156:157], s[28:29], 0, v[150:151]
	s_add_i32 m0, s9, 0xc000
	s_nop 0
	global_load_lds_dwordx4 v[156:157], off
	v_lshl_add_u64 v[156:157], s[28:29], 0, v[148:149]
	s_add_i32 m0, s9, 0xe000
	s_nop 0
	global_load_lds_dwordx4 v[156:157], off
	s_add_i32 s38, 0, 0x10000
	v_add_u32_e32 v78, s38, v163
	ds_read_b128 v[66:69], v78
	ds_read_b128 v[70:73], v78 offset:1024
	ds_read_b128 v[74:77], v78 offset:2048
	ds_read_b128 v[78:81], v78 offset:3072
	ds_read_b128 v[152:155], v165
	ds_read_b128 v[166:169], v165 offset:1024
	ds_read_b128 v[170:173], v165 offset:2048
	ds_read_b128 v[174:177], v165 offset:3072
	ds_read_b128 v[178:181], v165 offset:4096
	ds_read_b128 v[182:185], v165 offset:5120
	ds_read_b128 v[186:189], v165 offset:6144
	ds_read_b128 v[190:193], v165 offset:7168
	s_add_i32 s39, 0, 0x14000
	v_add_u32_e32 v156, s39, v163
	ds_read_b128 v[194:197], v156
	ds_read_b128 v[198:201], v156 offset:1024
	ds_read_b128 v[202:205], v156 offset:2048
	ds_read_b128 v[210:213], v156 offset:3072
	s_waitcnt lgkmcnt(4)
	s_barrier
	s_waitcnt lgkmcnt(0)
	s_setprio 1
	v_mfma_f32_16x16x32_bf16 v[142:145], v[66:69], v[152:155], v[142:145]
	v_mfma_f32_16x16x32_bf16 v[138:141], v[74:77], v[152:155], v[138:141]
	v_mfma_f32_16x16x32_bf16 v[126:129], v[66:69], v[170:173], v[126:129]
	v_mfma_f32_16x16x32_bf16 v[122:125], v[74:77], v[170:173], v[122:125]
	v_mfma_f32_16x16x32_bf16 v[110:113], v[66:69], v[178:181], v[110:113]
	v_mfma_f32_16x16x32_bf16 v[106:109], v[74:77], v[178:181], v[106:109]
	v_mfma_f32_16x16x32_bf16 v[102:105], v[66:69], v[186:189], v[102:105]
	v_mfma_f32_16x16x32_bf16 v[98:101], v[74:77], v[186:189], v[98:101]
	v_mfma_f32_16x16x32_bf16 v[142:145], v[70:73], v[166:169], v[142:145]
	v_mfma_f32_16x16x32_bf16 v[138:141], v[78:81], v[166:169], v[138:141]
	v_mfma_f32_16x16x32_bf16 v[126:129], v[70:73], v[174:177], v[126:129]
	v_mfma_f32_16x16x32_bf16 v[122:125], v[78:81], v[174:177], v[122:125]
	v_mfma_f32_16x16x32_bf16 v[110:113], v[70:73], v[182:185], v[110:113]
	v_mfma_f32_16x16x32_bf16 v[106:109], v[78:81], v[182:185], v[106:109]
	v_mfma_f32_16x16x32_bf16 v[102:105], v[70:73], v[190:193], v[102:105]
	v_mfma_f32_16x16x32_bf16 v[98:101], v[78:81], v[190:193], v[98:101]
	v_mfma_f32_16x16x32_bf16 v[134:137], v[194:197], v[152:155], v[134:137]
	v_mfma_f32_16x16x32_bf16 v[130:133], v[202:205], v[152:155], v[130:133]
	v_mfma_f32_16x16x32_bf16 v[118:121], v[194:197], v[170:173], v[118:121]
	v_mfma_f32_16x16x32_bf16 v[114:117], v[202:205], v[170:173], v[114:117]
	v_mfma_f32_16x16x32_bf16 v[94:97], v[194:197], v[178:181], v[94:97]
	v_mfma_f32_16x16x32_bf16 v[90:93], v[202:205], v[178:181], v[90:93]
	v_mfma_f32_16x16x32_bf16 v[86:89], v[194:197], v[186:189], v[86:89]
	v_mfma_f32_16x16x32_bf16 v[82:85], v[202:205], v[186:189], v[82:85]
	v_mfma_f32_16x16x32_bf16 v[134:137], v[198:201], v[166:169], v[134:137]
	v_mfma_f32_16x16x32_bf16 v[130:133], v[210:213], v[166:169], v[130:133]
	v_mfma_f32_16x16x32_bf16 v[118:121], v[198:201], v[174:177], v[118:121]
	v_mfma_f32_16x16x32_bf16 v[114:117], v[210:213], v[174:177], v[114:117]
	v_mfma_f32_16x16x32_bf16 v[94:97], v[198:201], v[182:185], v[94:97]
	v_mfma_f32_16x16x32_bf16 v[90:93], v[210:213], v[182:185], v[90:93]
	v_mfma_f32_16x16x32_bf16 v[86:89], v[198:201], v[190:193], v[86:89]
	v_mfma_f32_16x16x32_bf16 v[82:85], v[210:213], v[190:193], v[82:85]
	s_setprio 0
	s_barrier
	s_add_i32 s28, s38, s60
	v_lshl_add_u64 v[156:157], s[52:53], 0, v[0:1]
	s_mov_b32 m0, s28
	v_lshl_add_u64 v[160:161], s[52:53], 0, v[146:147]
	global_load_lds_dwordx4 v[156:157], off
	s_add_i32 m0, s28, 0x2000
	s_nop 0
	global_load_lds_dwordx4 v[160:161], off
	s_mov_b32 m0, s9
	v_lshl_add_u64 v[206:207], s[54:55], 0, v[0:1]
	global_load_lds_dwordx4 v[206:207], off
	v_lshl_add_u64 v[214:215], s[54:55], 0, v[146:147]
	s_mov_b32 m0, s61
	s_nop 0
	global_load_lds_dwordx4 v[214:215], off
	ds_read_b128 v[152:155], v165 offset:16384
	ds_read_b128 v[166:169], v165 offset:17408
	ds_read_b128 v[170:173], v165 offset:18432
	ds_read_b128 v[174:177], v165 offset:19456
	ds_read_b128 v[178:181], v165 offset:20480
	ds_read_b128 v[182:185], v165 offset:21504
	ds_read_b128 v[186:189], v165 offset:22528
	ds_read_b128 v[190:193], v165 offset:23552
	s_waitcnt vmcnt(4)
	s_waitcnt lgkmcnt(0)
	s_barrier
; #define PG8_STAGE(bufoff, gbase, voff) do { _Pragma("unroll") for (int _i = 0; _i < 2; ++_i) \
;         __builtin_amdgcn_global_load_lds((const unsigned*)((const char*)(gbase) + (voff)[_i]), (LAS unsigned*)(lds + (bufoff) + ldsw + _i * 8192), 16, 0, 0); } while (0)
; #define PG8_LDA(dst, b, h) do { _Pragma("unroll") for (int m = 0; m < 4; ++m) _Pragma("unroll") for (int k = 0; k < 2; ++k) dst[m][k] = *(const LAS bf16x8*)(lds + PG8_SA(b, h) + aoff + m * 2048 + k * 1024); } while (0)
; #define PG8_LDB(dst, b, h) do { _Pragma("unroll") for (int n = 0; n < 2; ++n) _Pragma("unroll") for (int k = 0; k < 2; ++k) dst[n][k] = *(const LAS bf16x8*)(lds + PG8_SB(b, h) + boff + n * 2048 + k * 1024); } while (0)
; #define PG8_MMA(ai, bj, At, Bt) do { __builtin_amdgcn_s_setprio(1); _Pragma("unroll") for (int m = 0; m < 4; ++m) _Pragma("unroll") for (int n = 0; n < 2; ++n) _Pragma("unroll") for (int k = 0; k < 2; ++k) \
;         acc[ai][bj][m][n] = __builtin_amdgcn_mfma_f32_16x16x32_bf16(Bt[n][k], At[m][k], acc[ai][bj][m][n], 0, 0, 0); __builtin_amdgcn_s_setprio(0); } while (0)
; #define PG8_WAIT_V(n) asm volatile("s_waitcnt vmcnt(" #n ")" ::: "memory")
; #define PG8_WAIT_L(n) asm volatile("s_waitcnt lgkmcnt(" #n ")" ::: "memory")
; #define PG8_BAR __builtin_amdgcn_s_barrier()
; #define PG8_SCHED __builtin_amdgcn_sched_barrier(0)
; template <class Epi, class Sched>
; __device__ __forceinline__ void gemm_phase(LAS unsigned char* lds, const Gemm g, const Sched& S, const Epi& E) {
;     ...
;             PG8_LDB(B1, 0, 1); PG8_STAGE(PG8_SB(0, 0), b2, voffB);
;             PG8_BAR; PG8_WAIT_L(0); PG8_MMA(0, 1, At, B1); PG8_BAR;
;             PG8_LDA(At, 0, 1); PG8_STAGE(PG8_SA(0, 0), a2, voffA);
;             PG8_BAR; PG8_WAIT_L(0); PG8_MMA(1, 0, At, B0); PG8_BAR; PG8_SCHED;
;             PG8_STAGE(PG8_SB(0, 1), b2 + hstep, voffB);
;             PG8_WAIT_V(6); PG8_BAR; PG8_MMA(1, 1, At, B1); PG8_BAR;
;             PG8_LDB(B0, 1, 0); PG8_SCHED; PG8_LDA(At, 1, 0); PG8_STAGE(PG8_SA(0, 1), a2 + hstep, voffA);
	s_setprio 1
	v_mfma_f32_16x16x32_bf16 v[62:65], v[66:69], v[152:155], v[62:65]
	v_mfma_f32_16x16x32_bf16 v[58:61], v[74:77], v[152:155], v[58:61]
	v_mfma_f32_16x16x32_bf16 v[46:49], v[66:69], v[170:173], v[46:49]
	v_mfma_f32_16x16x32_bf16 v[42:45], v[74:77], v[170:173], v[42:45]
	v_mfma_f32_16x16x32_bf16 v[30:33], v[66:69], v[178:181], v[30:33]
	v_mfma_f32_16x16x32_bf16 v[26:29], v[74:77], v[178:181], v[26:29]
	v_mfma_f32_16x16x32_bf16 v[22:25], v[66:69], v[186:189], v[22:25]
	v_mfma_f32_16x16x32_bf16 v[14:17], v[74:77], v[186:189], v[14:17]
	v_mfma_f32_16x16x32_bf16 v[62:65], v[70:73], v[166:169], v[62:65]
	v_mfma_f32_16x16x32_bf16 v[58:61], v[78:81], v[166:169], v[58:61]
	v_mfma_f32_16x16x32_bf16 v[46:49], v[70:73], v[174:177], v[46:49]
	v_mfma_f32_16x16x32_bf16 v[42:45], v[78:81], v[174:177], v[42:45]
	v_mfma_f32_16x16x32_bf16 v[30:33], v[70:73], v[182:185], v[30:33]
	v_mfma_f32_16x16x32_bf16 v[26:29], v[78:81], v[182:185], v[26:29]
	v_mfma_f32_16x16x32_bf16 v[22:25], v[70:73], v[190:193], v[22:25]
	v_mfma_f32_16x16x32_bf16 v[14:17], v[78:81], v[190:193], v[14:17]
	s_add_u32 s28, s52, 0x200000
	s_addc_u32 s29, s53, 0
	s_add_i32 s38, s39, s60
	v_lshl_add_u64 v[66:67], s[28:29], 0, v[0:1]
	s_mov_b32 m0, s38
	s_nop 0
	global_load_lds_dwordx4 v[66:67], off
	v_lshl_add_u64 v[66:67], s[28:29], 0, v[146:147]
	s_add_i32 m0, s38, 0x2000
	s_nop 0
	global_load_lds_dwordx4 v[66:67], off
	v_mfma_f32_16x16x32_bf16 v[54:57], v[194:197], v[152:155], v[54:57]
	v_mfma_f32_16x16x32_bf16 v[50:53], v[202:205], v[152:155], v[50:53]
	v_mfma_f32_16x16x32_bf16 v[38:41], v[194:197], v[170:173], v[38:41]
	v_mfma_f32_16x16x32_bf16 v[34:37], v[202:205], v[170:173], v[34:37]
	v_mfma_f32_16x16x32_bf16 v[18:21], v[194:197], v[178:181], v[18:21]
	v_mfma_f32_16x16x32_bf16 v[10:13], v[202:205], v[178:181], v[10:13]
	v_mfma_f32_16x16x32_bf16 v[6:9], v[194:197], v[186:189], v[6:9]
	v_mfma_f32_16x16x32_bf16 v[2:5], v[202:205], v[186:189], v[2:5]
	v_mfma_f32_16x16x32_bf16 v[54:57], v[198:201], v[166:169], v[54:57]
	v_mfma_f32_16x16x32_bf16 v[50:53], v[210:213], v[166:169], v[50:53]
	v_mfma_f32_16x16x32_bf16 v[38:41], v[198:201], v[174:177], v[38:41]
	v_mfma_f32_16x16x32_bf16 v[34:37], v[210:213], v[174:177], v[34:37]
	v_mfma_f32_16x16x32_bf16 v[18:21], v[198:201], v[182:185], v[18:21]
	v_mfma_f32_16x16x32_bf16 v[10:13], v[210:213], v[182:185], v[10:13]
	v_mfma_f32_16x16x32_bf16 v[6:9], v[198:201], v[190:193], v[6:9]
	v_mfma_f32_16x16x32_bf16 v[2:5], v[210:213], v[190:193], v[2:5]
	s_setprio 0
	s_barrier
	s_add_u32 s28, s54, 0x200000
	s_addc_u32 s29, s55, 0
	s_mov_b32 m0, s62
	v_lshl_add_u64 v[194:195], s[28:29], 0, v[0:1]
	global_load_lds_dwordx4 v[194:195], off
	v_lshl_add_u64 v[194:195], s[28:29], 0, v[146:147]
	s_mov_b32 m0, s63
	s_nop 0
	global_load_lds_dwordx4 v[194:195], off
	s_add_i32 s38, 0, 0x18000
	v_add_u32_e32 v78, s38, v163
	ds_read_b128 v[66:69], v78
	ds_read_b128 v[70:73], v78 offset:1024
	ds_read_b128 v[74:77], v78 offset:2048
	ds_read_b128 v[78:81], v78 offset:3072
	ds_read_b128 v[152:155], v165 offset:32768
	ds_read_b128 v[166:169], v165 offset:33792
	ds_read_b128 v[170:173], v165 offset:34816
	ds_read_b128 v[174:177], v165 offset:35840
	ds_read_b128 v[178:181], v165 offset:36864
	ds_read_b128 v[182:185], v165 offset:37888
	ds_read_b128 v[186:189], v165 offset:38912
	ds_read_b128 v[190:193], v165 offset:39936
	s_add_i32 s39, 0, 0x1c000
	v_add_u32_e32 v210, s39, v163
	ds_read_b128 v[194:197], v210
	ds_read_b128 v[198:201], v210 offset:1024
	ds_read_b128 v[202:205], v210 offset:2048
	ds_read_b128 v[210:213], v210 offset:3072
	s_waitcnt lgkmcnt(4)
	s_barrier
	s_waitcnt lgkmcnt(0)
	s_setprio 1
	v_mfma_f32_16x16x32_bf16 v[142:145], v[66:69], v[152:155], v[142:145]
	v_mfma_f32_16x16x32_bf16 v[138:141], v[74:77], v[152:155], v[138:141]
	v_mfma_f32_16x16x32_bf16 v[126:129], v[66:69], v[170:173], v[126:129]
	v_mfma_f32_16x16x32_bf16 v[122:125], v[74:77], v[170:173], v[122:125]
	v_mfma_f32_16x16x32_bf16 v[110:113], v[66:69], v[178:181], v[110:113]
	v_mfma_f32_16x16x32_bf16 v[106:109], v[74:77], v[178:181], v[106:109]
	v_mfma_f32_16x16x32_bf16 v[102:105], v[66:69], v[186:189], v[102:105]
	v_mfma_f32_16x16x32_bf16 v[98:101], v[74:77], v[186:189], v[98:101]
	v_mfma_f32_16x16x32_bf16 v[142:145], v[70:73], v[166:169], v[142:145]
	v_mfma_f32_16x16x32_bf16 v[138:141], v[78:81], v[166:169], v[138:141]
	v_mfma_f32_16x16x32_bf16 v[126:129], v[70:73], v[174:177], v[126:129]
	v_mfma_f32_16x16x32_bf16 v[122:125], v[78:81], v[174:177], v[122:125]
	v_mfma_f32_16x16x32_bf16 v[110:113], v[70:73], v[182:185], v[110:113]
	v_mfma_f32_16x16x32_bf16 v[106:109], v[78:81], v[182:185], v[106:109]
	v_mfma_f32_16x16x32_bf16 v[102:105], v[70:73], v[190:193], v[102:105]
	v_mfma_f32_16x16x32_bf16 v[98:101], v[78:81], v[190:193], v[98:101]
	v_mfma_f32_16x16x32_bf16 v[134:137], v[194:197], v[152:155], v[134:137]
	v_mfma_f32_16x16x32_bf16 v[130:133], v[202:205], v[152:155], v[130:133]
	v_mfma_f32_16x16x32_bf16 v[118:121], v[194:197], v[170:173], v[118:121]
	v_mfma_f32_16x16x32_bf16 v[114:117], v[202:205], v[170:173], v[114:117]
	v_mfma_f32_16x16x32_bf16 v[94:97], v[194:197], v[178:181], v[94:97]
	v_mfma_f32_16x16x32_bf16 v[90:93], v[202:205], v[178:181], v[90:93]
	v_mfma_f32_16x16x32_bf16 v[86:89], v[194:197], v[186:189], v[86:89]
	v_mfma_f32_16x16x32_bf16 v[82:85], v[202:205], v[186:189], v[82:85]
	v_mfma_f32_16x16x32_bf16 v[134:137], v[198:201], v[166:169], v[134:137]
	v_mfma_f32_16x16x32_bf16 v[130:133], v[210:213], v[166:169], v[130:133]
	v_mfma_f32_16x16x32_bf16 v[118:121], v[198:201], v[174:177], v[118:121]
	v_mfma_f32_16x16x32_bf16 v[114:117], v[210:213], v[174:177], v[114:117]
	v_mfma_f32_16x16x32_bf16 v[94:97], v[198:201], v[182:185], v[94:97]
	v_mfma_f32_16x16x32_bf16 v[90:93], v[210:213], v[182:185], v[90:93]
	v_mfma_f32_16x16x32_bf16 v[86:89], v[198:201], v[190:193], v[86:89]
	v_mfma_f32_16x16x32_bf16 v[82:85], v[210:213], v[190:193], v[82:85]
	s_setprio 0
	s_barrier
; #define PG8_STAGE(bufoff, gbase, voff) do { _Pragma("unroll") for (int _i = 0; _i < 2; ++_i) \
;         __builtin_amdgcn_global_load_lds((const unsigned*)((const char*)(gbase) + (voff)[_i]), (LAS unsigned*)(lds + (bufoff) + ldsw + _i * 8192), 16, 0, 0); } while (0)
; #define PG8_LDA(dst, b, h) do { _Pragma("unroll") for (int m = 0; m < 4; ++m) _Pragma("unroll") for (int k = 0; k < 2; ++k) dst[m][k] = *(const LAS bf16x8*)(lds + PG8_SA(b, h) + aoff + m * 2048 + k * 1024); } while (0)
; #define PG8_LDB(dst, b, h) do { _Pragma("unroll") for (int n = 0; n < 2; ++n) _Pragma("unroll") for (int k = 0; k < 2; ++k) dst[n][k] = *(const LAS bf16x8*)(lds + PG8_SB(b, h) + boff + n * 2048 + k * 1024); } while (0)
; #define PG8_MMA(ai, bj, At, Bt) do { __builtin_amdgcn_s_setprio(1); _Pragma("unroll") for (int m = 0; m < 4; ++m) _Pragma("unroll") for (int n = 0; n < 2; ++n) _Pragma("unroll") for (int k = 0; k < 2; ++k) \
;         acc[ai][bj][m][n] = __builtin_amdgcn_mfma_f32_16x16x32_bf16(Bt[n][k], At[m][k], acc[ai][bj][m][n], 0, 0, 0); __builtin_amdgcn_s_setprio(0); } while (0)
; #define PG8_WAIT_V(n) asm volatile("s_waitcnt vmcnt(" #n ")" ::: "memory")
; #define PG8_WAIT_L(n) asm volatile("s_waitcnt lgkmcnt(" #n ")" ::: "memory")
; #define PG8_BAR __builtin_amdgcn_s_barrier()
; #define PG8_SCHED __builtin_amdgcn_sched_barrier(0)
; template <class Epi, class Sched>
; __device__ __forceinline__ void gemm_phase(LAS unsigned char* lds, const Gemm g, const Sched& S, const Epi& E) {
;     ...
;             PG8_LDB(B0, 1, 0); PG8_SCHED; PG8_LDA(At, 1, 0); PG8_STAGE(PG8_SA(0, 1), a2 + hstep, voffA);
;             PG8_WAIT_L(8); PG8_BAR; PG8_WAIT_L(0); PG8_MMA(0, 0, At, B0); PG8_BAR; PG8_SCHED;
;             PG8_LDB(B1, 1, 1); PG8_STAGE(PG8_SB(1, 0), b3, voffB);
;             PG8_BAR; PG8_WAIT_L(0); PG8_MMA(0, 1, At, B1); PG8_BAR;
;             PG8_LDA(At, 1, 1); PG8_STAGE(PG8_SA(1, 0), a3, voffA);
;             PG8_BAR; PG8_WAIT_L(0); PG8_MMA(1, 0, At, B0); PG8_BAR; PG8_SCHED;
;             PG8_STAGE(PG8_SB(1, 1), b3 + hstep, voffB);
;             PG8_WAIT_V(6); PG8_BAR; PG8_MMA(1, 1, At, B1); PG8_BAR;
;         }
;         E(acc, cur, wr, wc, fr, fq);
;         if (!has_next) break;
	s_add_i32 s28, s38, s60
	v_lshl_add_u64 v[156:157], v[156:157], 0, s[36:37]
	s_mov_b32 m0, s28
	s_nop 0
	global_load_lds_dwordx4 v[156:157], off
	v_lshl_add_u64 v[156:157], v[160:161], 0, s[36:37]
	s_add_i32 m0, s28, 0x2000
	s_nop 0
	global_load_lds_dwordx4 v[156:157], off
	s_mov_b32 m0, s66
	v_lshl_add_u64 v[156:157], v[206:207], 0, s[36:37]
	global_load_lds_dwordx4 v[156:157], off
	v_lshl_add_u64 v[156:157], v[214:215], 0, s[36:37]
	s_mov_b32 m0, s67
	s_nop 0
	global_load_lds_dwordx4 v[156:157], off
	ds_read_b128 v[152:155], v165 offset:49152
	ds_read_b128 v[166:169], v165 offset:50176
	ds_read_b128 v[170:173], v165 offset:51200
	ds_read_b128 v[174:177], v165 offset:52224
	ds_read_b128 v[178:181], v165 offset:53248
	ds_read_b128 v[182:185], v165 offset:54272
	ds_read_b128 v[186:189], v165 offset:55296
	ds_read_b128 v[190:193], v165 offset:56320
	s_waitcnt vmcnt(4)
	s_waitcnt lgkmcnt(0)
	s_barrier
	s_setprio 1
	v_mfma_f32_16x16x32_bf16 v[62:65], v[66:69], v[152:155], v[62:65]
	v_mfma_f32_16x16x32_bf16 v[58:61], v[74:77], v[152:155], v[58:61]
	v_mfma_f32_16x16x32_bf16 v[46:49], v[66:69], v[170:173], v[46:49]
	v_mfma_f32_16x16x32_bf16 v[42:45], v[74:77], v[170:173], v[42:45]
	v_mfma_f32_16x16x32_bf16 v[30:33], v[66:69], v[178:181], v[30:33]
	v_mfma_f32_16x16x32_bf16 v[26:29], v[74:77], v[178:181], v[26:29]
	v_mfma_f32_16x16x32_bf16 v[22:25], v[66:69], v[186:189], v[22:25]
	v_mfma_f32_16x16x32_bf16 v[14:17], v[74:77], v[186:189], v[14:17]
	v_mfma_f32_16x16x32_bf16 v[62:65], v[70:73], v[166:169], v[62:65]
	v_mfma_f32_16x16x32_bf16 v[58:61], v[78:81], v[166:169], v[58:61]
	v_mfma_f32_16x16x32_bf16 v[46:49], v[70:73], v[174:177], v[46:49]
	v_mfma_f32_16x16x32_bf16 v[42:45], v[78:81], v[174:177], v[42:45]
	v_mfma_f32_16x16x32_bf16 v[30:33], v[70:73], v[182:185], v[30:33]
	v_mfma_f32_16x16x32_bf16 v[26:29], v[78:81], v[182:185], v[26:29]
	v_mfma_f32_16x16x32_bf16 v[22:25], v[70:73], v[190:193], v[22:25]
	v_mfma_f32_16x16x32_bf16 v[14:17], v[78:81], v[190:193], v[14:17]
	s_add_u32 s28, s52, 0x200080
	s_addc_u32 s29, s53, 0
	s_add_i32 s38, s39, s60
	v_lshl_add_u64 v[66:67], s[28:29], 0, v[0:1]
	s_mov_b32 m0, s38
	s_nop 0
	global_load_lds_dwordx4 v[66:67], off
	v_lshl_add_u64 v[66:67], s[28:29], 0, v[146:147]
	s_add_i32 m0, s38, 0x2000
	s_nop 0
	global_load_lds_dwordx4 v[66:67], off
	v_mfma_f32_16x16x32_bf16 v[54:57], v[194:197], v[152:155], v[54:57]
	v_mfma_f32_16x16x32_bf16 v[50:53], v[202:205], v[152:155], v[50:53]
	v_mfma_f32_16x16x32_bf16 v[38:41], v[194:197], v[170:173], v[38:41]
	v_mfma_f32_16x16x32_bf16 v[34:37], v[202:205], v[170:173], v[34:37]
	v_mfma_f32_16x16x32_bf16 v[18:21], v[194:197], v[178:181], v[18:21]
	v_mfma_f32_16x16x32_bf16 v[10:13], v[202:205], v[178:181], v[10:13]
	v_mfma_f32_16x16x32_bf16 v[6:9], v[194:197], v[186:189], v[6:9]
	v_mfma_f32_16x16x32_bf16 v[2:5], v[202:205], v[186:189], v[2:5]
	v_mfma_f32_16x16x32_bf16 v[54:57], v[198:201], v[166:169], v[54:57]
	v_mfma_f32_16x16x32_bf16 v[50:53], v[210:213], v[166:169], v[50:53]
	v_mfma_f32_16x16x32_bf16 v[38:41], v[198:201], v[174:177], v[38:41]
	v_mfma_f32_16x16x32_bf16 v[34:37], v[210:213], v[174:177], v[34:37]
	v_mfma_f32_16x16x32_bf16 v[18:21], v[198:201], v[182:185], v[18:21]
	v_mfma_f32_16x16x32_bf16 v[10:13], v[210:213], v[182:185], v[10:13]
	v_mfma_f32_16x16x32_bf16 v[6:9], v[198:201], v[190:193], v[6:9]
	v_mfma_f32_16x16x32_bf16 v[2:5], v[210:213], v[190:193], v[2:5]
	s_setprio 0
	s_add_i32 s75, s75, 2
	s_add_u32 s73, s73, 0x100
	s_addc_u32 s74, s74, 0
	s_cmpk_gt_u32 s75, 0x7d
	s_mov_b64 s[28:29], s[50:51]
	s_barrier
	s_cbranch_scc0 .LBB0_44
	s_cmp_lt_i32 s8, 64
	s_cselect_b64 s[50:51], -1, 0
	s_cmp_gt_i32 s8, 63
	s_cbranch_scc0 .LBB0_35
	s_mov_b64 s[52:53], 0x18000
	s_mov_b64 s[28:29], s[46:47]
	s_branch .LBB0_36

; #define PG8_STAGE(bufoff, gbase, voff) do { _Pragma("unroll") for (int _i = 0; _i < 2; ++_i) \
;         __builtin_amdgcn_global_load_lds((const unsigned*)((const char*)(gbase) + (voff)[_i]), (LAS unsigned*)(lds + (bufoff) + ldsw + _i * 8192), 16, 0, 0); } while (0)
; #define PG8_LDA(dst, b, h) do { _Pragma("unroll") for (int m = 0; m < 4; ++m) _Pragma("unroll") for (int k = 0; k < 2; ++k) dst[m][k] = *(const LAS bf16x8*)(lds + PG8_SA(b, h) + aoff + m * 2048 + k * 1024); } while (0)
; #define PG8_LDB(dst, b, h) do { _Pragma("unroll") for (int n = 0; n < 2; ++n) _Pragma("unroll") for (int k = 0; k < 2; ++k) dst[n][k] = *(const LAS bf16x8*)(lds + PG8_SB(b, h) + boff + n * 2048 + k * 1024); } while (0)
; #define PG8_MMA(ai, bj, At, Bt) do { __builtin_amdgcn_s_setprio(1); _Pragma("unroll") for (int m = 0; m < 4; ++m) _Pragma("unroll") for (int n = 0; n < 2; ++n) _Pragma("unroll") for (int k = 0; k < 2; ++k) \
;         acc[ai][bj][m][n] = __builtin_amdgcn_mfma_f32_16x16x32_bf16(Bt[n][k], At[m][k], acc[ai][bj][m][n], 0, 0, 0); __builtin_amdgcn_s_setprio(0); } while (0)
; #define PG8_WAIT_V(n) asm volatile("s_waitcnt vmcnt(" #n ")" ::: "memory")
; #define PG8_WAIT_L(n) asm volatile("s_waitcnt lgkmcnt(" #n ")" ::: "memory")
; template <class Epi, class Sched>
; __device__ __forceinline__ void gemm_phase(LAS unsigned char* lds, const Gemm g, const Sched& S, const Epi& E) {
;     ...
;         for (int t = 0; t < nt; t += 2) {
;             const bool last = (t == nt - 2);
;             const char* a1 = cA + (size_t)(t + 1) * kstep;
;             const char* a2 = last ? nA : cA + (size_t)(t + 2) * kstep; const char* b2 = last ? nB : cB + (size_t)(t + 2) * kstep;
;             const char* a3 = a2 + kstep; const char* b3 = b2 + kstep;
;             PG8_LDB(B0, 0, 0); PG8_SCHED; PG8_LDA(At, 0, 0); PG8_STAGE(PG8_SA(1, 1), a1 + hstep, voffA);
;             PG8_WAIT_L(8); PG8_BAR; PG8_WAIT_L(0); PG8_MMA(0, 0, At, B0); PG8_BAR; PG8_SCHED;
;             PG8_LDB(B1, 0, 1); PG8_STAGE(PG8_SB(0, 0), b2, voffB);
;             PG8_BAR; PG8_WAIT_L(0); PG8_MMA(0, 1, At, B1); PG8_BAR;
;             PG8_LDA(At, 0, 1); PG8_STAGE(PG8_SA(0, 0), a2, voffA);
;             PG8_BAR; PG8_WAIT_L(0); PG8_MMA(1, 0, At, B0); PG8_BAR; PG8_SCHED;
;             PG8_STAGE(PG8_SB(0, 1), b2 + hstep, voffB);
;             PG8_WAIT_V(6); PG8_BAR; PG8_MMA(1, 1, At, B1); PG8_BAR;
.LBB0_58:
	s_add_u32 s52, s50, 0x100
	s_addc_u32 s53, s51, 0
	s_cmp_eq_u32 s71, 28
	s_cselect_b32 s57, s11, s53
	s_cselect_b32 s56, s29, s52
	s_cselect_b32 s55, s41, s70
	s_cselect_b32 s54, s43, s69
	v_lshl_add_u64 v[156:157], s[50:51], 0, v[134:135]
	s_add_i32 m0, s25, 0xc000
	s_nop 0
	global_load_lds_dwordx4 v[156:157], off
	v_lshl_add_u64 v[156:157], s[50:51], 0, v[132:133]
	s_add_i32 m0, s25, 0xe000
	s_nop 0
	global_load_lds_dwordx4 v[156:157], off
	s_add_i32 s38, 0, 0x10000
	v_add_u32_e32 v152, s38, v137
	ds_read_b128 v[140:143], v152
	ds_read_b128 v[144:147], v152 offset:1024
	ds_read_b128 v[148:151], v152 offset:2048
	ds_read_b128 v[152:155], v152 offset:3072
	ds_read_b128 v[160:163], v139
	ds_read_b128 v[164:167], v139 offset:1024
	ds_read_b128 v[168:171], v139 offset:2048
	ds_read_b128 v[172:175], v139 offset:3072
	ds_read_b128 v[176:179], v139 offset:4096
	ds_read_b128 v[180:183], v139 offset:5120
	ds_read_b128 v[184:187], v139 offset:6144
	ds_read_b128 v[188:191], v139 offset:7168
	s_add_i32 s50, 0, 0x14000
	v_add_u32_e32 v156, s50, v137
	ds_read_b128 v[192:195], v156
	ds_read_b128 v[196:199], v156 offset:1024
	ds_read_b128 v[200:203], v156 offset:2048
	ds_read_b128 v[204:207], v156 offset:3072
	s_waitcnt lgkmcnt(4)
	s_barrier
	s_waitcnt lgkmcnt(0)
	s_setprio 1
	v_mfma_f32_16x16x32_bf16 v[126:129], v[140:143], v[160:163], v[126:129]
	v_mfma_f32_16x16x32_bf16 v[122:125], v[148:151], v[160:163], v[122:125]
	v_mfma_f32_16x16x32_bf16 v[118:121], v[140:143], v[168:171], v[118:121]
	v_mfma_f32_16x16x32_bf16 v[114:117], v[148:151], v[168:171], v[114:117]
	v_mfma_f32_16x16x32_bf16 v[106:109], v[140:143], v[176:179], v[106:109]
	v_mfma_f32_16x16x32_bf16 v[98:101], v[148:151], v[176:179], v[98:101]
	v_mfma_f32_16x16x32_bf16 v[90:93], v[140:143], v[184:187], v[90:93]
	v_mfma_f32_16x16x32_bf16 v[82:85], v[148:151], v[184:187], v[82:85]
	v_mfma_f32_16x16x32_bf16 v[126:129], v[144:147], v[164:167], v[126:129]
	v_mfma_f32_16x16x32_bf16 v[122:125], v[152:155], v[164:167], v[122:125]
	v_mfma_f32_16x16x32_bf16 v[118:121], v[144:147], v[172:175], v[118:121]
	v_mfma_f32_16x16x32_bf16 v[114:117], v[152:155], v[172:175], v[114:117]
	v_mfma_f32_16x16x32_bf16 v[106:109], v[144:147], v[180:183], v[106:109]
	v_mfma_f32_16x16x32_bf16 v[98:101], v[152:155], v[180:183], v[98:101]
	v_mfma_f32_16x16x32_bf16 v[90:93], v[144:147], v[188:191], v[90:93]
	v_mfma_f32_16x16x32_bf16 v[82:85], v[152:155], v[188:191], v[82:85]
	v_mfma_f32_16x16x32_bf16 v[110:113], v[192:195], v[160:163], v[110:113]
	v_mfma_f32_16x16x32_bf16 v[102:105], v[200:203], v[160:163], v[102:105]
	v_mfma_f32_16x16x32_bf16 v[94:97], v[192:195], v[168:171], v[94:97]
	v_mfma_f32_16x16x32_bf16 v[86:89], v[200:203], v[168:171], v[86:89]
	v_mfma_f32_16x16x32_bf16 v[78:81], v[192:195], v[176:179], v[78:81]
	v_mfma_f32_16x16x32_bf16 v[74:77], v[200:203], v[176:179], v[74:77]
	v_mfma_f32_16x16x32_bf16 v[70:73], v[192:195], v[184:187], v[70:73]
	v_mfma_f32_16x16x32_bf16 v[66:69], v[200:203], v[184:187], v[66:69]
	v_mfma_f32_16x16x32_bf16 v[110:113], v[196:199], v[164:167], v[110:113]
	v_mfma_f32_16x16x32_bf16 v[102:105], v[204:207], v[164:167], v[102:105]
	v_mfma_f32_16x16x32_bf16 v[94:97], v[196:199], v[172:175], v[94:97]
	v_mfma_f32_16x16x32_bf16 v[86:89], v[204:207], v[172:175], v[86:89]
	v_mfma_f32_16x16x32_bf16 v[78:81], v[196:199], v[180:183], v[78:81]
	v_mfma_f32_16x16x32_bf16 v[74:77], v[204:207], v[180:183], v[74:77]
	v_mfma_f32_16x16x32_bf16 v[70:73], v[196:199], v[188:191], v[70:73]
	v_mfma_f32_16x16x32_bf16 v[66:69], v[204:207], v[188:191], v[66:69]
	s_setprio 0
	s_barrier
	s_add_i32 s38, s38, s63
	v_lshl_add_u64 v[156:157], s[54:55], 0, v[0:1]
	s_mov_b32 m0, s38
	v_lshl_add_u64 v[210:211], s[54:55], 0, v[130:131]
	global_load_lds_dwordx4 v[156:157], off
	s_add_i32 m0, s38, 0x2000
	s_nop 0
	global_load_lds_dwordx4 v[210:211], off
	s_mov_b32 m0, s25
	v_lshl_add_u64 v[212:213], s[56:57], 0, v[0:1]
	global_load_lds_dwordx4 v[212:213], off
	v_lshl_add_u64 v[214:215], s[56:57], 0, v[130:131]
	s_mov_b32 m0, s27
	s_nop 0
	global_load_lds_dwordx4 v[214:215], off
	ds_read_b128 v[160:163], v139 offset:16384
	ds_read_b128 v[164:167], v139 offset:17408
	ds_read_b128 v[168:171], v139 offset:18432
	ds_read_b128 v[172:175], v139 offset:19456
	ds_read_b128 v[176:179], v139 offset:20480
	ds_read_b128 v[180:183], v139 offset:21504
	ds_read_b128 v[184:187], v139 offset:22528
	ds_read_b128 v[188:191], v139 offset:23552
	s_waitcnt vmcnt(4)
	s_waitcnt lgkmcnt(0)
	s_barrier
; #define PG8_STAGE(bufoff, gbase, voff) do { _Pragma("unroll") for (int _i = 0; _i < 2; ++_i) \
;         __builtin_amdgcn_global_load_lds((const unsigned*)((const char*)(gbase) + (voff)[_i]), (LAS unsigned*)(lds + (bufoff) + ldsw + _i * 8192), 16, 0, 0); } while (0)
; #define PG8_LDA(dst, b, h) do { _Pragma("unroll") for (int m = 0; m < 4; ++m) _Pragma("unroll") for (int k = 0; k < 2; ++k) dst[m][k] = *(const LAS bf16x8*)(lds + PG8_SA(b, h) + aoff + m * 2048 + k * 1024); } while (0)
; #define PG8_LDB(dst, b, h) do { _Pragma("unroll") for (int n = 0; n < 2; ++n) _Pragma("unroll") for (int k = 0; k < 2; ++k) dst[n][k] = *(const LAS bf16x8*)(lds + PG8_SB(b, h) + boff + n * 2048 + k * 1024); } while (0)
; #define PG8_MMA(ai, bj, At, Bt) do { __builtin_amdgcn_s_setprio(1); _Pragma("unroll") for (int m = 0; m < 4; ++m) _Pragma("unroll") for (int n = 0; n < 2; ++n) _Pragma("unroll") for (int k = 0; k < 2; ++k) \
;         acc[ai][bj][m][n] = __builtin_amdgcn_mfma_f32_16x16x32_bf16(Bt[n][k], At[m][k], acc[ai][bj][m][n], 0, 0, 0); __builtin_amdgcn_s_setprio(0); } while (0)
; #define PG8_WAIT_V(n) asm volatile("s_waitcnt vmcnt(" #n ")" ::: "memory")
; #define PG8_WAIT_L(n) asm volatile("s_waitcnt lgkmcnt(" #n ")" ::: "memory")
; #define PG8_BAR __builtin_amdgcn_s_barrier()
; #define PG8_SCHED __builtin_amdgcn_sched_barrier(0)
; template <class Epi, class Sched>
; __device__ __forceinline__ void gemm_phase(LAS unsigned char* lds, const Gemm g, const Sched& S, const Epi& E) {
;     ...
;             PG8_LDB(B1, 0, 1); PG8_STAGE(PG8_SB(0, 0), b2, voffB);
;             PG8_BAR; PG8_WAIT_L(0); PG8_MMA(0, 1, At, B1); PG8_BAR;
;             PG8_LDA(At, 0, 1); PG8_STAGE(PG8_SA(0, 0), a2, voffA);
;             PG8_BAR; PG8_WAIT_L(0); PG8_MMA(1, 0, At, B0); PG8_BAR; PG8_SCHED;
;             PG8_STAGE(PG8_SB(0, 1), b2 + hstep, voffB);
;             PG8_WAIT_V(6); PG8_BAR; PG8_MMA(1, 1, At, B1); PG8_BAR;
;             PG8_LDB(B0, 1, 0); PG8_SCHED; PG8_LDA(At, 1, 0); PG8_STAGE(PG8_SA(0, 1), a2 + hstep, voffA);
;             PG8_WAIT_L(8); PG8_BAR; PG8_WAIT_L(0); PG8_MMA(0, 0, At, B0); PG8_BAR; PG8_SCHED;
;             PG8_LDB(B1, 1, 1); PG8_STAGE(PG8_SB(1, 0), b3, voffB);
;             PG8_BAR; PG8_WAIT_L(0); PG8_MMA(0, 1, At, B1); PG8_BAR;
	s_setprio 1
	v_mfma_f32_16x16x32_bf16 v[62:65], v[140:143], v[160:163], v[62:65]
	v_mfma_f32_16x16x32_bf16 v[58:61], v[148:151], v[160:163], v[58:61]
	v_mfma_f32_16x16x32_bf16 v[54:57], v[140:143], v[168:171], v[54:57]
	v_mfma_f32_16x16x32_bf16 v[50:53], v[148:151], v[168:171], v[50:53]
	v_mfma_f32_16x16x32_bf16 v[38:41], v[140:143], v[176:179], v[38:41]
	v_mfma_f32_16x16x32_bf16 v[34:37], v[148:151], v[176:179], v[34:37]
	v_mfma_f32_16x16x32_bf16 v[22:25], v[140:143], v[184:187], v[22:25]
	v_mfma_f32_16x16x32_bf16 v[18:21], v[148:151], v[184:187], v[18:21]
	v_mfma_f32_16x16x32_bf16 v[62:65], v[144:147], v[164:167], v[62:65]
	v_mfma_f32_16x16x32_bf16 v[58:61], v[152:155], v[164:167], v[58:61]
	v_mfma_f32_16x16x32_bf16 v[54:57], v[144:147], v[172:175], v[54:57]
	v_mfma_f32_16x16x32_bf16 v[50:53], v[152:155], v[172:175], v[50:53]
	v_mfma_f32_16x16x32_bf16 v[38:41], v[144:147], v[180:183], v[38:41]
	v_mfma_f32_16x16x32_bf16 v[34:37], v[152:155], v[180:183], v[34:37]
	v_mfma_f32_16x16x32_bf16 v[22:25], v[144:147], v[188:191], v[22:25]
	v_mfma_f32_16x16x32_bf16 v[18:21], v[152:155], v[188:191], v[18:21]
	s_add_u32 s38, s54, 0x200000
	s_addc_u32 s39, s55, 0
	s_add_i32 s50, s50, s63
	v_lshl_add_u64 v[140:141], s[38:39], 0, v[0:1]
	s_mov_b32 m0, s50
	s_nop 0
	global_load_lds_dwordx4 v[140:141], off
	v_lshl_add_u64 v[140:141], s[38:39], 0, v[130:131]
	s_add_i32 m0, s50, 0x2000
	s_nop 0
	global_load_lds_dwordx4 v[140:141], off
	v_mfma_f32_16x16x32_bf16 v[46:49], v[192:195], v[160:163], v[46:49]
	v_mfma_f32_16x16x32_bf16 v[42:45], v[200:203], v[160:163], v[42:45]
	v_mfma_f32_16x16x32_bf16 v[30:33], v[192:195], v[168:171], v[30:33]
	v_mfma_f32_16x16x32_bf16 v[26:29], v[200:203], v[168:171], v[26:29]
	v_mfma_f32_16x16x32_bf16 v[14:17], v[192:195], v[176:179], v[14:17]
	v_mfma_f32_16x16x32_bf16 v[10:13], v[200:203], v[176:179], v[10:13]
	v_mfma_f32_16x16x32_bf16 v[6:9], v[192:195], v[184:187], v[6:9]
	v_mfma_f32_16x16x32_bf16 v[2:5], v[200:203], v[184:187], v[2:5]
	v_mfma_f32_16x16x32_bf16 v[46:49], v[196:199], v[164:167], v[46:49]
	v_mfma_f32_16x16x32_bf16 v[42:45], v[204:207], v[164:167], v[42:45]
	v_mfma_f32_16x16x32_bf16 v[30:33], v[196:199], v[172:175], v[30:33]
	v_mfma_f32_16x16x32_bf16 v[26:29], v[204:207], v[172:175], v[26:29]
	v_mfma_f32_16x16x32_bf16 v[14:17], v[196:199], v[180:183], v[14:17]
	v_mfma_f32_16x16x32_bf16 v[10:13], v[204:207], v[180:183], v[10:13]
	v_mfma_f32_16x16x32_bf16 v[6:9], v[196:199], v[188:191], v[6:9]
	v_mfma_f32_16x16x32_bf16 v[2:5], v[204:207], v[188:191], v[2:5]
	s_setprio 0
	s_barrier
	s_add_u32 s38, s56, 0x200000
	s_addc_u32 s39, s57, 0
	s_mov_b32 m0, s64
	v_lshl_add_u64 v[192:193], s[38:39], 0, v[0:1]
	global_load_lds_dwordx4 v[192:193], off
	v_lshl_add_u64 v[192:193], s[38:39], 0, v[130:131]
	s_mov_b32 m0, s65
	s_nop 0
	global_load_lds_dwordx4 v[192:193], off
	s_add_i32 s50, 0, 0x18000
	v_add_u32_e32 v152, s50, v137
	ds_read_b128 v[140:143], v152
	ds_read_b128 v[144:147], v152 offset:1024
	ds_read_b128 v[148:151], v152 offset:2048
	ds_read_b128 v[152:155], v152 offset:3072
	ds_read_b128 v[160:163], v139 offset:32768
	ds_read_b128 v[164:167], v139 offset:33792
	ds_read_b128 v[168:171], v139 offset:34816
	ds_read_b128 v[172:175], v139 offset:35840
	ds_read_b128 v[176:179], v139 offset:36864
	ds_read_b128 v[180:183], v139 offset:37888
	ds_read_b128 v[184:187], v139 offset:38912
	ds_read_b128 v[188:191], v139 offset:39936
	s_add_i32 s51, 0, 0x1c000
	v_add_u32_e32 v204, s51, v137
	ds_read_b128 v[192:195], v204
	ds_read_b128 v[196:199], v204 offset:1024
	ds_read_b128 v[200:203], v204 offset:2048
	ds_read_b128 v[204:207], v204 offset:3072
	s_waitcnt lgkmcnt(4)
	s_barrier
	s_waitcnt lgkmcnt(0)
	s_setprio 1
	v_mfma_f32_16x16x32_bf16 v[126:129], v[140:143], v[160:163], v[126:129]
	v_mfma_f32_16x16x32_bf16 v[122:125], v[148:151], v[160:163], v[122:125]
	v_mfma_f32_16x16x32_bf16 v[118:121], v[140:143], v[168:171], v[118:121]
	v_mfma_f32_16x16x32_bf16 v[114:117], v[148:151], v[168:171], v[114:117]
	v_mfma_f32_16x16x32_bf16 v[106:109], v[140:143], v[176:179], v[106:109]
	v_mfma_f32_16x16x32_bf16 v[98:101], v[148:151], v[176:179], v[98:101]
	v_mfma_f32_16x16x32_bf16 v[90:93], v[140:143], v[184:187], v[90:93]
	v_mfma_f32_16x16x32_bf16 v[82:85], v[148:151], v[184:187], v[82:85]
	v_mfma_f32_16x16x32_bf16 v[126:129], v[144:147], v[164:167], v[126:129]
	v_mfma_f32_16x16x32_bf16 v[122:125], v[152:155], v[164:167], v[122:125]
	v_mfma_f32_16x16x32_bf16 v[118:121], v[144:147], v[172:175], v[118:121]
	v_mfma_f32_16x16x32_bf16 v[114:117], v[152:155], v[172:175], v[114:117]
	v_mfma_f32_16x16x32_bf16 v[106:109], v[144:147], v[180:183], v[106:109]
	v_mfma_f32_16x16x32_bf16 v[98:101], v[152:155], v[180:183], v[98:101]
	v_mfma_f32_16x16x32_bf16 v[90:93], v[144:147], v[188:191], v[90:93]
	v_mfma_f32_16x16x32_bf16 v[82:85], v[152:155], v[188:191], v[82:85]
	v_mfma_f32_16x16x32_bf16 v[110:113], v[192:195], v[160:163], v[110:113]
	v_mfma_f32_16x16x32_bf16 v[102:105], v[200:203], v[160:163], v[102:105]
	v_mfma_f32_16x16x32_bf16 v[94:97], v[192:195], v[168:171], v[94:97]
	v_mfma_f32_16x16x32_bf16 v[86:89], v[200:203], v[168:171], v[86:89]
	v_mfma_f32_16x16x32_bf16 v[78:81], v[192:195], v[176:179], v[78:81]
	v_mfma_f32_16x16x32_bf16 v[74:77], v[200:203], v[176:179], v[74:77]
	v_mfma_f32_16x16x32_bf16 v[70:73], v[192:195], v[184:187], v[70:73]
	v_mfma_f32_16x16x32_bf16 v[66:69], v[200:203], v[184:187], v[66:69]
	v_mfma_f32_16x16x32_bf16 v[110:113], v[196:199], v[164:167], v[110:113]
	v_mfma_f32_16x16x32_bf16 v[102:105], v[204:207], v[164:167], v[102:105]
	v_mfma_f32_16x16x32_bf16 v[94:97], v[196:199], v[172:175], v[94:97]
	v_mfma_f32_16x16x32_bf16 v[86:89], v[204:207], v[172:175], v[86:89]
	v_mfma_f32_16x16x32_bf16 v[78:81], v[196:199], v[180:183], v[78:81]
	v_mfma_f32_16x16x32_bf16 v[74:77], v[204:207], v[180:183], v[74:77]
	v_mfma_f32_16x16x32_bf16 v[70:73], v[196:199], v[188:191], v[70:73]
	v_mfma_f32_16x16x32_bf16 v[66:69], v[204:207], v[188:191], v[66:69]
	s_setprio 0
	s_barrier
; #define PG8_STAGE(bufoff, gbase, voff) do { _Pragma("unroll") for (int _i = 0; _i < 2; ++_i) \
;         __builtin_amdgcn_global_load_lds((const unsigned*)((const char*)(gbase) + (voff)[_i]), (LAS unsigned*)(lds + (bufoff) + ldsw + _i * 8192), 16, 0, 0); } while (0)
; #define PG8_LDA(dst, b, h) do { _Pragma("unroll") for (int m = 0; m < 4; ++m) _Pragma("unroll") for (int k = 0; k < 2; ++k) dst[m][k] = *(const LAS bf16x8*)(lds + PG8_SA(b, h) + aoff + m * 2048 + k * 1024); } while (0)
; #define PG8_LDB(dst, b, h) do { _Pragma("unroll") for (int n = 0; n < 2; ++n) _Pragma("unroll") for (int k = 0; k < 2; ++k) dst[n][k] = *(const LAS bf16x8*)(lds + PG8_SB(b, h) + boff + n * 2048 + k * 1024); } while (0)
; #define PG8_MMA(ai, bj, At, Bt) do { __builtin_amdgcn_s_setprio(1); _Pragma("unroll") for (int m = 0; m < 4; ++m) _Pragma("unroll") for (int n = 0; n < 2; ++n) _Pragma("unroll") for (int k = 0; k < 2; ++k) \
;         acc[ai][bj][m][n] = __builtin_amdgcn_mfma_f32_16x16x32_bf16(Bt[n][k], At[m][k], acc[ai][bj][m][n], 0, 0, 0); __builtin_amdgcn_s_setprio(0); } while (0)
; #define PG8_WAIT_V(n) asm volatile("s_waitcnt vmcnt(" #n ")" ::: "memory")
; #define PG8_WAIT_L(n) asm volatile("s_waitcnt lgkmcnt(" #n ")" ::: "memory")
; #define PG8_BAR __builtin_amdgcn_s_barrier()
; #define PG8_SCHED __builtin_amdgcn_sched_barrier(0)
; template <class Epi, class Sched>
; __device__ __forceinline__ void gemm_phase(LAS unsigned char* lds, const Gemm g, const Sched& S, const Epi& E) {
;     ...
;             PG8_LDB(B0, 1, 0); PG8_SCHED; PG8_LDA(At, 1, 0); PG8_STAGE(PG8_SA(0, 1), a2 + hstep, voffA);
;             PG8_WAIT_L(8); PG8_BAR; PG8_WAIT_L(0); PG8_MMA(0, 0, At, B0); PG8_BAR; PG8_SCHED;
;             PG8_LDB(B1, 1, 1); PG8_STAGE(PG8_SB(1, 0), b3, voffB);
;             PG8_BAR; PG8_WAIT_L(0); PG8_MMA(0, 1, At, B1); PG8_BAR;
;             PG8_LDA(At, 1, 1); PG8_STAGE(PG8_SA(1, 0), a3, voffA);
;             PG8_BAR; PG8_WAIT_L(0); PG8_MMA(1, 0, At, B0); PG8_BAR; PG8_SCHED;
;             PG8_STAGE(PG8_SB(1, 1), b3 + hstep, voffB);
;             PG8_WAIT_V(6); PG8_BAR; PG8_MMA(1, 1, At, B1); PG8_BAR;
;         }
	s_add_i32 s38, s50, s63
	v_lshl_add_u64 v[156:157], v[156:157], 0, s[36:37]
	s_mov_b32 m0, s38
	s_nop 0
	global_load_lds_dwordx4 v[156:157], off
	v_lshl_add_u64 v[156:157], v[210:211], 0, s[36:37]
	s_add_i32 m0, s38, 0x2000
	s_nop 0
	global_load_lds_dwordx4 v[156:157], off
	s_mov_b32 m0, s66
	v_lshl_add_u64 v[156:157], v[212:213], 0, s[36:37]
	global_load_lds_dwordx4 v[156:157], off
	v_lshl_add_u64 v[156:157], v[214:215], 0, s[36:37]
	s_mov_b32 m0, s67
	s_nop 0
	global_load_lds_dwordx4 v[156:157], off
	ds_read_b128 v[160:163], v139 offset:49152
	ds_read_b128 v[164:167], v139 offset:50176
	ds_read_b128 v[168:171], v139 offset:51200
	ds_read_b128 v[172:175], v139 offset:52224
	ds_read_b128 v[176:179], v139 offset:53248
	ds_read_b128 v[180:183], v139 offset:54272
	ds_read_b128 v[184:187], v139 offset:55296
	ds_read_b128 v[188:191], v139 offset:56320
	s_waitcnt vmcnt(4)
	s_waitcnt lgkmcnt(0)
	s_barrier
	s_setprio 1
	v_mfma_f32_16x16x32_bf16 v[62:65], v[140:143], v[160:163], v[62:65]
	v_mfma_f32_16x16x32_bf16 v[58:61], v[148:151], v[160:163], v[58:61]
	v_mfma_f32_16x16x32_bf16 v[54:57], v[140:143], v[168:171], v[54:57]
	v_mfma_f32_16x16x32_bf16 v[50:53], v[148:151], v[168:171], v[50:53]
	v_mfma_f32_16x16x32_bf16 v[38:41], v[140:143], v[176:179], v[38:41]
	v_mfma_f32_16x16x32_bf16 v[34:37], v[148:151], v[176:179], v[34:37]
	v_mfma_f32_16x16x32_bf16 v[22:25], v[140:143], v[184:187], v[22:25]
	v_mfma_f32_16x16x32_bf16 v[18:21], v[148:151], v[184:187], v[18:21]
	v_mfma_f32_16x16x32_bf16 v[62:65], v[144:147], v[164:167], v[62:65]
	v_mfma_f32_16x16x32_bf16 v[58:61], v[152:155], v[164:167], v[58:61]
	v_mfma_f32_16x16x32_bf16 v[54:57], v[144:147], v[172:175], v[54:57]
	v_mfma_f32_16x16x32_bf16 v[50:53], v[152:155], v[172:175], v[50:53]
	v_mfma_f32_16x16x32_bf16 v[38:41], v[144:147], v[180:183], v[38:41]
	v_mfma_f32_16x16x32_bf16 v[34:37], v[152:155], v[180:183], v[34:37]
	v_mfma_f32_16x16x32_bf16 v[22:25], v[144:147], v[188:191], v[22:25]
	v_mfma_f32_16x16x32_bf16 v[18:21], v[152:155], v[188:191], v[18:21]
	s_add_u32 s38, s54, 0x200080
	s_addc_u32 s39, s55, 0
	s_add_i32 s50, s51, s63
	v_lshl_add_u64 v[140:141], s[38:39], 0, v[0:1]
	s_mov_b32 m0, s50
	s_nop 0
	global_load_lds_dwordx4 v[140:141], off
	v_lshl_add_u64 v[140:141], s[38:39], 0, v[130:131]
	s_add_i32 m0, s50, 0x2000
	s_nop 0
	global_load_lds_dwordx4 v[140:141], off
	v_mfma_f32_16x16x32_bf16 v[46:49], v[192:195], v[160:163], v[46:49]
	v_mfma_f32_16x16x32_bf16 v[42:45], v[200:203], v[160:163], v[42:45]
	v_mfma_f32_16x16x32_bf16 v[30:33], v[192:195], v[168:171], v[30:33]
	v_mfma_f32_16x16x32_bf16 v[26:29], v[200:203], v[168:171], v[26:29]
	v_mfma_f32_16x16x32_bf16 v[14:17], v[192:195], v[176:179], v[14:17]
	v_mfma_f32_16x16x32_bf16 v[10:13], v[200:203], v[176:179], v[10:13]
	v_mfma_f32_16x16x32_bf16 v[6:9], v[192:195], v[184:187], v[6:9]
	v_mfma_f32_16x16x32_bf16 v[2:5], v[200:203], v[184:187], v[2:5]
	v_mfma_f32_16x16x32_bf16 v[46:49], v[196:199], v[164:167], v[46:49]
	v_mfma_f32_16x16x32_bf16 v[42:45], v[204:207], v[164:167], v[42:45]
	v_mfma_f32_16x16x32_bf16 v[30:33], v[196:199], v[172:175], v[30:33]
	v_mfma_f32_16x16x32_bf16 v[26:29], v[204:207], v[172:175], v[26:29]
	v_mfma_f32_16x16x32_bf16 v[14:17], v[196:199], v[180:183], v[14:17]
	v_mfma_f32_16x16x32_bf16 v[10:13], v[204:207], v[180:183], v[10:13]
	v_mfma_f32_16x16x32_bf16 v[6:9], v[196:199], v[188:191], v[6:9]
	v_mfma_f32_16x16x32_bf16 v[2:5], v[204:207], v[188:191], v[2:5]
	s_setprio 0
	s_add_i32 s71, s71, 2
	s_add_u32 s69, s69, 0x100
	s_addc_u32 s70, s70, 0
	s_cmp_gt_u32 s71, 29
	s_mov_b64 s[50:51], s[52:53]
	s_barrier
	s_cbranch_scc0 .LBB0_58
;     __device__ __forceinline__ void operator()(const f32x4 (&acc)[2][2][4][2], const Unit& u, int wr, int wc, int fr, int fq) const {
;         const int row0 = u.pm * BM + wr * 64 + fr, col0 = u.pn * BM + wc * 32 + 4 * fq;
;         float* base = part + (size_t)u.ks * Mp * ldc;
; #pragma unroll
;         for (int ai = 0; ai < 2; ++ai)
; #pragma unroll
;             for (int m = 0; m < 4; ++m) { float* rowp = base + (size_t)(row0 + ai * HALF + m * 16) * ldc + col0;
; #pragma unroll
;                 for (int bj = 0; bj < 2; ++bj)
; #pragma unroll
;                     for (int n = 0; n < 2; ++n) *(f32x4*)(rowp + bj * HALF + n * 16) = acc[ai][bj][m][n]; }
;     }
	s_ashr_i32 s11, s10, 31
	s_lshl_b64 s[10:11], s[10:11], 24
	v_lshl_or_b32 v140, s26, 8, v138
	s_add_u32 s10, s8, s10
	v_lshl_add_u32 v142, s24, 8, v136
	s_addc_u32 s11, s9, s11
	v_ashrrev_i32_e32 v141, 31, v140
	v_ashrrev_i32_e32 v143, 31, v142
	v_lshl_add_u64 v[140:141], v[140:141], 2, s[10:11]
	v_lshlrev_b64 v[144:145], 13, v[142:143]
	v_lshl_add_u64 v[144:145], v[140:141], 0, v[144:145]
	global_store_dwordx4 v[144:145], v[126:129], off
	global_store_dwordx4 v[144:145], v[122:125], off offset:64
	global_store_dwordx4 v[144:145], v[110:113], off offset:512
	global_store_dwordx4 v[144:145], v[102:105], off offset:576
	s_mov_b64 s[10:11], 0x100000
	s_mov_b32 s26, s40
	v_or_b32_e32 v102, 16, v142
	v_ashrrev_i32_e32 v103, 31, v102
	v_lshlrev_b64 v[102:103], 13, v[102:103]
	v_lshl_add_u64 v[102:103], v[140:141], 0, v[102:103]
	global_store_dwordx4 v[102:103], v[118:121], off
	global_store_dwordx4 v[102:103], v[114:117], off offset:64
	global_store_dwordx4 v[102:103], v[94:97], off offset:512
	global_store_dwordx4 v[102:103], v[86:89], off offset:576
	s_mov_b32 s24, s42
	s_mov_b64 s[52:53], s[48:49]
	v_or_b32_e32 v86, 32, v142
	v_ashrrev_i32_e32 v87, 31, v86
	v_lshlrev_b64 v[86:87], 13, v[86:87]
	v_lshl_add_u64 v[86:87], v[140:141], 0, v[86:87]
	global_store_dwordx4 v[86:87], v[106:109], off
	global_store_dwordx4 v[86:87], v[98:101], off offset:64
	global_store_dwordx4 v[86:87], v[78:81], off offset:512
	global_store_dwordx4 v[86:87], v[74:77], off offset:576
	s_mov_b64 s[50:51], s[46:47]
	s_nop 0
	v_or_b32_e32 v74, 48, v142
	v_ashrrev_i32_e32 v75, 31, v74
	v_lshlrev_b64 v[74:75], 13, v[74:75]
	v_lshl_add_u64 v[74:75], v[140:141], 0, v[74:75]
	global_store_dwordx4 v[74:75], v[90:93], off
	global_store_dwordx4 v[74:75], v[82:85], off offset:64
	global_store_dwordx4 v[74:75], v[70:73], off offset:512
	global_store_dwordx4 v[74:75], v[66:69], off offset:576
	s_nop 1
	v_add_co_u32_e32 v68, vcc, s93, v144
	v_lshl_add_u64 v[66:67], v[144:145], 0, s[10:11]
	s_nop 0
	v_addc_co_u32_e32 v69, vcc, 0, v145, vcc
	s_mov_b64 s[10:11], 0x120000
	global_store_dwordx4 v[68:69], v[62:65], off
	global_store_dwordx4 v[66:67], v[58:61], off offset:64
	global_store_dwordx4 v[66:67], v[46:49], off offset:512
	global_store_dwordx4 v[66:67], v[42:45], off offset:576
	s_nop 1
	v_lshl_add_u64 v[42:43], v[144:145], 0, s[10:11]
	s_mov_b32 s10, 0x120000
	v_add_co_u32_e32 v44, vcc, s10, v144
	s_mov_b64 s[10:11], 0x140000
	s_nop 0
	v_addc_co_u32_e32 v45, vcc, 0, v145, vcc
	global_store_dwordx4 v[44:45], v[54:57], off
	global_store_dwordx4 v[42:43], v[50:53], off offset:64
	global_store_dwordx4 v[42:43], v[30:33], off offset:512
	global_store_dwordx4 v[42:43], v[26:29], off offset:576
	s_nop 1
	v_lshl_add_u64 v[26:27], v[144:145], 0, s[10:11]
	s_mov_b32 s10, 0x140000
	v_add_co_u32_e32 v28, vcc, s10, v144
	s_mov_b64 s[10:11], 0x160000
	s_nop 0
	v_addc_co_u32_e32 v29, vcc, 0, v145, vcc
	global_store_dwordx4 v[28:29], v[38:41], off
	global_store_dwordx4 v[26:27], v[34:37], off offset:64
	global_store_dwordx4 v[26:27], v[14:17], off offset:512
	global_store_dwordx4 v[26:27], v[10:13], off offset:576
	s_nop 1
	v_add_co_u32_e32 v12, vcc, 0x160000, v144
	v_lshl_add_u64 v[10:11], v[144:145], 0, s[10:11]
	s_nop 0
	v_addc_co_u32_e32 v13, vcc, 0, v145, vcc
	s_and_b64 vcc, exec, s[44:45]
	s_mov_b32 s10, s28
	global_store_dwordx4 v[12:13], v[22:25], off
	global_store_dwordx4 v[10:11], v[18:21], off offset:64
	global_store_dwordx4 v[10:11], v[6:9], off offset:512
	global_store_dwordx4 v[10:11], v[2:5], off offset:576
	s_cbranch_vccz .LBB0_55
	s_waitcnt vmcnt(0)
	s_cmpk_gt_u32 s60, 0xff
	s_cbranch_scc1 .LBB0_62
	s_barrier

; #define PG8_STAGE(bufoff, gbase, voff) do { _Pragma("unroll") for (int _i = 0; _i < 2; ++_i) \
;         __builtin_amdgcn_global_load_lds((const unsigned*)((const char*)(gbase) + (voff)[_i]), (LAS unsigned*)(lds + (bufoff) + ldsw + _i * 8192), 16, 0, 0); } while (0)
; #define PG8_LDA(dst, b, h) do { _Pragma("unroll") for (int m = 0; m < 4; ++m) _Pragma("unroll") for (int k = 0; k < 2; ++k) dst[m][k] = *(const LAS bf16x8*)(lds + PG8_SA(b, h) + aoff + m * 2048 + k * 1024); } while (0)
; #define PG8_LDB(dst, b, h) do { _Pragma("unroll") for (int n = 0; n < 2; ++n) _Pragma("unroll") for (int k = 0; k < 2; ++k) dst[n][k] = *(const LAS bf16x8*)(lds + PG8_SB(b, h) + boff + n * 2048 + k * 1024); } while (0)
; #define PG8_MMA(ai, bj, At, Bt) do { __builtin_amdgcn_s_setprio(1); _Pragma("unroll") for (int m = 0; m < 4; ++m) _Pragma("unroll") for (int n = 0; n < 2; ++n) _Pragma("unroll") for (int k = 0; k < 2; ++k) \
;         acc[ai][bj][m][n] = __builtin_amdgcn_mfma_f32_16x16x32_bf16(Bt[n][k], At[m][k], acc[ai][bj][m][n], 0, 0, 0); __builtin_amdgcn_s_setprio(0); } while (0)
; #define PG8_WAIT_V(n) asm volatile("s_waitcnt vmcnt(" #n ")" ::: "memory")
; #define PG8_WAIT_L(n) asm volatile("s_waitcnt lgkmcnt(" #n ")" ::: "memory")
; template <class Epi, class Sched>
; __device__ __forceinline__ void gemm_phase(LAS unsigned char* lds, const Gemm g, const Sched& S, const Epi& E) {
;     ...
;         for (int t = 0; t < nt; t += 2) {
;             const bool last = (t == nt - 2);
;             const char* a1 = cA + (size_t)(t + 1) * kstep;
;             const char* a2 = last ? nA : cA + (size_t)(t + 2) * kstep; const char* b2 = last ? nB : cB + (size_t)(t + 2) * kstep;
;             const char* a3 = a2 + kstep; const char* b3 = b2 + kstep;
;             PG8_LDB(B0, 0, 0); PG8_SCHED; PG8_LDA(At, 0, 0); PG8_STAGE(PG8_SA(1, 1), a1 + hstep, voffA);
;             PG8_WAIT_L(8); PG8_BAR; PG8_WAIT_L(0); PG8_MMA(0, 0, At, B0); PG8_BAR; PG8_SCHED;
;             PG8_LDB(B1, 0, 1); PG8_STAGE(PG8_SB(0, 0), b2, voffB);
;             PG8_BAR; PG8_WAIT_L(0); PG8_MMA(0, 1, At, B1); PG8_BAR;
;             PG8_LDA(At, 0, 1); PG8_STAGE(PG8_SA(0, 0), a2, voffA);
;             PG8_BAR; PG8_WAIT_L(0); PG8_MMA(1, 0, At, B0); PG8_BAR; PG8_SCHED;
;             PG8_STAGE(PG8_SB(0, 1), b2 + hstep, voffB);
;             PG8_WAIT_V(6); PG8_BAR; PG8_MMA(1, 1, At, B1); PG8_BAR;
.LBB0_73:
	s_add_u32 s38, s46, 0xfff80080
	s_addc_u32 s39, s47, -1
	s_cmp_eq_u32 s73, 28
	s_cselect_b32 s51, s29, s39
	s_cselect_b32 s50, s69, s38
	s_cselect_b32 s49, s27, s72
	s_cselect_b32 s48, s70, s71
	v_lshl_add_u64 v[140:141], s[46:47], 0, v[138:139]
	s_add_i32 m0, s9, 0xc000
	s_nop 0
	global_load_lds_dwordx4 v[140:141], off
	v_lshl_add_u64 v[140:141], s[46:47], 0, v[136:137]
	s_add_i32 m0, s9, 0xe000
	s_nop 0
	global_load_lds_dwordx4 v[140:141], off
	s_add_i32 s74, 0, 0x10000
	v_add_u32_e32 v140, s74, v143
	ds_read_b128 v[146:149], v140
	ds_read_b128 v[150:153], v140 offset:1024
	ds_read_b128 v[154:157], v140 offset:2048
	ds_read_b128 v[160:163], v140 offset:3072
	ds_read_b128 v[164:167], v145
	ds_read_b128 v[168:171], v145 offset:1024
	ds_read_b128 v[172:175], v145 offset:2048
	ds_read_b128 v[176:179], v145 offset:3072
	ds_read_b128 v[180:183], v145 offset:4096
	ds_read_b128 v[184:187], v145 offset:5120
	ds_read_b128 v[188:191], v145 offset:6144
	ds_read_b128 v[192:195], v145 offset:7168
	s_add_i32 s75, 0, 0x14000
	v_add_u32_e32 v140, s75, v143
	ds_read_b128 v[196:199], v140
	ds_read_b128 v[200:203], v140 offset:1024
	ds_read_b128 v[204:207], v140 offset:2048
	ds_read_b128 v[210:213], v140 offset:3072
	s_waitcnt lgkmcnt(4)
	s_barrier
	s_waitcnt lgkmcnt(0)
	s_setprio 1
	v_mfma_f32_16x16x32_bf16 v[126:129], v[146:149], v[164:167], v[126:129]
	v_mfma_f32_16x16x32_bf16 v[122:125], v[154:157], v[164:167], v[122:125]
	v_mfma_f32_16x16x32_bf16 v[110:113], v[146:149], v[172:175], v[110:113]
	v_mfma_f32_16x16x32_bf16 v[106:109], v[154:157], v[172:175], v[106:109]
	v_mfma_f32_16x16x32_bf16 v[94:97], v[146:149], v[180:183], v[94:97]
	v_mfma_f32_16x16x32_bf16 v[90:93], v[154:157], v[180:183], v[90:93]
	v_mfma_f32_16x16x32_bf16 v[78:81], v[146:149], v[188:191], v[78:81]
	v_mfma_f32_16x16x32_bf16 v[74:77], v[154:157], v[188:191], v[74:77]
	v_mfma_f32_16x16x32_bf16 v[126:129], v[150:153], v[168:171], v[126:129]
	v_mfma_f32_16x16x32_bf16 v[122:125], v[160:163], v[168:171], v[122:125]
	v_mfma_f32_16x16x32_bf16 v[110:113], v[150:153], v[176:179], v[110:113]
	v_mfma_f32_16x16x32_bf16 v[106:109], v[160:163], v[176:179], v[106:109]
	v_mfma_f32_16x16x32_bf16 v[94:97], v[150:153], v[184:187], v[94:97]
	v_mfma_f32_16x16x32_bf16 v[90:93], v[160:163], v[184:187], v[90:93]
	v_mfma_f32_16x16x32_bf16 v[78:81], v[150:153], v[192:195], v[78:81]
	v_mfma_f32_16x16x32_bf16 v[74:77], v[160:163], v[192:195], v[74:77]
	v_mfma_f32_16x16x32_bf16 v[118:121], v[196:199], v[164:167], v[118:121]
	v_mfma_f32_16x16x32_bf16 v[114:117], v[204:207], v[164:167], v[114:117]
	v_mfma_f32_16x16x32_bf16 v[102:105], v[196:199], v[172:175], v[102:105]
	v_mfma_f32_16x16x32_bf16 v[98:101], v[204:207], v[172:175], v[98:101]
	v_mfma_f32_16x16x32_bf16 v[86:89], v[196:199], v[180:183], v[86:89]
	v_mfma_f32_16x16x32_bf16 v[82:85], v[204:207], v[180:183], v[82:85]
	v_mfma_f32_16x16x32_bf16 v[70:73], v[196:199], v[188:191], v[70:73]
	v_mfma_f32_16x16x32_bf16 v[66:69], v[204:207], v[188:191], v[66:69]
	v_mfma_f32_16x16x32_bf16 v[118:121], v[200:203], v[168:171], v[118:121]
	v_mfma_f32_16x16x32_bf16 v[114:117], v[210:213], v[168:171], v[114:117]
	v_mfma_f32_16x16x32_bf16 v[102:105], v[200:203], v[176:179], v[102:105]
	v_mfma_f32_16x16x32_bf16 v[98:101], v[210:213], v[176:179], v[98:101]
	v_mfma_f32_16x16x32_bf16 v[86:89], v[200:203], v[184:187], v[86:89]
	v_mfma_f32_16x16x32_bf16 v[82:85], v[210:213], v[184:187], v[82:85]
	v_mfma_f32_16x16x32_bf16 v[70:73], v[200:203], v[192:195], v[70:73]
	v_mfma_f32_16x16x32_bf16 v[66:69], v[210:213], v[192:195], v[66:69]
	s_setprio 0
	s_barrier
	s_add_i32 s38, s74, s56
	v_lshl_add_u64 v[140:141], s[48:49], 0, v[0:1]
	s_mov_b32 m0, s38
	v_lshl_add_u64 v[214:215], s[48:49], 0, v[130:131]
	global_load_lds_dwordx4 v[140:141], off
	s_add_i32 m0, s38, 0x2000
	s_nop 0
	global_load_lds_dwordx4 v[214:215], off
	s_mov_b32 m0, s9
	v_lshl_add_u64 v[216:217], s[50:51], 0, v[134:135]
	global_load_lds_dwordx4 v[216:217], off
	v_lshl_add_u64 v[224:225], s[50:51], 0, v[132:133]
	s_mov_b32 m0, s60
	s_nop 0
	global_load_lds_dwordx4 v[224:225], off
	ds_read_b128 v[164:167], v145 offset:16384
	ds_read_b128 v[168:171], v145 offset:17408
	ds_read_b128 v[172:175], v145 offset:18432
	ds_read_b128 v[176:179], v145 offset:19456
	ds_read_b128 v[180:183], v145 offset:20480
	ds_read_b128 v[184:187], v145 offset:21504
	ds_read_b128 v[188:191], v145 offset:22528
	ds_read_b128 v[192:195], v145 offset:23552
	s_waitcnt vmcnt(4)
	s_waitcnt lgkmcnt(0)
	s_barrier
; #define PG8_STAGE(bufoff, gbase, voff) do { _Pragma("unroll") for (int _i = 0; _i < 2; ++_i) \
;         __builtin_amdgcn_global_load_lds((const unsigned*)((const char*)(gbase) + (voff)[_i]), (LAS unsigned*)(lds + (bufoff) + ldsw + _i * 8192), 16, 0, 0); } while (0)
; #define PG8_LDA(dst, b, h) do { _Pragma("unroll") for (int m = 0; m < 4; ++m) _Pragma("unroll") for (int k = 0; k < 2; ++k) dst[m][k] = *(const LAS bf16x8*)(lds + PG8_SA(b, h) + aoff + m * 2048 + k * 1024); } while (0)
; #define PG8_LDB(dst, b, h) do { _Pragma("unroll") for (int n = 0; n < 2; ++n) _Pragma("unroll") for (int k = 0; k < 2; ++k) dst[n][k] = *(const LAS bf16x8*)(lds + PG8_SB(b, h) + boff + n * 2048 + k * 1024); } while (0)
; #define PG8_MMA(ai, bj, At, Bt) do { __builtin_amdgcn_s_setprio(1); _Pragma("unroll") for (int m = 0; m < 4; ++m) _Pragma("unroll") for (int n = 0; n < 2; ++n) _Pragma("unroll") for (int k = 0; k < 2; ++k) \
;         acc[ai][bj][m][n] = __builtin_amdgcn_mfma_f32_16x16x32_bf16(Bt[n][k], At[m][k], acc[ai][bj][m][n], 0, 0, 0); __builtin_amdgcn_s_setprio(0); } while (0)
; #define PG8_WAIT_V(n) asm volatile("s_waitcnt vmcnt(" #n ")" ::: "memory")
; #define PG8_WAIT_L(n) asm volatile("s_waitcnt lgkmcnt(" #n ")" ::: "memory")
; #define PG8_BAR __builtin_amdgcn_s_barrier()
; #define PG8_SCHED __builtin_amdgcn_sched_barrier(0)
; template <class Epi, class Sched>
; __device__ __forceinline__ void gemm_phase(LAS unsigned char* lds, const Gemm g, const Sched& S, const Epi& E) {
;     ...
;             PG8_LDB(B1, 0, 1); PG8_STAGE(PG8_SB(0, 0), b2, voffB);
;             PG8_BAR; PG8_WAIT_L(0); PG8_MMA(0, 1, At, B1); PG8_BAR;
;             PG8_LDA(At, 0, 1); PG8_STAGE(PG8_SA(0, 0), a2, voffA);
;             PG8_BAR; PG8_WAIT_L(0); PG8_MMA(1, 0, At, B0); PG8_BAR; PG8_SCHED;
;             PG8_STAGE(PG8_SB(0, 1), b2 + hstep, voffB);
;             PG8_WAIT_V(6); PG8_BAR; PG8_MMA(1, 1, At, B1); PG8_BAR;
;             PG8_LDB(B0, 1, 0); PG8_SCHED; PG8_LDA(At, 1, 0); PG8_STAGE(PG8_SA(0, 1), a2 + hstep, voffA);
;             PG8_WAIT_L(8); PG8_BAR; PG8_WAIT_L(0); PG8_MMA(0, 0, At, B0); PG8_BAR; PG8_SCHED;
;             PG8_LDB(B1, 1, 1); PG8_STAGE(PG8_SB(1, 0), b3, voffB);
;             PG8_BAR; PG8_WAIT_L(0); PG8_MMA(0, 1, At, B1); PG8_BAR;
	s_setprio 1
	v_mfma_f32_16x16x32_bf16 v[62:65], v[146:149], v[164:167], v[62:65]
	v_mfma_f32_16x16x32_bf16 v[58:61], v[154:157], v[164:167], v[58:61]
	v_mfma_f32_16x16x32_bf16 v[46:49], v[146:149], v[172:175], v[46:49]
	v_mfma_f32_16x16x32_bf16 v[42:45], v[154:157], v[172:175], v[42:45]
	v_mfma_f32_16x16x32_bf16 v[30:33], v[146:149], v[180:183], v[30:33]
	v_mfma_f32_16x16x32_bf16 v[26:29], v[154:157], v[180:183], v[26:29]
	v_mfma_f32_16x16x32_bf16 v[14:17], v[146:149], v[188:191], v[14:17]
	v_mfma_f32_16x16x32_bf16 v[10:13], v[154:157], v[188:191], v[10:13]
	v_mfma_f32_16x16x32_bf16 v[62:65], v[150:153], v[168:171], v[62:65]
	v_mfma_f32_16x16x32_bf16 v[58:61], v[160:163], v[168:171], v[58:61]
	v_mfma_f32_16x16x32_bf16 v[46:49], v[150:153], v[176:179], v[46:49]
	v_mfma_f32_16x16x32_bf16 v[42:45], v[160:163], v[176:179], v[42:45]
	v_mfma_f32_16x16x32_bf16 v[30:33], v[150:153], v[184:187], v[30:33]
	v_mfma_f32_16x16x32_bf16 v[26:29], v[160:163], v[184:187], v[26:29]
	v_mfma_f32_16x16x32_bf16 v[14:17], v[150:153], v[192:195], v[14:17]
	v_mfma_f32_16x16x32_bf16 v[10:13], v[160:163], v[192:195], v[10:13]
	s_add_u32 s38, s48, 0x80000
	s_addc_u32 s39, s49, 0
	s_add_i32 s74, s75, s56
	v_lshl_add_u64 v[146:147], s[38:39], 0, v[0:1]
	s_mov_b32 m0, s74
	s_nop 0
	global_load_lds_dwordx4 v[146:147], off
	v_lshl_add_u64 v[146:147], s[38:39], 0, v[130:131]
	s_add_i32 m0, s74, 0x2000
	s_nop 0
	global_load_lds_dwordx4 v[146:147], off
	v_mfma_f32_16x16x32_bf16 v[54:57], v[196:199], v[164:167], v[54:57]
	v_mfma_f32_16x16x32_bf16 v[50:53], v[204:207], v[164:167], v[50:53]
	v_mfma_f32_16x16x32_bf16 v[38:41], v[196:199], v[172:175], v[38:41]
	v_mfma_f32_16x16x32_bf16 v[34:37], v[204:207], v[172:175], v[34:37]
	v_mfma_f32_16x16x32_bf16 v[22:25], v[196:199], v[180:183], v[22:25]
	v_mfma_f32_16x16x32_bf16 v[18:21], v[204:207], v[180:183], v[18:21]
	v_mfma_f32_16x16x32_bf16 v[6:9], v[196:199], v[188:191], v[6:9]
	v_mfma_f32_16x16x32_bf16 v[2:5], v[204:207], v[188:191], v[2:5]
	v_mfma_f32_16x16x32_bf16 v[54:57], v[200:203], v[168:171], v[54:57]
	v_mfma_f32_16x16x32_bf16 v[50:53], v[210:213], v[168:171], v[50:53]
	v_mfma_f32_16x16x32_bf16 v[38:41], v[200:203], v[176:179], v[38:41]
	v_mfma_f32_16x16x32_bf16 v[34:37], v[210:213], v[176:179], v[34:37]
	v_mfma_f32_16x16x32_bf16 v[22:25], v[200:203], v[184:187], v[22:25]
	v_mfma_f32_16x16x32_bf16 v[18:21], v[210:213], v[184:187], v[18:21]
	v_mfma_f32_16x16x32_bf16 v[6:9], v[200:203], v[192:195], v[6:9]
	v_mfma_f32_16x16x32_bf16 v[2:5], v[210:213], v[192:195], v[2:5]
	s_setprio 0
	s_barrier
	s_add_u32 s38, s50, 0x80000
	s_addc_u32 s39, s51, 0
	s_mov_b32 m0, s61
	v_lshl_add_u64 v[196:197], s[38:39], 0, v[134:135]
	global_load_lds_dwordx4 v[196:197], off
	v_lshl_add_u64 v[196:197], s[38:39], 0, v[132:133]
	s_mov_b32 m0, s62
	s_nop 0
	global_load_lds_dwordx4 v[196:197], off
	s_add_i32 s74, 0, 0x18000
	v_add_u32_e32 v160, s74, v143
	ds_read_b128 v[146:149], v160
	ds_read_b128 v[150:153], v160 offset:1024
	ds_read_b128 v[154:157], v160 offset:2048
	ds_read_b128 v[160:163], v160 offset:3072
	ds_read_b128 v[164:167], v145 offset:32768
	ds_read_b128 v[168:171], v145 offset:33792
	ds_read_b128 v[172:175], v145 offset:34816
	ds_read_b128 v[176:179], v145 offset:35840
	ds_read_b128 v[180:183], v145 offset:36864
	ds_read_b128 v[184:187], v145 offset:37888
	ds_read_b128 v[188:191], v145 offset:38912
	ds_read_b128 v[192:195], v145 offset:39936
	s_add_i32 s50, 0, 0x1c000
	v_add_u32_e32 v210, s50, v143
	ds_read_b128 v[196:199], v210
	ds_read_b128 v[200:203], v210 offset:1024
	ds_read_b128 v[204:207], v210 offset:2048
	ds_read_b128 v[210:213], v210 offset:3072
	s_waitcnt lgkmcnt(4)
	s_barrier
	s_waitcnt lgkmcnt(0)
	s_setprio 1
	v_mfma_f32_16x16x32_bf16 v[126:129], v[146:149], v[164:167], v[126:129]
	v_mfma_f32_16x16x32_bf16 v[122:125], v[154:157], v[164:167], v[122:125]
	v_mfma_f32_16x16x32_bf16 v[110:113], v[146:149], v[172:175], v[110:113]
	v_mfma_f32_16x16x32_bf16 v[106:109], v[154:157], v[172:175], v[106:109]
	v_mfma_f32_16x16x32_bf16 v[94:97], v[146:149], v[180:183], v[94:97]
	v_mfma_f32_16x16x32_bf16 v[90:93], v[154:157], v[180:183], v[90:93]
	v_mfma_f32_16x16x32_bf16 v[78:81], v[146:149], v[188:191], v[78:81]
	v_mfma_f32_16x16x32_bf16 v[74:77], v[154:157], v[188:191], v[74:77]
	v_mfma_f32_16x16x32_bf16 v[126:129], v[150:153], v[168:171], v[126:129]
	v_mfma_f32_16x16x32_bf16 v[122:125], v[160:163], v[168:171], v[122:125]
	v_mfma_f32_16x16x32_bf16 v[110:113], v[150:153], v[176:179], v[110:113]
	v_mfma_f32_16x16x32_bf16 v[106:109], v[160:163], v[176:179], v[106:109]
	v_mfma_f32_16x16x32_bf16 v[94:97], v[150:153], v[184:187], v[94:97]
	v_mfma_f32_16x16x32_bf16 v[90:93], v[160:163], v[184:187], v[90:93]
	v_mfma_f32_16x16x32_bf16 v[78:81], v[150:153], v[192:195], v[78:81]
	v_mfma_f32_16x16x32_bf16 v[74:77], v[160:163], v[192:195], v[74:77]
	v_mfma_f32_16x16x32_bf16 v[118:121], v[196:199], v[164:167], v[118:121]
	v_mfma_f32_16x16x32_bf16 v[114:117], v[204:207], v[164:167], v[114:117]
	v_mfma_f32_16x16x32_bf16 v[102:105], v[196:199], v[172:175], v[102:105]
	v_mfma_f32_16x16x32_bf16 v[98:101], v[204:207], v[172:175], v[98:101]
	v_mfma_f32_16x16x32_bf16 v[86:89], v[196:199], v[180:183], v[86:89]
	v_mfma_f32_16x16x32_bf16 v[82:85], v[204:207], v[180:183], v[82:85]
	v_mfma_f32_16x16x32_bf16 v[70:73], v[196:199], v[188:191], v[70:73]
	v_mfma_f32_16x16x32_bf16 v[66:69], v[204:207], v[188:191], v[66:69]
	v_mfma_f32_16x16x32_bf16 v[118:121], v[200:203], v[168:171], v[118:121]
	v_mfma_f32_16x16x32_bf16 v[114:117], v[210:213], v[168:171], v[114:117]
	v_mfma_f32_16x16x32_bf16 v[102:105], v[200:203], v[176:179], v[102:105]
	v_mfma_f32_16x16x32_bf16 v[98:101], v[210:213], v[176:179], v[98:101]
	v_mfma_f32_16x16x32_bf16 v[86:89], v[200:203], v[184:187], v[86:89]
	v_mfma_f32_16x16x32_bf16 v[82:85], v[210:213], v[184:187], v[82:85]
	v_mfma_f32_16x16x32_bf16 v[70:73], v[200:203], v[192:195], v[70:73]
	v_mfma_f32_16x16x32_bf16 v[66:69], v[210:213], v[192:195], v[66:69]
	s_setprio 0
	s_barrier
; __device__ __forceinline__ unsigned cvt_pk_bf16(float lo, float hi) { unsigned r; asm("v_cvt_pk_bf16_f32 %0, %1, %2" : "=v"(r) : "v"(lo), "v"(hi)); return r; }
; #define PG8_STAGE(bufoff, gbase, voff) do { _Pragma("unroll") for (int _i = 0; _i < 2; ++_i) \
;         __builtin_amdgcn_global_load_lds((const unsigned*)((const char*)(gbase) + (voff)[_i]), (LAS unsigned*)(lds + (bufoff) + ldsw + _i * 8192), 16, 0, 0); } while (0)
; #define PG8_LDA(dst, b, h) do { _Pragma("unroll") for (int m = 0; m < 4; ++m) _Pragma("unroll") for (int k = 0; k < 2; ++k) dst[m][k] = *(const LAS bf16x8*)(lds + PG8_SA(b, h) + aoff + m * 2048 + k * 1024); } while (0)
; #define PG8_WAIT_V(n) asm volatile("s_waitcnt vmcnt(" #n ")" ::: "memory")
;     __device__ __forceinline__ void operator()(const f32x4 (&acc)[2][2][4][2], const Unit& u, int wr, int wc, int fr, int fq) const {
;     ...
;         for (int ai = 0; ai < 2; ++ai)
; #pragma unroll
;             for (int m = 0; m < 4; ++m) { bf16_t* rowp = O + (size_t)(row0 + ai * HALF + m * 16) * ldc + col0;
; #pragma unroll
;                 for (int bj = 0; bj < 2; ++bj) { f32x4 v0 = acc[ai][bj][m][0], v1 = acc[ai][bj][m][1];
;                     if (ACT == 1) {
; #pragma unroll
;                         for (int j = 0; j < 4; ++j) { float a = fmaxf(v0[j], 0.f), b = fmaxf(v1[j], 0.f); v0[j] = a * a; v1[j] = b * b; } }
;                     u32x4 w; w.x = cvt_pk_bf16(v0[0], v0[1]); w.y = cvt_pk_bf16(v0[2], v0[3]); w.z = cvt_pk_bf16(v1[0], v1[1]); w.w = cvt_pk_bf16(v1[2], v1[3]);
;                     if (ACT == 1) __builtin_nontemporal_store(w, (u32x4*)(rowp + bj * HALF));
; template <class Epi, class Sched>
; __device__ __forceinline__ void gemm_phase(LAS unsigned char* lds, const Gemm g, const Sched& S, const Epi& E) {
;     ...
;             PG8_LDB(B0, 1, 0); PG8_SCHED; PG8_LDA(At, 1, 0); PG8_STAGE(PG8_SA(0, 1), a2 + hstep, voffA);
;             PG8_WAIT_L(8); PG8_BAR; PG8_WAIT_L(0); PG8_MMA(0, 0, At, B0); PG8_BAR; PG8_SCHED;
;             PG8_LDB(B1, 1, 1); PG8_STAGE(PG8_SB(1, 0), b3, voffB);
;             PG8_BAR; PG8_WAIT_L(0); PG8_MMA(0, 1, At, B1); PG8_BAR;
;             PG8_LDA(At, 1, 1); PG8_STAGE(PG8_SA(1, 0), a3, voffA);
;             PG8_BAR; PG8_WAIT_L(0); PG8_MMA(1, 0, At, B0); PG8_BAR; PG8_SCHED;
;             PG8_STAGE(PG8_SB(1, 1), b3 + hstep, voffB);
;             PG8_WAIT_V(6); PG8_BAR; PG8_MMA(1, 1, At, B1); PG8_BAR;
;         }
	s_add_i32 s38, s74, s56
	v_lshl_add_u64 v[140:141], v[140:141], 0, s[36:37]
	s_mov_b32 m0, s38
	s_nop 0
	global_load_lds_dwordx4 v[140:141], off
	v_lshl_add_u64 v[140:141], v[214:215], 0, s[36:37]
	s_add_i32 m0, s38, 0x2000
	s_nop 0
	global_load_lds_dwordx4 v[140:141], off
	s_mov_b32 m0, s64
	v_lshl_add_u64 v[140:141], v[216:217], 0, s[36:37]
	global_load_lds_dwordx4 v[140:141], off
	v_lshl_add_u64 v[140:141], v[224:225], 0, s[36:37]
	s_mov_b32 m0, s65
	s_nop 0
	global_load_lds_dwordx4 v[140:141], off
	ds_read_b128 v[164:167], v145 offset:49152
	ds_read_b128 v[168:171], v145 offset:50176
	ds_read_b128 v[172:175], v145 offset:51200
	ds_read_b128 v[176:179], v145 offset:52224
	ds_read_b128 v[180:183], v145 offset:53248
	ds_read_b128 v[184:187], v145 offset:54272
	ds_read_b128 v[188:191], v145 offset:55296
	ds_read_b128 v[192:195], v145 offset:56320
	s_waitcnt vmcnt(4)
	s_waitcnt lgkmcnt(0)
	s_barrier
	s_setprio 1
	v_mfma_f32_16x16x32_bf16 v[62:65], v[146:149], v[164:167], v[62:65]
	v_mfma_f32_16x16x32_bf16 v[58:61], v[154:157], v[164:167], v[58:61]
	v_mfma_f32_16x16x32_bf16 v[46:49], v[146:149], v[172:175], v[46:49]
	v_mfma_f32_16x16x32_bf16 v[42:45], v[154:157], v[172:175], v[42:45]
	v_mfma_f32_16x16x32_bf16 v[30:33], v[146:149], v[180:183], v[30:33]
	v_mfma_f32_16x16x32_bf16 v[26:29], v[154:157], v[180:183], v[26:29]
	v_mfma_f32_16x16x32_bf16 v[14:17], v[146:149], v[188:191], v[14:17]
	v_mfma_f32_16x16x32_bf16 v[10:13], v[154:157], v[188:191], v[10:13]
	v_mfma_f32_16x16x32_bf16 v[62:65], v[150:153], v[168:171], v[62:65]
	v_mfma_f32_16x16x32_bf16 v[58:61], v[160:163], v[168:171], v[58:61]
	v_mfma_f32_16x16x32_bf16 v[46:49], v[150:153], v[176:179], v[46:49]
	v_mfma_f32_16x16x32_bf16 v[42:45], v[160:163], v[176:179], v[42:45]
	v_mfma_f32_16x16x32_bf16 v[30:33], v[150:153], v[184:187], v[30:33]
	v_mfma_f32_16x16x32_bf16 v[26:29], v[160:163], v[184:187], v[26:29]
	v_mfma_f32_16x16x32_bf16 v[14:17], v[150:153], v[192:195], v[14:17]
	v_mfma_f32_16x16x32_bf16 v[10:13], v[160:163], v[192:195], v[10:13]
	s_add_u32 s38, s48, 0x80080
	s_addc_u32 s39, s49, 0
	s_add_i32 s48, s50, s56
	v_lshl_add_u64 v[140:141], s[38:39], 0, v[0:1]
	s_mov_b32 m0, s48
	s_nop 0
	global_load_lds_dwordx4 v[140:141], off
	v_lshl_add_u64 v[140:141], s[38:39], 0, v[130:131]
	s_add_i32 m0, s48, 0x2000
	s_nop 0
	global_load_lds_dwordx4 v[140:141], off
	v_mfma_f32_16x16x32_bf16 v[54:57], v[196:199], v[164:167], v[54:57]
	v_mfma_f32_16x16x32_bf16 v[50:53], v[204:207], v[164:167], v[50:53]
	v_mfma_f32_16x16x32_bf16 v[38:41], v[196:199], v[172:175], v[38:41]
	v_mfma_f32_16x16x32_bf16 v[34:37], v[204:207], v[172:175], v[34:37]
	v_mfma_f32_16x16x32_bf16 v[22:25], v[196:199], v[180:183], v[22:25]
	v_mfma_f32_16x16x32_bf16 v[18:21], v[204:207], v[180:183], v[18:21]
	v_mfma_f32_16x16x32_bf16 v[6:9], v[196:199], v[188:191], v[6:9]
	v_mfma_f32_16x16x32_bf16 v[2:5], v[204:207], v[188:191], v[2:5]
	v_mfma_f32_16x16x32_bf16 v[54:57], v[200:203], v[168:171], v[54:57]
	v_mfma_f32_16x16x32_bf16 v[50:53], v[210:213], v[168:171], v[50:53]
	v_mfma_f32_16x16x32_bf16 v[38:41], v[200:203], v[176:179], v[38:41]
	v_mfma_f32_16x16x32_bf16 v[34:37], v[210:213], v[176:179], v[34:37]
	v_mfma_f32_16x16x32_bf16 v[22:25], v[200:203], v[184:187], v[22:25]
	v_mfma_f32_16x16x32_bf16 v[18:21], v[210:213], v[184:187], v[18:21]
	v_mfma_f32_16x16x32_bf16 v[6:9], v[200:203], v[192:195], v[6:9]
	v_mfma_f32_16x16x32_bf16 v[2:5], v[210:213], v[192:195], v[2:5]
	s_setprio 0
	s_add_i32 s73, s73, 2
	s_add_u32 s71, s71, 0x100
	s_addc_u32 s72, s72, 0
	s_add_u32 s46, s46, 0x100
	s_addc_u32 s47, s47, 0
	s_cmp_gt_u32 s73, 29
	s_barrier
	s_cbranch_scc0 .LBB0_73
	v_lshl_add_u32 v146, s8, 8, v142
	v_max_f32_e32 v122, v122, v122
	v_ashrrev_i32_e32 v147, 31, v146
	v_max_f32_e32 v122, 0, v122
	v_max_f32_e32 v123, v123, v123
	v_max_f32_e32 v124, v124, v124
	v_lshl_or_b32 v140, s68, 8, v144
	v_lshlrev_b64 v[148:149], 14, v[146:147]
	v_mul_f32_e32 v147, v122, v122
	v_max_f32_e32 v122, v127, v127
	v_max_f32_e32 v123, 0, v123
	v_max_f32_e32 v124, 0, v124
	v_ashrrev_i32_e32 v141, 31, v140
	v_max_f32_e32 v126, v126, v126
	v_max_f32_e32 v122, 0, v122
	v_mul_f32_e32 v127, v123, v123
	v_max_f32_e32 v123, v128, v128
	v_mul_f32_e32 v128, v124, v124
	v_max_f32_e32 v124, v129, v129
	v_max_f32_e32 v125, v125, v125
	v_lshl_add_u64 v[148:149], s[24:25], 0, v[148:149]
	v_lshlrev_b64 v[150:151], 1, v[140:141]
	v_max_f32_e32 v126, 0, v126
	v_mul_f32_e32 v122, v122, v122
	v_max_f32_e32 v123, 0, v123
	v_max_f32_e32 v124, 0, v124
	v_max_f32_e32 v125, 0, v125
	v_max_f32_e32 v114, v114, v114
	v_lshl_add_u64 v[140:141], v[148:149], 0, v[150:151]
	v_mul_f32_e32 v126, v126, v126
	v_mul_f32_e32 v123, v123, v123
	v_mul_f32_e32 v124, v124, v124
	v_mul_f32_e32 v125, v125, v125
	v_cvt_pk_bf16_f32 v122, v126, v122
	v_max_f32_e32 v114, 0, v114
	v_max_f32_e32 v115, v115, v115
	v_max_f32_e32 v116, v116, v116
	v_cvt_pk_bf16_f32 v123, v123, v124
	v_cvt_pk_bf16_f32 v124, v147, v127
	v_cvt_pk_bf16_f32 v125, v128, v125
	global_store_dwordx4 v[140:141], v[122:125], off nt
	v_max_f32_e32 v115, 0, v115
	v_max_f32_e32 v116, 0, v116
	v_mul_f32_e32 v122, v114, v114
	v_max_f32_e32 v114, v119, v119
	v_max_f32_e32 v118, v118, v118
	v_max_f32_e32 v114, 0, v114
	v_mul_f32_e32 v119, v115, v115
	v_max_f32_e32 v115, v120, v120
	v_mul_f32_e32 v120, v116, v116
	v_max_f32_e32 v116, v121, v121
	v_max_f32_e32 v117, v117, v117
	v_max_f32_e32 v118, 0, v118
	v_mul_f32_e32 v114, v114, v114
	v_max_f32_e32 v115, 0, v115
	v_max_f32_e32 v116, 0, v116
	v_max_f32_e32 v117, 0, v117
	v_mul_f32_e32 v118, v118, v118
	v_mul_f32_e32 v115, v115, v115
	v_mul_f32_e32 v116, v116, v116
	v_mul_f32_e32 v117, v117, v117
; __device__ __forceinline__ unsigned cvt_pk_bf16(float lo, float hi) { unsigned r; asm("v_cvt_pk_bf16_f32 %0, %1, %2" : "=v"(r) : "v"(lo), "v"(hi)); return r; }
;     __device__ __forceinline__ void operator()(const f32x4 (&acc)[2][2][4][2], const Unit& u, int wr, int wc, int fr, int fq) const {
;     ...
;         for (int ai = 0; ai < 2; ++ai)
; #pragma unroll
;             for (int m = 0; m < 4; ++m) { bf16_t* rowp = O + (size_t)(row0 + ai * HALF + m * 16) * ldc + col0;
; #pragma unroll
;                 for (int bj = 0; bj < 2; ++bj) { f32x4 v0 = acc[ai][bj][m][0], v1 = acc[ai][bj][m][1];
;                     if (ACT == 1) {
; #pragma unroll
;                         for (int j = 0; j < 4; ++j) { float a = fmaxf(v0[j], 0.f), b = fmaxf(v1[j], 0.f); v0[j] = a * a; v1[j] = b * b; } }
;                     u32x4 w; w.x = cvt_pk_bf16(v0[0], v0[1]); w.y = cvt_pk_bf16(v0[2], v0[3]); w.z = cvt_pk_bf16(v1[0], v1[1]); w.w = cvt_pk_bf16(v1[2], v1[3]);
;                     if (ACT == 1) __builtin_nontemporal_store(w, (u32x4*)(rowp + bj * HALF));
;                     else *(u32x4*)(rowp + bj * HALF) = w; } }
	v_cvt_pk_bf16_f32 v114, v118, v114
	v_max_f32_e32 v106, v106, v106
	v_cvt_pk_bf16_f32 v115, v115, v116
	v_cvt_pk_bf16_f32 v116, v122, v119
	v_cvt_pk_bf16_f32 v117, v120, v117
	global_store_dwordx4 v[140:141], v[114:117], off offset:256 nt
	v_max_f32_e32 v106, 0, v106
	v_max_f32_e32 v107, v107, v107
	v_or_b32_e32 v114, 16, v146
	v_max_f32_e32 v108, v108, v108
	v_ashrrev_i32_e32 v115, 31, v114
	v_mul_f32_e32 v116, v106, v106
	v_max_f32_e32 v106, v111, v111
	v_max_f32_e32 v107, 0, v107
	v_max_f32_e32 v108, 0, v108
	v_lshlrev_b64 v[114:115], 14, v[114:115]
	v_max_f32_e32 v110, v110, v110
	v_max_f32_e32 v106, 0, v106
	v_mul_f32_e32 v111, v107, v107
	v_max_f32_e32 v107, v112, v112
	v_mul_f32_e32 v112, v108, v108
	v_max_f32_e32 v108, v113, v113
	v_max_f32_e32 v109, v109, v109
	v_lshl_add_u64 v[114:115], s[24:25], 0, v[114:115]
	v_max_f32_e32 v110, 0, v110
	v_mul_f32_e32 v106, v106, v106
	v_max_f32_e32 v107, 0, v107
	v_max_f32_e32 v108, 0, v108
	v_max_f32_e32 v109, 0, v109
	v_max_f32_e32 v98, v98, v98
	v_lshl_add_u64 v[114:115], v[114:115], 0, v[150:151]
	v_mul_f32_e32 v110, v110, v110
	v_mul_f32_e32 v107, v107, v107
	v_mul_f32_e32 v108, v108, v108
	v_mul_f32_e32 v109, v109, v109
	v_cvt_pk_bf16_f32 v106, v110, v106
	v_max_f32_e32 v98, 0, v98
	v_max_f32_e32 v99, v99, v99
	v_max_f32_e32 v100, v100, v100
	v_cvt_pk_bf16_f32 v107, v107, v108
	v_cvt_pk_bf16_f32 v108, v116, v111
	v_cvt_pk_bf16_f32 v109, v112, v109
	global_store_dwordx4 v[114:115], v[106:109], off nt
	v_max_f32_e32 v99, 0, v99
	v_max_f32_e32 v100, 0, v100
	v_mul_f32_e32 v106, v98, v98
	v_max_f32_e32 v98, v103, v103
	v_max_f32_e32 v102, v102, v102
	v_max_f32_e32 v98, 0, v98
	v_mul_f32_e32 v103, v99, v99
	v_max_f32_e32 v99, v104, v104
	v_mul_f32_e32 v104, v100, v100
	v_max_f32_e32 v100, v105, v105
	v_max_f32_e32 v101, v101, v101
	v_max_f32_e32 v102, 0, v102
	v_mul_f32_e32 v98, v98, v98
	v_max_f32_e32 v99, 0, v99
	v_max_f32_e32 v100, 0, v100
	v_max_f32_e32 v101, 0, v101
	v_mul_f32_e32 v102, v102, v102
	v_mul_f32_e32 v99, v99, v99
	v_mul_f32_e32 v100, v100, v100
	v_mul_f32_e32 v101, v101, v101
	v_cvt_pk_bf16_f32 v98, v102, v98
	v_max_f32_e32 v90, v90, v90
	v_cvt_pk_bf16_f32 v99, v99, v100
	v_cvt_pk_bf16_f32 v100, v106, v103
	v_cvt_pk_bf16_f32 v101, v104, v101
	global_store_dwordx4 v[114:115], v[98:101], off offset:256 nt
	v_max_f32_e32 v90, 0, v90
	v_max_f32_e32 v91, v91, v91
	v_or_b32_e32 v98, 32, v146
	v_max_f32_e32 v92, v92, v92
	v_ashrrev_i32_e32 v99, 31, v98
	v_mul_f32_e32 v100, v90, v90
	v_max_f32_e32 v90, v95, v95
	v_max_f32_e32 v91, 0, v91
	v_max_f32_e32 v92, 0, v92
	v_lshlrev_b64 v[98:99], 14, v[98:99]
	v_max_f32_e32 v94, v94, v94
	v_max_f32_e32 v90, 0, v90
	v_mul_f32_e32 v95, v91, v91
	v_max_f32_e32 v91, v96, v96
	v_mul_f32_e32 v96, v92, v92
	v_max_f32_e32 v92, v97, v97
	v_max_f32_e32 v93, v93, v93
	v_lshl_add_u64 v[98:99], s[24:25], 0, v[98:99]
	v_max_f32_e32 v94, 0, v94
	v_mul_f32_e32 v90, v90, v90
	v_max_f32_e32 v91, 0, v91
	v_max_f32_e32 v92, 0, v92
	v_max_f32_e32 v93, 0, v93
	v_max_f32_e32 v82, v82, v82
	v_lshl_add_u64 v[98:99], v[98:99], 0, v[150:151]
	v_mul_f32_e32 v94, v94, v94
	v_mul_f32_e32 v91, v91, v91
	v_mul_f32_e32 v92, v92, v92
	v_mul_f32_e32 v93, v93, v93
	v_cvt_pk_bf16_f32 v90, v94, v90
	v_max_f32_e32 v82, 0, v82
	v_max_f32_e32 v83, v83, v83
	v_max_f32_e32 v84, v84, v84
	v_cvt_pk_bf16_f32 v91, v91, v92
	v_cvt_pk_bf16_f32 v92, v100, v95
	v_cvt_pk_bf16_f32 v93, v96, v93
	global_store_dwordx4 v[98:99], v[90:93], off nt
	v_max_f32_e32 v83, 0, v83
	v_max_f32_e32 v84, 0, v84
	v_mul_f32_e32 v90, v82, v82
	v_max_f32_e32 v82, v87, v87
	v_max_f32_e32 v86, v86, v86
	v_max_f32_e32 v82, 0, v82
	v_mul_f32_e32 v87, v83, v83
	v_max_f32_e32 v83, v88, v88
	v_mul_f32_e32 v88, v84, v84
	v_max_f32_e32 v84, v89, v89
	v_max_f32_e32 v85, v85, v85
	v_max_f32_e32 v86, 0, v86
	v_mul_f32_e32 v82, v82, v82
	v_max_f32_e32 v83, 0, v83
	v_max_f32_e32 v84, 0, v84
	v_max_f32_e32 v85, 0, v85
	v_mul_f32_e32 v86, v86, v86
	v_mul_f32_e32 v83, v83, v83
	v_mul_f32_e32 v84, v84, v84
	v_mul_f32_e32 v85, v85, v85
	v_cvt_pk_bf16_f32 v82, v86, v82
	v_max_f32_e32 v74, v74, v74
	v_cvt_pk_bf16_f32 v83, v83, v84
	v_cvt_pk_bf16_f32 v84, v90, v87
	v_cvt_pk_bf16_f32 v85, v88, v85
	global_store_dwordx4 v[98:99], v[82:85], off offset:256 nt
	v_max_f32_e32 v74, 0, v74
	v_max_f32_e32 v75, v75, v75
	v_or_b32_e32 v82, 48, v146
	v_max_f32_e32 v76, v76, v76
	v_ashrrev_i32_e32 v83, 31, v82
	v_mul_f32_e32 v84, v74, v74
	v_max_f32_e32 v74, v79, v79
	v_max_f32_e32 v75, 0, v75
	v_max_f32_e32 v76, 0, v76
	v_lshlrev_b64 v[82:83], 14, v[82:83]
	v_max_f32_e32 v78, v78, v78
	v_max_f32_e32 v74, 0, v74
	v_mul_f32_e32 v79, v75, v75
	v_max_f32_e32 v75, v80, v80
	v_mul_f32_e32 v80, v76, v76
	v_max_f32_e32 v76, v81, v81
	v_max_f32_e32 v77, v77, v77
	v_lshl_add_u64 v[82:83], s[24:25], 0, v[82:83]
	v_max_f32_e32 v78, 0, v78
	v_mul_f32_e32 v74, v74, v74
	v_max_f32_e32 v75, 0, v75
	v_max_f32_e32 v76, 0, v76
	v_max_f32_e32 v77, 0, v77
	v_max_f32_e32 v66, v66, v66
	v_max_f32_e32 v67, v67, v67
	v_max_f32_e32 v68, v68, v68
	v_lshl_add_u64 v[82:83], v[82:83], 0, v[150:151]
	v_mul_f32_e32 v78, v78, v78
	v_mul_f32_e32 v75, v75, v75
	v_mul_f32_e32 v76, v76, v76
	v_mul_f32_e32 v77, v77, v77
	v_cvt_pk_bf16_f32 v74, v78, v74
	v_max_f32_e32 v66, 0, v66
	v_max_f32_e32 v67, 0, v67
	v_max_f32_e32 v68, 0, v68
	v_cvt_pk_bf16_f32 v75, v75, v76
	v_cvt_pk_bf16_f32 v76, v84, v79
	v_cvt_pk_bf16_f32 v77, v80, v77
	global_store_dwordx4 v[82:83], v[74:77], off nt
	v_max_f32_e32 v69, v69, v69
	v_max_f32_e32 v70, v70, v70
	v_mul_f32_e32 v74, v66, v66
	v_max_f32_e32 v66, v71, v71
	v_mul_f32_e32 v71, v67, v67
	v_max_f32_e32 v67, v72, v72
	v_mul_f32_e32 v72, v68, v68
; __device__ __forceinline__ unsigned cvt_pk_bf16(float lo, float hi) { unsigned r; asm("v_cvt_pk_bf16_f32 %0, %1, %2" : "=v"(r) : "v"(lo), "v"(hi)); return r; }
;     __device__ __forceinline__ void operator()(const f32x4 (&acc)[2][2][4][2], const Unit& u, int wr, int wc, int fr, int fq) const {
;     ...
;         for (int ai = 0; ai < 2; ++ai)
; #pragma unroll
;             for (int m = 0; m < 4; ++m) { bf16_t* rowp = O + (size_t)(row0 + ai * HALF + m * 16) * ldc + col0;
; #pragma unroll
;                 for (int bj = 0; bj < 2; ++bj) { f32x4 v0 = acc[ai][bj][m][0], v1 = acc[ai][bj][m][1];
;                     if (ACT == 1) {
; #pragma unroll
;                         for (int j = 0; j < 4; ++j) { float a = fmaxf(v0[j], 0.f), b = fmaxf(v1[j], 0.f); v0[j] = a * a; v1[j] = b * b; } }
;                     u32x4 w; w.x = cvt_pk_bf16(v0[0], v0[1]); w.y = cvt_pk_bf16(v0[2], v0[3]); w.z = cvt_pk_bf16(v1[0], v1[1]); w.w = cvt_pk_bf16(v1[2], v1[3]);
;                     if (ACT == 1) __builtin_nontemporal_store(w, (u32x4*)(rowp + bj * HALF));
;                     else *(u32x4*)(rowp + bj * HALF) = w; } }
	v_max_f32_e32 v68, v73, v73
	v_max_f32_e32 v67, 0, v67
	v_max_f32_e32 v68, 0, v68
	v_max_f32_e32 v66, 0, v66
	v_mul_f32_e32 v67, v67, v67
	v_max_f32_e32 v69, 0, v69
	v_mul_f32_e32 v68, v68, v68
	v_max_f32_e32 v58, v58, v58
	v_max_f32_e32 v70, 0, v70
	v_mul_f32_e32 v66, v66, v66
	v_mul_f32_e32 v69, v69, v69
	v_cvt_pk_bf16_f32 v67, v67, v68
	v_cvt_pk_bf16_f32 v68, v74, v71
	v_max_f32_e32 v58, 0, v58
	v_max_f32_e32 v59, v59, v59
	v_max_f32_e32 v60, v60, v60
	v_mul_f32_e32 v70, v70, v70
	v_cvt_pk_bf16_f32 v66, v70, v66
	v_cvt_pk_bf16_f32 v69, v72, v69
	global_store_dwordx4 v[82:83], v[66:69], off offset:256 nt
	v_max_f32_e32 v62, v62, v62
	v_max_f32_e32 v59, 0, v59
	v_mul_f32_e32 v68, v58, v58
	v_max_f32_e32 v58, v63, v63
	v_max_f32_e32 v60, 0, v60
	v_max_f32_e32 v62, 0, v62
	v_max_f32_e32 v58, 0, v58
	v_mul_f32_e32 v63, v59, v59
	v_max_f32_e32 v59, v64, v64
	v_mul_f32_e32 v64, v60, v60
	v_max_f32_e32 v60, v65, v65
	v_mul_f32_e32 v62, v62, v62
	v_mul_f32_e32 v58, v58, v58
	v_max_f32_e32 v59, 0, v59
	v_max_f32_e32 v60, 0, v60
	v_max_f32_e32 v61, v61, v61
	s_mov_b32 s8, 0x200000
	v_mul_f32_e32 v59, v59, v59
	v_max_f32_e32 v61, 0, v61
	v_mul_f32_e32 v60, v60, v60
	v_cvt_pk_bf16_f32 v58, v62, v58
	v_add_co_u32_e32 v62, vcc, s8, v140
	v_max_f32_e32 v50, v50, v50
	v_max_f32_e32 v51, v51, v51
	v_max_f32_e32 v52, v52, v52
	v_mul_f32_e32 v61, v61, v61
	v_cvt_pk_bf16_f32 v59, v59, v60
	v_cvt_pk_bf16_f32 v60, v68, v63
	v_addc_co_u32_e32 v63, vcc, 0, v141, vcc
	v_max_f32_e32 v50, 0, v50
	v_max_f32_e32 v51, 0, v51
	v_max_f32_e32 v52, 0, v52
	v_cvt_pk_bf16_f32 v61, v64, v61
	global_store_dwordx4 v[62:63], v[58:61], off nt
	v_max_f32_e32 v53, v53, v53
	s_mov_b64 s[38:39], 0x200000
	v_mul_f32_e32 v58, v50, v50
	v_max_f32_e32 v50, v55, v55
	v_mul_f32_e32 v55, v51, v51
	v_max_f32_e32 v51, v56, v56
	v_mul_f32_e32 v56, v52, v52
	v_max_f32_e32 v52, v57, v57
	v_max_f32_e32 v51, 0, v51
	v_max_f32_e32 v52, 0, v52
	v_max_f32_e32 v54, v54, v54
	v_max_f32_e32 v50, 0, v50
	v_mul_f32_e32 v51, v51, v51
	v_max_f32_e32 v53, 0, v53
	v_mul_f32_e32 v52, v52, v52
	v_max_f32_e32 v42, v42, v42
	v_lshl_add_u64 v[66:67], v[140:141], 0, s[38:39]
	v_max_f32_e32 v54, 0, v54
	v_mul_f32_e32 v50, v50, v50
	v_mul_f32_e32 v53, v53, v53
	v_cvt_pk_bf16_f32 v51, v51, v52
	v_cvt_pk_bf16_f32 v52, v58, v55
	v_max_f32_e32 v42, 0, v42
	v_max_f32_e32 v43, v43, v43
	v_max_f32_e32 v44, v44, v44
	v_mul_f32_e32 v54, v54, v54
	v_cvt_pk_bf16_f32 v50, v54, v50
	v_cvt_pk_bf16_f32 v53, v56, v53
	global_store_dwordx4 v[66:67], v[50:53], off offset:256 nt
	v_max_f32_e32 v46, v46, v46
	v_max_f32_e32 v43, 0, v43
	v_mul_f32_e32 v52, v42, v42
	v_max_f32_e32 v42, v47, v47
	v_max_f32_e32 v44, 0, v44
	v_max_f32_e32 v46, 0, v46
	v_max_f32_e32 v42, 0, v42
	v_mul_f32_e32 v47, v43, v43
	v_max_f32_e32 v43, v48, v48
	v_mul_f32_e32 v48, v44, v44
	v_max_f32_e32 v44, v49, v49
	v_mul_f32_e32 v46, v46, v46
	v_mul_f32_e32 v42, v42, v42
	v_max_f32_e32 v43, 0, v43
	v_max_f32_e32 v44, 0, v44
	v_max_f32_e32 v45, v45, v45
	s_mov_b32 s8, 0x240000
	v_mul_f32_e32 v43, v43, v43
	v_max_f32_e32 v45, 0, v45
	v_mul_f32_e32 v44, v44, v44
	v_cvt_pk_bf16_f32 v42, v46, v42
	v_add_co_u32_e32 v46, vcc, s8, v140
	v_max_f32_e32 v34, v34, v34
	v_max_f32_e32 v35, v35, v35
	v_max_f32_e32 v36, v36, v36
	v_mul_f32_e32 v45, v45, v45
	v_cvt_pk_bf16_f32 v43, v43, v44
	v_cvt_pk_bf16_f32 v44, v52, v47
	v_addc_co_u32_e32 v47, vcc, 0, v141, vcc
	v_max_f32_e32 v34, 0, v34
	v_max_f32_e32 v35, 0, v35
	v_max_f32_e32 v36, 0, v36
	v_cvt_pk_bf16_f32 v45, v48, v45
	global_store_dwordx4 v[46:47], v[42:45], off nt
	v_max_f32_e32 v37, v37, v37
	s_mov_b64 s[38:39], 0x240000
	v_mul_f32_e32 v42, v34, v34
	v_max_f32_e32 v34, v39, v39
	v_mul_f32_e32 v39, v35, v35
	v_max_f32_e32 v35, v40, v40
	v_mul_f32_e32 v40, v36, v36
	v_max_f32_e32 v36, v41, v41
	v_max_f32_e32 v35, 0, v35
	v_max_f32_e32 v36, 0, v36
	v_max_f32_e32 v38, v38, v38
	v_max_f32_e32 v34, 0, v34
	v_mul_f32_e32 v35, v35, v35
	v_max_f32_e32 v37, 0, v37
	v_mul_f32_e32 v36, v36, v36
	v_max_f32_e32 v26, v26, v26
	v_lshl_add_u64 v[50:51], v[140:141], 0, s[38:39]
	v_max_f32_e32 v38, 0, v38
	v_mul_f32_e32 v34, v34, v34
	v_mul_f32_e32 v37, v37, v37
	v_cvt_pk_bf16_f32 v35, v35, v36
; __device__ __forceinline__ unsigned cvt_pk_bf16(float lo, float hi) { unsigned r; asm("v_cvt_pk_bf16_f32 %0, %1, %2" : "=v"(r) : "v"(lo), "v"(hi)); return r; }
; #define PG8_WAIT_V(n) asm volatile("s_waitcnt vmcnt(" #n ")" ::: "memory")
; #define PG8_BAR __builtin_amdgcn_s_barrier()
;     __device__ __forceinline__ void operator()(const f32x4 (&acc)[2][2][4][2], const Unit& u, int wr, int wc, int fr, int fq) const {
;     ...
;         for (int ai = 0; ai < 2; ++ai)
; #pragma unroll
;             for (int m = 0; m < 4; ++m) { bf16_t* rowp = O + (size_t)(row0 + ai * HALF + m * 16) * ldc + col0;
; #pragma unroll
;                 for (int bj = 0; bj < 2; ++bj) { f32x4 v0 = acc[ai][bj][m][0], v1 = acc[ai][bj][m][1];
;                     if (ACT == 1) {
; #pragma unroll
;                         for (int j = 0; j < 4; ++j) { float a = fmaxf(v0[j], 0.f), b = fmaxf(v1[j], 0.f); v0[j] = a * a; v1[j] = b * b; } }
;                     u32x4 w; w.x = cvt_pk_bf16(v0[0], v0[1]); w.y = cvt_pk_bf16(v0[2], v0[3]); w.z = cvt_pk_bf16(v1[0], v1[1]); w.w = cvt_pk_bf16(v1[2], v1[3]);
;                     if (ACT == 1) __builtin_nontemporal_store(w, (u32x4*)(rowp + bj * HALF));
;                     else *(u32x4*)(rowp + bj * HALF) = w; } }
; template <class Epi, class Sched>
; __device__ __forceinline__ void gemm_phase(LAS unsigned char* lds, const Gemm g, const Sched& S, const Epi& E) {
;     ...
;         E(acc, cur, wr, wc, fr, fq);
;         if (!has_next) break;
; #pragma unroll
;         for (int a = 0; a < 2; ++a)
; #pragma unroll
;             for (int b = 0; b < 2; ++b)
; #pragma unroll
;                 for (int m = 0; m < 4; ++m)
; #pragma unroll
;                     for (int n = 0; n < 2; ++n) acc[a][b][m][n] = (f32x4){0.f, 0.f, 0.f, 0.f};
;         cur = nxt; cA = nA; cB = nB; ++ui;
;     }
;     PG8_WAIT_V(0);
;     if (wr == 0) PG8_BAR;
;     PG8_BAR;
	v_cvt_pk_bf16_f32 v36, v42, v39
	v_max_f32_e32 v26, 0, v26
	v_max_f32_e32 v27, v27, v27
	v_max_f32_e32 v28, v28, v28
	v_mul_f32_e32 v38, v38, v38
	v_cvt_pk_bf16_f32 v34, v38, v34
	v_cvt_pk_bf16_f32 v37, v40, v37
	global_store_dwordx4 v[50:51], v[34:37], off offset:256 nt
	v_max_f32_e32 v30, v30, v30
	v_max_f32_e32 v27, 0, v27
	v_mul_f32_e32 v36, v26, v26
	v_max_f32_e32 v26, v31, v31
	v_max_f32_e32 v28, 0, v28
	v_max_f32_e32 v30, 0, v30
	v_max_f32_e32 v26, 0, v26
	v_mul_f32_e32 v31, v27, v27
	v_max_f32_e32 v27, v32, v32
	v_mul_f32_e32 v32, v28, v28
	v_max_f32_e32 v28, v33, v33
	v_mul_f32_e32 v30, v30, v30
	v_mul_f32_e32 v26, v26, v26
	v_max_f32_e32 v27, 0, v27
	v_max_f32_e32 v28, 0, v28
	v_max_f32_e32 v29, v29, v29
	s_mov_b32 s8, 0x280000
	v_mul_f32_e32 v27, v27, v27
	v_max_f32_e32 v29, 0, v29
	v_mul_f32_e32 v28, v28, v28
	v_cvt_pk_bf16_f32 v26, v30, v26
	v_add_co_u32_e32 v30, vcc, s8, v140
	v_max_f32_e32 v18, v18, v18
	v_max_f32_e32 v19, v19, v19
	v_max_f32_e32 v20, v20, v20
	v_mul_f32_e32 v29, v29, v29
	v_cvt_pk_bf16_f32 v27, v27, v28
	v_cvt_pk_bf16_f32 v28, v36, v31
	v_addc_co_u32_e32 v31, vcc, 0, v141, vcc
	v_max_f32_e32 v18, 0, v18
	v_max_f32_e32 v19, 0, v19
	v_max_f32_e32 v20, 0, v20
	v_cvt_pk_bf16_f32 v29, v32, v29
	global_store_dwordx4 v[30:31], v[26:29], off nt
	v_max_f32_e32 v21, v21, v21
	s_mov_b64 s[38:39], 0x280000
	v_mul_f32_e32 v26, v18, v18
	v_max_f32_e32 v18, v23, v23
	v_mul_f32_e32 v23, v19, v19
	v_max_f32_e32 v19, v24, v24
	v_mul_f32_e32 v24, v20, v20
	v_max_f32_e32 v20, v25, v25
	v_max_f32_e32 v19, 0, v19
	v_max_f32_e32 v20, 0, v20
	v_max_f32_e32 v22, v22, v22
	v_max_f32_e32 v18, 0, v18
	v_mul_f32_e32 v19, v19, v19
	v_max_f32_e32 v21, 0, v21
	v_mul_f32_e32 v20, v20, v20
	v_max_f32_e32 v10, v10, v10
	v_lshl_add_u64 v[34:35], v[140:141], 0, s[38:39]
	v_max_f32_e32 v22, 0, v22
	v_mul_f32_e32 v18, v18, v18
	v_mul_f32_e32 v21, v21, v21
	v_cvt_pk_bf16_f32 v19, v19, v20
	v_cvt_pk_bf16_f32 v20, v26, v23
	v_max_f32_e32 v10, 0, v10
	v_max_f32_e32 v11, v11, v11
	v_max_f32_e32 v12, v12, v12
	v_mul_f32_e32 v22, v22, v22
	v_cvt_pk_bf16_f32 v18, v22, v18
	v_cvt_pk_bf16_f32 v21, v24, v21
	global_store_dwordx4 v[34:35], v[18:21], off offset:256 nt
	v_max_f32_e32 v14, v14, v14
	v_max_f32_e32 v11, 0, v11
	v_mul_f32_e32 v20, v10, v10
	v_max_f32_e32 v10, v15, v15
	v_max_f32_e32 v12, 0, v12
	v_max_f32_e32 v14, 0, v14
	v_max_f32_e32 v10, 0, v10
	v_mul_f32_e32 v15, v11, v11
	v_max_f32_e32 v11, v16, v16
	v_mul_f32_e32 v16, v12, v12
	v_max_f32_e32 v12, v17, v17
	v_mul_f32_e32 v14, v14, v14
	v_mul_f32_e32 v10, v10, v10
	v_max_f32_e32 v11, 0, v11
	v_max_f32_e32 v12, 0, v12
	v_max_f32_e32 v13, v13, v13
	s_mov_b32 s8, 0x2c0000
	v_mul_f32_e32 v11, v11, v11
	v_max_f32_e32 v13, 0, v13
	v_mul_f32_e32 v12, v12, v12
	v_cvt_pk_bf16_f32 v10, v14, v10
	v_add_co_u32_e32 v14, vcc, s8, v140
	v_max_f32_e32 v2, v2, v2
	v_max_f32_e32 v3, v3, v3
	v_max_f32_e32 v4, v4, v4
	v_mul_f32_e32 v13, v13, v13
	v_cvt_pk_bf16_f32 v11, v11, v12
	v_cvt_pk_bf16_f32 v12, v20, v15
	v_addc_co_u32_e32 v15, vcc, 0, v141, vcc
	v_max_f32_e32 v2, 0, v2
	v_max_f32_e32 v3, 0, v3
	v_max_f32_e32 v4, 0, v4
	v_cvt_pk_bf16_f32 v13, v16, v13
	global_store_dwordx4 v[14:15], v[10:13], off nt
	v_max_f32_e32 v5, v5, v5
	s_mov_b64 s[38:39], 0x2c0000
	v_mul_f32_e32 v10, v2, v2
	v_max_f32_e32 v2, v7, v7
	v_mul_f32_e32 v7, v3, v3
	v_max_f32_e32 v3, v8, v8
	v_mul_f32_e32 v8, v4, v4
	v_max_f32_e32 v4, v9, v9
	v_max_f32_e32 v6, v6, v6
	v_max_f32_e32 v2, 0, v2
	v_max_f32_e32 v3, 0, v3
	v_max_f32_e32 v4, 0, v4
	v_max_f32_e32 v5, 0, v5
	v_lshl_add_u64 v[18:19], v[140:141], 0, s[38:39]
	v_max_f32_e32 v6, 0, v6
	v_mul_f32_e32 v2, v2, v2
	v_mul_f32_e32 v3, v3, v3
	v_mul_f32_e32 v4, v4, v4
	v_mul_f32_e32 v5, v5, v5
	s_and_b64 vcc, exec, s[40:41]
	s_mov_b32 s68, s26
	s_mov_b32 s8, s28
	s_mov_b64 s[46:47], s[44:45]
	s_mov_b64 s[48:49], s[42:43]
	v_mul_f32_e32 v6, v6, v6
	v_cvt_pk_bf16_f32 v2, v6, v2
	v_cvt_pk_bf16_f32 v3, v3, v4
	v_cvt_pk_bf16_f32 v4, v10, v7
	v_cvt_pk_bf16_f32 v5, v8, v5
	global_store_dwordx4 v[18:19], v[2:5], off offset:256 nt
	s_cbranch_vccz .LBB0_70
	s_waitcnt vmcnt(0)
	s_cmpk_gt_u32 s52, 0xff
	s_cbranch_scc1 .LBB0_77
	s_barrier

; #define PG8_STAGE(bufoff, gbase, voff) do { _Pragma("unroll") for (int _i = 0; _i < 2; ++_i) \
;         __builtin_amdgcn_global_load_lds((const unsigned*)((const char*)(gbase) + (voff)[_i]), (LAS unsigned*)(lds + (bufoff) + ldsw + _i * 8192), 16, 0, 0); } while (0)
; #define PG8_LDA(dst, b, h) do { _Pragma("unroll") for (int m = 0; m < 4; ++m) _Pragma("unroll") for (int k = 0; k < 2; ++k) dst[m][k] = *(const LAS bf16x8*)(lds + PG8_SA(b, h) + aoff + m * 2048 + k * 1024); } while (0)
; #define PG8_LDB(dst, b, h) do { _Pragma("unroll") for (int n = 0; n < 2; ++n) _Pragma("unroll") for (int k = 0; k < 2; ++k) dst[n][k] = *(const LAS bf16x8*)(lds + PG8_SB(b, h) + boff + n * 2048 + k * 1024); } while (0)
; #define PG8_MMA(ai, bj, At, Bt) do { __builtin_amdgcn_s_setprio(1); _Pragma("unroll") for (int m = 0; m < 4; ++m) _Pragma("unroll") for (int n = 0; n < 2; ++n) _Pragma("unroll") for (int k = 0; k < 2; ++k) \
;         acc[ai][bj][m][n] = __builtin_amdgcn_mfma_f32_16x16x32_bf16(Bt[n][k], At[m][k], acc[ai][bj][m][n], 0, 0, 0); __builtin_amdgcn_s_setprio(0); } while (0)
; #define PG8_WAIT_L(n) asm volatile("s_waitcnt lgkmcnt(" #n ")" ::: "memory")
; #define PG8_BAR __builtin_amdgcn_s_barrier()
; #define PG8_SCHED __builtin_amdgcn_sched_barrier(0)
; template <class Epi, class Sched>
; __device__ __forceinline__ void gemm_phase(LAS unsigned char* lds, const Gemm g, const Sched& S, const Epi& E) {
;     ...
;             const bool last = (t == nt - 2);
;             const char* a1 = cA + (size_t)(t + 1) * kstep;
;             const char* a2 = last ? nA : cA + (size_t)(t + 2) * kstep; const char* b2 = last ? nB : cB + (size_t)(t + 2) * kstep;
;             const char* a3 = a2 + kstep; const char* b3 = b2 + kstep;
;             PG8_LDB(B0, 0, 0); PG8_SCHED; PG8_LDA(At, 0, 0); PG8_STAGE(PG8_SA(1, 1), a1 + hstep, voffA);
;             PG8_WAIT_L(8); PG8_BAR; PG8_WAIT_L(0); PG8_MMA(0, 0, At, B0); PG8_BAR; PG8_SCHED;
;             PG8_LDB(B1, 0, 1); PG8_STAGE(PG8_SB(0, 0), b2, voffB);
;             PG8_BAR; PG8_WAIT_L(0); PG8_MMA(0, 1, At, B1); PG8_BAR;
;             PG8_LDA(At, 0, 1); PG8_STAGE(PG8_SA(0, 0), a2, voffA);
;             PG8_BAR; PG8_WAIT_L(0); PG8_MMA(1, 0, At, B0); PG8_BAR; PG8_SCHED;
;             PG8_STAGE(PG8_SB(0, 1), b2 + hstep, voffB);
.LBB0_99:
	s_add_u32 s56, s28, 0x100
	s_addc_u32 s57, s29, 0
	s_cmp_eq_u32 s81, 28
	s_cselect_b32 s61, s51, s57
	s_cselect_b32 s60, s77, s56
	s_cselect_b32 s59, s49, s80
	s_cselect_b32 s58, s78, s79
	v_lshl_add_u64 v[156:157], s[28:29], 0, v[150:151]
	s_add_i32 m0, s9, 0xc000
	s_nop 0
	global_load_lds_dwordx4 v[156:157], off
	v_lshl_add_u64 v[156:157], s[28:29], 0, v[148:149]
	s_add_i32 m0, s9, 0xe000
	s_nop 0
	global_load_lds_dwordx4 v[156:157], off
	s_add_i32 s38, 0, 0x10000
	v_add_u32_e32 v110, s38, v169
	ds_read_b128 v[98:101], v110
	ds_read_b128 v[102:105], v110 offset:1024
	ds_read_b128 v[106:109], v110 offset:2048
	ds_read_b128 v[110:113], v110 offset:3072
	ds_read_b128 v[152:155], v171
	ds_read_b128 v[160:163], v171 offset:1024
	ds_read_b128 v[164:167], v171 offset:2048
	ds_read_b128 v[172:175], v171 offset:3072
	ds_read_b128 v[176:179], v171 offset:4096
	ds_read_b128 v[180:183], v171 offset:5120
	ds_read_b128 v[184:187], v171 offset:6144
	ds_read_b128 v[188:191], v171 offset:7168
	s_add_i32 s39, 0, 0x14000
	v_add_u32_e32 v156, s39, v169
	ds_read_b128 v[192:195], v156
	ds_read_b128 v[196:199], v156 offset:1024
	ds_read_b128 v[200:203], v156 offset:2048
	ds_read_b128 v[204:207], v156 offset:3072
	s_waitcnt lgkmcnt(4)
	s_barrier
	s_waitcnt lgkmcnt(0)
	s_setprio 1
	v_mfma_f32_16x16x32_bf16 v[142:145], v[98:101], v[152:155], v[142:145]
	v_mfma_f32_16x16x32_bf16 v[138:141], v[106:109], v[152:155], v[138:141]
	v_mfma_f32_16x16x32_bf16 v[126:129], v[98:101], v[164:167], v[126:129]
	v_mfma_f32_16x16x32_bf16 v[122:125], v[106:109], v[164:167], v[122:125]
	v_mfma_f32_16x16x32_bf16 v[94:97], v[98:101], v[176:179], v[94:97]
	v_mfma_f32_16x16x32_bf16 v[90:93], v[106:109], v[176:179], v[90:93]
	v_mfma_f32_16x16x32_bf16 v[86:89], v[98:101], v[184:187], v[86:89]
	v_mfma_f32_16x16x32_bf16 v[82:85], v[106:109], v[184:187], v[82:85]
	v_mfma_f32_16x16x32_bf16 v[142:145], v[102:105], v[160:163], v[142:145]
	v_mfma_f32_16x16x32_bf16 v[138:141], v[110:113], v[160:163], v[138:141]
	v_mfma_f32_16x16x32_bf16 v[126:129], v[102:105], v[172:175], v[126:129]
	v_mfma_f32_16x16x32_bf16 v[122:125], v[110:113], v[172:175], v[122:125]
	v_mfma_f32_16x16x32_bf16 v[94:97], v[102:105], v[180:183], v[94:97]
	v_mfma_f32_16x16x32_bf16 v[90:93], v[110:113], v[180:183], v[90:93]
	v_mfma_f32_16x16x32_bf16 v[86:89], v[102:105], v[188:191], v[86:89]
	v_mfma_f32_16x16x32_bf16 v[82:85], v[110:113], v[188:191], v[82:85]
	v_mfma_f32_16x16x32_bf16 v[134:137], v[192:195], v[152:155], v[134:137]
	v_mfma_f32_16x16x32_bf16 v[130:133], v[200:203], v[152:155], v[130:133]
	v_mfma_f32_16x16x32_bf16 v[118:121], v[192:195], v[164:167], v[118:121]
	v_mfma_f32_16x16x32_bf16 v[114:117], v[200:203], v[164:167], v[114:117]
	v_mfma_f32_16x16x32_bf16 v[78:81], v[192:195], v[176:179], v[78:81]
	v_mfma_f32_16x16x32_bf16 v[74:77], v[200:203], v[176:179], v[74:77]
	v_mfma_f32_16x16x32_bf16 v[70:73], v[192:195], v[184:187], v[70:73]
	v_mfma_f32_16x16x32_bf16 v[66:69], v[200:203], v[184:187], v[66:69]
	v_mfma_f32_16x16x32_bf16 v[134:137], v[196:199], v[160:163], v[134:137]
	v_mfma_f32_16x16x32_bf16 v[130:133], v[204:207], v[160:163], v[130:133]
	v_mfma_f32_16x16x32_bf16 v[118:121], v[196:199], v[172:175], v[118:121]
	v_mfma_f32_16x16x32_bf16 v[114:117], v[204:207], v[172:175], v[114:117]
	v_mfma_f32_16x16x32_bf16 v[78:81], v[196:199], v[180:183], v[78:81]
	v_mfma_f32_16x16x32_bf16 v[74:77], v[204:207], v[180:183], v[74:77]
	v_mfma_f32_16x16x32_bf16 v[70:73], v[196:199], v[188:191], v[70:73]
	v_mfma_f32_16x16x32_bf16 v[66:69], v[204:207], v[188:191], v[66:69]
	s_setprio 0
	s_barrier
	s_add_i32 s28, s38, s67
	v_lshl_add_u64 v[156:157], s[58:59], 0, v[0:1]
	s_mov_b32 m0, s28
	v_lshl_add_u64 v[210:211], s[58:59], 0, v[146:147]
	global_load_lds_dwordx4 v[156:157], off
	s_add_i32 m0, s28, 0x2000
	s_nop 0
	global_load_lds_dwordx4 v[210:211], off
	s_mov_b32 m0, s9
	v_lshl_add_u64 v[212:213], s[60:61], 0, v[0:1]
	global_load_lds_dwordx4 v[212:213], off
	v_lshl_add_u64 v[214:215], s[60:61], 0, v[146:147]
	s_mov_b32 m0, s68
	s_nop 0
	global_load_lds_dwordx4 v[214:215], off
	ds_read_b128 v[152:155], v171 offset:16384
	ds_read_b128 v[160:163], v171 offset:17408
	ds_read_b128 v[164:167], v171 offset:18432
	ds_read_b128 v[172:175], v171 offset:19456
	ds_read_b128 v[176:179], v171 offset:20480
	ds_read_b128 v[180:183], v171 offset:21504
	ds_read_b128 v[184:187], v171 offset:22528
	ds_read_b128 v[188:191], v171 offset:23552
	s_waitcnt vmcnt(4)
	s_waitcnt lgkmcnt(0)
	s_barrier
; #define PG8_STAGE(bufoff, gbase, voff) do { _Pragma("unroll") for (int _i = 0; _i < 2; ++_i) \
;         __builtin_amdgcn_global_load_lds((const unsigned*)((const char*)(gbase) + (voff)[_i]), (LAS unsigned*)(lds + (bufoff) + ldsw + _i * 8192), 16, 0, 0); } while (0)
; #define PG8_LDA(dst, b, h) do { _Pragma("unroll") for (int m = 0; m < 4; ++m) _Pragma("unroll") for (int k = 0; k < 2; ++k) dst[m][k] = *(const LAS bf16x8*)(lds + PG8_SA(b, h) + aoff + m * 2048 + k * 1024); } while (0)
; #define PG8_LDB(dst, b, h) do { _Pragma("unroll") for (int n = 0; n < 2; ++n) _Pragma("unroll") for (int k = 0; k < 2; ++k) dst[n][k] = *(const LAS bf16x8*)(lds + PG8_SB(b, h) + boff + n * 2048 + k * 1024); } while (0)
; #define PG8_MMA(ai, bj, At, Bt) do { __builtin_amdgcn_s_setprio(1); _Pragma("unroll") for (int m = 0; m < 4; ++m) _Pragma("unroll") for (int n = 0; n < 2; ++n) _Pragma("unroll") for (int k = 0; k < 2; ++k) \
;         acc[ai][bj][m][n] = __builtin_amdgcn_mfma_f32_16x16x32_bf16(Bt[n][k], At[m][k], acc[ai][bj][m][n], 0, 0, 0); __builtin_amdgcn_s_setprio(0); } while (0)
; #define PG8_WAIT_V(n) asm volatile("s_waitcnt vmcnt(" #n ")" ::: "memory")
; #define PG8_WAIT_L(n) asm volatile("s_waitcnt lgkmcnt(" #n ")" ::: "memory")
; #define PG8_BAR __builtin_amdgcn_s_barrier()
; #define PG8_SCHED __builtin_amdgcn_sched_barrier(0)
; template <class Epi, class Sched>
; __device__ __forceinline__ void gemm_phase(LAS unsigned char* lds, const Gemm g, const Sched& S, const Epi& E) {
;     ...
;             PG8_BAR; PG8_WAIT_L(0); PG8_MMA(0, 1, At, B1); PG8_BAR;
;             PG8_LDA(At, 0, 1); PG8_STAGE(PG8_SA(0, 0), a2, voffA);
;             PG8_BAR; PG8_WAIT_L(0); PG8_MMA(1, 0, At, B0); PG8_BAR; PG8_SCHED;
;             PG8_STAGE(PG8_SB(0, 1), b2 + hstep, voffB);
;             PG8_WAIT_V(6); PG8_BAR; PG8_MMA(1, 1, At, B1); PG8_BAR;
;             PG8_LDB(B0, 1, 0); PG8_SCHED; PG8_LDA(At, 1, 0); PG8_STAGE(PG8_SA(0, 1), a2 + hstep, voffA);
;             PG8_WAIT_L(8); PG8_BAR; PG8_WAIT_L(0); PG8_MMA(0, 0, At, B0); PG8_BAR; PG8_SCHED;
;             PG8_LDB(B1, 1, 1); PG8_STAGE(PG8_SB(1, 0), b3, voffB);
;             PG8_BAR; PG8_WAIT_L(0); PG8_MMA(0, 1, At, B1); PG8_BAR;
	s_setprio 1
	v_mfma_f32_16x16x32_bf16 v[62:65], v[98:101], v[152:155], v[62:65]
	v_mfma_f32_16x16x32_bf16 v[58:61], v[106:109], v[152:155], v[58:61]
	v_mfma_f32_16x16x32_bf16 v[46:49], v[98:101], v[164:167], v[46:49]
	v_mfma_f32_16x16x32_bf16 v[42:45], v[106:109], v[164:167], v[42:45]
	v_mfma_f32_16x16x32_bf16 v[30:33], v[98:101], v[176:179], v[30:33]
	v_mfma_f32_16x16x32_bf16 v[26:29], v[106:109], v[176:179], v[26:29]
	v_mfma_f32_16x16x32_bf16 v[22:25], v[98:101], v[184:187], v[22:25]
	v_mfma_f32_16x16x32_bf16 v[18:21], v[106:109], v[184:187], v[18:21]
	v_mfma_f32_16x16x32_bf16 v[62:65], v[102:105], v[160:163], v[62:65]
	v_mfma_f32_16x16x32_bf16 v[58:61], v[110:113], v[160:163], v[58:61]
	v_mfma_f32_16x16x32_bf16 v[46:49], v[102:105], v[172:175], v[46:49]
	v_mfma_f32_16x16x32_bf16 v[42:45], v[110:113], v[172:175], v[42:45]
	v_mfma_f32_16x16x32_bf16 v[30:33], v[102:105], v[180:183], v[30:33]
	v_mfma_f32_16x16x32_bf16 v[26:29], v[110:113], v[180:183], v[26:29]
	v_mfma_f32_16x16x32_bf16 v[22:25], v[102:105], v[188:191], v[22:25]
	v_mfma_f32_16x16x32_bf16 v[18:21], v[110:113], v[188:191], v[18:21]
	s_add_u32 s28, s58, 0x80000
	s_addc_u32 s29, s59, 0
	s_add_i32 s38, s39, s67
	v_lshl_add_u64 v[98:99], s[28:29], 0, v[0:1]
	s_mov_b32 m0, s38
	s_nop 0
	global_load_lds_dwordx4 v[98:99], off
	v_lshl_add_u64 v[98:99], s[28:29], 0, v[146:147]
	s_add_i32 m0, s38, 0x2000
	s_nop 0
	global_load_lds_dwordx4 v[98:99], off
	v_mfma_f32_16x16x32_bf16 v[54:57], v[192:195], v[152:155], v[54:57]
	v_mfma_f32_16x16x32_bf16 v[50:53], v[200:203], v[152:155], v[50:53]
	v_mfma_f32_16x16x32_bf16 v[38:41], v[192:195], v[164:167], v[38:41]
	v_mfma_f32_16x16x32_bf16 v[34:37], v[200:203], v[164:167], v[34:37]
	v_mfma_f32_16x16x32_bf16 v[14:17], v[192:195], v[176:179], v[14:17]
	v_mfma_f32_16x16x32_bf16 v[10:13], v[200:203], v[176:179], v[10:13]
	v_mfma_f32_16x16x32_bf16 v[6:9], v[192:195], v[184:187], v[6:9]
	v_mfma_f32_16x16x32_bf16 v[2:5], v[200:203], v[184:187], v[2:5]
	v_mfma_f32_16x16x32_bf16 v[54:57], v[196:199], v[160:163], v[54:57]
	v_mfma_f32_16x16x32_bf16 v[50:53], v[204:207], v[160:163], v[50:53]
	v_mfma_f32_16x16x32_bf16 v[38:41], v[196:199], v[172:175], v[38:41]
	v_mfma_f32_16x16x32_bf16 v[34:37], v[204:207], v[172:175], v[34:37]
	v_mfma_f32_16x16x32_bf16 v[14:17], v[196:199], v[180:183], v[14:17]
	v_mfma_f32_16x16x32_bf16 v[10:13], v[204:207], v[180:183], v[10:13]
	v_mfma_f32_16x16x32_bf16 v[6:9], v[196:199], v[188:191], v[6:9]
	v_mfma_f32_16x16x32_bf16 v[2:5], v[204:207], v[188:191], v[2:5]
	s_setprio 0
	s_barrier
	s_add_u32 s28, s60, 0x80000
	s_addc_u32 s29, s61, 0
	s_mov_b32 m0, s69
	v_lshl_add_u64 v[192:193], s[28:29], 0, v[0:1]
	global_load_lds_dwordx4 v[192:193], off
	v_lshl_add_u64 v[192:193], s[28:29], 0, v[146:147]
	s_mov_b32 m0, s70
	s_nop 0
	global_load_lds_dwordx4 v[192:193], off
	s_add_i32 s38, 0, 0x18000
	v_add_u32_e32 v110, s38, v169
	ds_read_b128 v[98:101], v110
	ds_read_b128 v[102:105], v110 offset:1024
	ds_read_b128 v[106:109], v110 offset:2048
	ds_read_b128 v[110:113], v110 offset:3072
	ds_read_b128 v[152:155], v171 offset:32768
	ds_read_b128 v[160:163], v171 offset:33792
	ds_read_b128 v[164:167], v171 offset:34816
	ds_read_b128 v[172:175], v171 offset:35840
	ds_read_b128 v[176:179], v171 offset:36864
	ds_read_b128 v[180:183], v171 offset:37888
	ds_read_b128 v[184:187], v171 offset:38912
	ds_read_b128 v[188:191], v171 offset:39936
	s_add_i32 s39, 0, 0x1c000
	v_add_u32_e32 v204, s39, v169
	ds_read_b128 v[192:195], v204
	ds_read_b128 v[196:199], v204 offset:1024
	ds_read_b128 v[200:203], v204 offset:2048
	ds_read_b128 v[204:207], v204 offset:3072
	s_waitcnt lgkmcnt(4)
	s_barrier
	s_waitcnt lgkmcnt(0)
	s_setprio 1
	v_mfma_f32_16x16x32_bf16 v[142:145], v[98:101], v[152:155], v[142:145]
	v_mfma_f32_16x16x32_bf16 v[138:141], v[106:109], v[152:155], v[138:141]
	v_mfma_f32_16x16x32_bf16 v[126:129], v[98:101], v[164:167], v[126:129]
	v_mfma_f32_16x16x32_bf16 v[122:125], v[106:109], v[164:167], v[122:125]
	v_mfma_f32_16x16x32_bf16 v[94:97], v[98:101], v[176:179], v[94:97]
	v_mfma_f32_16x16x32_bf16 v[90:93], v[106:109], v[176:179], v[90:93]
	v_mfma_f32_16x16x32_bf16 v[86:89], v[98:101], v[184:187], v[86:89]
	v_mfma_f32_16x16x32_bf16 v[82:85], v[106:109], v[184:187], v[82:85]
	v_mfma_f32_16x16x32_bf16 v[142:145], v[102:105], v[160:163], v[142:145]
	v_mfma_f32_16x16x32_bf16 v[138:141], v[110:113], v[160:163], v[138:141]
	v_mfma_f32_16x16x32_bf16 v[126:129], v[102:105], v[172:175], v[126:129]
	v_mfma_f32_16x16x32_bf16 v[122:125], v[110:113], v[172:175], v[122:125]
	v_mfma_f32_16x16x32_bf16 v[94:97], v[102:105], v[180:183], v[94:97]
	v_mfma_f32_16x16x32_bf16 v[90:93], v[110:113], v[180:183], v[90:93]
	v_mfma_f32_16x16x32_bf16 v[86:89], v[102:105], v[188:191], v[86:89]
	v_mfma_f32_16x16x32_bf16 v[82:85], v[110:113], v[188:191], v[82:85]
	v_mfma_f32_16x16x32_bf16 v[134:137], v[192:195], v[152:155], v[134:137]
	v_mfma_f32_16x16x32_bf16 v[130:133], v[200:203], v[152:155], v[130:133]
	v_mfma_f32_16x16x32_bf16 v[118:121], v[192:195], v[164:167], v[118:121]
	v_mfma_f32_16x16x32_bf16 v[114:117], v[200:203], v[164:167], v[114:117]
	v_mfma_f32_16x16x32_bf16 v[78:81], v[192:195], v[176:179], v[78:81]
	v_mfma_f32_16x16x32_bf16 v[74:77], v[200:203], v[176:179], v[74:77]
	v_mfma_f32_16x16x32_bf16 v[70:73], v[192:195], v[184:187], v[70:73]
	v_mfma_f32_16x16x32_bf16 v[66:69], v[200:203], v[184:187], v[66:69]
	v_mfma_f32_16x16x32_bf16 v[134:137], v[196:199], v[160:163], v[134:137]
	v_mfma_f32_16x16x32_bf16 v[130:133], v[204:207], v[160:163], v[130:133]
	v_mfma_f32_16x16x32_bf16 v[118:121], v[196:199], v[172:175], v[118:121]
	v_mfma_f32_16x16x32_bf16 v[114:117], v[204:207], v[172:175], v[114:117]
	v_mfma_f32_16x16x32_bf16 v[78:81], v[196:199], v[180:183], v[78:81]
	v_mfma_f32_16x16x32_bf16 v[74:77], v[204:207], v[180:183], v[74:77]
	v_mfma_f32_16x16x32_bf16 v[70:73], v[196:199], v[188:191], v[70:73]
	v_mfma_f32_16x16x32_bf16 v[66:69], v[204:207], v[188:191], v[66:69]
	s_setprio 0
	s_barrier
; #define PG8_STAGE(bufoff, gbase, voff) do { _Pragma("unroll") for (int _i = 0; _i < 2; ++_i) \
;         __builtin_amdgcn_global_load_lds((const unsigned*)((const char*)(gbase) + (voff)[_i]), (LAS unsigned*)(lds + (bufoff) + ldsw + _i * 8192), 16, 0, 0); } while (0)
; #define PG8_LDA(dst, b, h) do { _Pragma("unroll") for (int m = 0; m < 4; ++m) _Pragma("unroll") for (int k = 0; k < 2; ++k) dst[m][k] = *(const LAS bf16x8*)(lds + PG8_SA(b, h) + aoff + m * 2048 + k * 1024); } while (0)
; #define PG8_LDB(dst, b, h) do { _Pragma("unroll") for (int n = 0; n < 2; ++n) _Pragma("unroll") for (int k = 0; k < 2; ++k) dst[n][k] = *(const LAS bf16x8*)(lds + PG8_SB(b, h) + boff + n * 2048 + k * 1024); } while (0)
; #define PG8_MMA(ai, bj, At, Bt) do { __builtin_amdgcn_s_setprio(1); _Pragma("unroll") for (int m = 0; m < 4; ++m) _Pragma("unroll") for (int n = 0; n < 2; ++n) _Pragma("unroll") for (int k = 0; k < 2; ++k) \
;         acc[ai][bj][m][n] = __builtin_amdgcn_mfma_f32_16x16x32_bf16(Bt[n][k], At[m][k], acc[ai][bj][m][n], 0, 0, 0); __builtin_amdgcn_s_setprio(0); } while (0)
; #define PG8_WAIT_V(n) asm volatile("s_waitcnt vmcnt(" #n ")" ::: "memory")
; #define PG8_WAIT_L(n) asm volatile("s_waitcnt lgkmcnt(" #n ")" ::: "memory")
; #define PG8_BAR __builtin_amdgcn_s_barrier()
; #define PG8_SCHED __builtin_amdgcn_sched_barrier(0)
; template <class Epi, class Sched>
; __device__ __forceinline__ void gemm_phase(LAS unsigned char* lds, const Gemm g, const Sched& S, const Epi& E) {
;     ...
;             PG8_LDB(B1, 1, 1); PG8_STAGE(PG8_SB(1, 0), b3, voffB);
;             PG8_BAR; PG8_WAIT_L(0); PG8_MMA(0, 1, At, B1); PG8_BAR;
;             PG8_LDA(At, 1, 1); PG8_STAGE(PG8_SA(1, 0), a3, voffA);
;             PG8_BAR; PG8_WAIT_L(0); PG8_MMA(1, 0, At, B0); PG8_BAR; PG8_SCHED;
;             PG8_STAGE(PG8_SB(1, 1), b3 + hstep, voffB);
;             PG8_WAIT_V(6); PG8_BAR; PG8_MMA(1, 1, At, B1); PG8_BAR;
;         }
;         E(acc, cur, wr, wc, fr, fq);
;         if (!has_next) break;
	s_add_i32 s28, s38, s67
	v_lshl_add_u64 v[156:157], v[156:157], 0, s[36:37]
	s_mov_b32 m0, s28
	s_nop 0
	global_load_lds_dwordx4 v[156:157], off
	v_lshl_add_u64 v[156:157], v[210:211], 0, s[36:37]
	s_add_i32 m0, s28, 0x2000
	s_nop 0
	global_load_lds_dwordx4 v[156:157], off
	s_mov_b32 m0, s72
	v_lshl_add_u64 v[156:157], v[212:213], 0, s[36:37]
	global_load_lds_dwordx4 v[156:157], off
	v_lshl_add_u64 v[156:157], v[214:215], 0, s[36:37]
	s_mov_b32 m0, s73
	s_nop 0
	global_load_lds_dwordx4 v[156:157], off
	ds_read_b128 v[152:155], v171 offset:49152
	ds_read_b128 v[160:163], v171 offset:50176
	ds_read_b128 v[164:167], v171 offset:51200
	ds_read_b128 v[172:175], v171 offset:52224
	ds_read_b128 v[176:179], v171 offset:53248
	ds_read_b128 v[180:183], v171 offset:54272
	ds_read_b128 v[184:187], v171 offset:55296
	ds_read_b128 v[188:191], v171 offset:56320
	s_waitcnt vmcnt(4)
	s_waitcnt lgkmcnt(0)
	s_barrier
	s_setprio 1
	v_mfma_f32_16x16x32_bf16 v[62:65], v[98:101], v[152:155], v[62:65]
	v_mfma_f32_16x16x32_bf16 v[58:61], v[106:109], v[152:155], v[58:61]
	v_mfma_f32_16x16x32_bf16 v[46:49], v[98:101], v[164:167], v[46:49]
	v_mfma_f32_16x16x32_bf16 v[42:45], v[106:109], v[164:167], v[42:45]
	v_mfma_f32_16x16x32_bf16 v[30:33], v[98:101], v[176:179], v[30:33]
	v_mfma_f32_16x16x32_bf16 v[26:29], v[106:109], v[176:179], v[26:29]
	v_mfma_f32_16x16x32_bf16 v[22:25], v[98:101], v[184:187], v[22:25]
	v_mfma_f32_16x16x32_bf16 v[18:21], v[106:109], v[184:187], v[18:21]
	v_mfma_f32_16x16x32_bf16 v[62:65], v[102:105], v[160:163], v[62:65]
	v_mfma_f32_16x16x32_bf16 v[58:61], v[110:113], v[160:163], v[58:61]
	v_mfma_f32_16x16x32_bf16 v[46:49], v[102:105], v[172:175], v[46:49]
	v_mfma_f32_16x16x32_bf16 v[42:45], v[110:113], v[172:175], v[42:45]
	v_mfma_f32_16x16x32_bf16 v[30:33], v[102:105], v[180:183], v[30:33]
	v_mfma_f32_16x16x32_bf16 v[26:29], v[110:113], v[180:183], v[26:29]
	v_mfma_f32_16x16x32_bf16 v[22:25], v[102:105], v[188:191], v[22:25]
	v_mfma_f32_16x16x32_bf16 v[18:21], v[110:113], v[188:191], v[18:21]
	s_add_u32 s28, s58, 0x80080
	s_addc_u32 s29, s59, 0
	s_add_i32 s38, s39, s67
	v_lshl_add_u64 v[98:99], s[28:29], 0, v[0:1]
	s_mov_b32 m0, s38
	s_nop 0
	global_load_lds_dwordx4 v[98:99], off
	v_lshl_add_u64 v[98:99], s[28:29], 0, v[146:147]
	s_add_i32 m0, s38, 0x2000
	s_nop 0
	global_load_lds_dwordx4 v[98:99], off
	v_mfma_f32_16x16x32_bf16 v[54:57], v[192:195], v[152:155], v[54:57]
	v_mfma_f32_16x16x32_bf16 v[50:53], v[200:203], v[152:155], v[50:53]
	v_mfma_f32_16x16x32_bf16 v[38:41], v[192:195], v[164:167], v[38:41]
	v_mfma_f32_16x16x32_bf16 v[34:37], v[200:203], v[164:167], v[34:37]
	v_mfma_f32_16x16x32_bf16 v[14:17], v[192:195], v[176:179], v[14:17]
	v_mfma_f32_16x16x32_bf16 v[10:13], v[200:203], v[176:179], v[10:13]
	v_mfma_f32_16x16x32_bf16 v[6:9], v[192:195], v[184:187], v[6:9]
	v_mfma_f32_16x16x32_bf16 v[2:5], v[200:203], v[184:187], v[2:5]
	v_mfma_f32_16x16x32_bf16 v[54:57], v[196:199], v[160:163], v[54:57]
	v_mfma_f32_16x16x32_bf16 v[50:53], v[204:207], v[160:163], v[50:53]
	v_mfma_f32_16x16x32_bf16 v[38:41], v[196:199], v[172:175], v[38:41]
	v_mfma_f32_16x16x32_bf16 v[34:37], v[204:207], v[172:175], v[34:37]
	v_mfma_f32_16x16x32_bf16 v[14:17], v[196:199], v[180:183], v[14:17]
	v_mfma_f32_16x16x32_bf16 v[10:13], v[204:207], v[180:183], v[10:13]
	v_mfma_f32_16x16x32_bf16 v[6:9], v[196:199], v[188:191], v[6:9]
	v_mfma_f32_16x16x32_bf16 v[2:5], v[204:207], v[188:191], v[2:5]
	s_setprio 0
	s_add_i32 s81, s81, 2
	s_add_u32 s79, s79, 0x100
	s_addc_u32 s80, s80, 0
	s_cmp_gt_u32 s81, 29
	s_mov_b64 s[28:29], s[56:57]
	s_barrier
	s_cbranch_scc0 .LBB0_99
	s_cmp_lt_i32 s8, 64
	s_cselect_b64 s[58:59], -1, 0
	s_cmp_gt_i32 s8, 63
	s_cbranch_scc0 .LBB0_90
	s_mov_b64 s[60:61], 0x18000
	s_mov_b64 s[28:29], s[46:47]
	s_mov_b64 s[56:57], s[24:25]
	s_branch .LBB0_91

; #define PG8_STAGE(bufoff, gbase, voff) do { _Pragma("unroll") for (int _i = 0; _i < 2; ++_i) \
;         __builtin_amdgcn_global_load_lds((const unsigned*)((const char*)(gbase) + (voff)[_i]), (LAS unsigned*)(lds + (bufoff) + ldsw + _i * 8192), 16, 0, 0); } while (0)
; #define PG8_LDA(dst, b, h) do { _Pragma("unroll") for (int m = 0; m < 4; ++m) _Pragma("unroll") for (int k = 0; k < 2; ++k) dst[m][k] = *(const LAS bf16x8*)(lds + PG8_SA(b, h) + aoff + m * 2048 + k * 1024); } while (0)
; #define PG8_LDB(dst, b, h) do { _Pragma("unroll") for (int n = 0; n < 2; ++n) _Pragma("unroll") for (int k = 0; k < 2; ++k) dst[n][k] = *(const LAS bf16x8*)(lds + PG8_SB(b, h) + boff + n * 2048 + k * 1024); } while (0)
; #define PG8_MMA(ai, bj, At, Bt) do { __builtin_amdgcn_s_setprio(1); _Pragma("unroll") for (int m = 0; m < 4; ++m) _Pragma("unroll") for (int n = 0; n < 2; ++n) _Pragma("unroll") for (int k = 0; k < 2; ++k) \
;         acc[ai][bj][m][n] = __builtin_amdgcn_mfma_f32_16x16x32_bf16(Bt[n][k], At[m][k], acc[ai][bj][m][n], 0, 0, 0); __builtin_amdgcn_s_setprio(0); } while (0)
; #define PG8_WAIT_L(n) asm volatile("s_waitcnt lgkmcnt(" #n ")" ::: "memory")
; #define PG8_BAR __builtin_amdgcn_s_barrier()
; #define PG8_SCHED __builtin_amdgcn_sched_barrier(0)
; template <class Epi, class Sched>
; __device__ __forceinline__ void gemm_phase(LAS unsigned char* lds, const Gemm g, const Sched& S, const Epi& E) {
;     ...
;             const bool last = (t == nt - 2);
;             const char* a1 = cA + (size_t)(t + 1) * kstep;
;             const char* a2 = last ? nA : cA + (size_t)(t + 2) * kstep; const char* b2 = last ? nB : cB + (size_t)(t + 2) * kstep;
;             const char* a3 = a2 + kstep; const char* b3 = b2 + kstep;
;             PG8_LDB(B0, 0, 0); PG8_SCHED; PG8_LDA(At, 0, 0); PG8_STAGE(PG8_SA(1, 1), a1 + hstep, voffA);
;             PG8_WAIT_L(8); PG8_BAR; PG8_WAIT_L(0); PG8_MMA(0, 0, At, B0); PG8_BAR; PG8_SCHED;
;             PG8_LDB(B1, 0, 1); PG8_STAGE(PG8_SB(0, 0), b2, voffB);
;             PG8_BAR; PG8_WAIT_L(0); PG8_MMA(0, 1, At, B1); PG8_BAR;
;             PG8_LDA(At, 0, 1); PG8_STAGE(PG8_SA(0, 0), a2, voffA);
;             PG8_BAR; PG8_WAIT_L(0); PG8_MMA(1, 0, At, B0); PG8_BAR; PG8_SCHED;
;             PG8_STAGE(PG8_SB(0, 1), b2 + hstep, voffB);
.LBB0_113:
	s_add_u32 s54, s52, 0x100
	s_addc_u32 s55, s53, 0
	s_cmp_eq_u32 s73, 4
	s_cselect_b32 s59, s11, s55
	s_cselect_b32 s58, s29, s54
	s_cselect_b32 s57, s41, s72
	s_cselect_b32 s56, s45, s71
	v_lshl_add_u64 v[156:157], s[52:53], 0, v[134:135]
	s_add_i32 m0, s25, 0xc000
	s_nop 0
	global_load_lds_dwordx4 v[156:157], off
	v_lshl_add_u64 v[156:157], s[52:53], 0, v[132:133]
	s_add_i32 m0, s25, 0xe000
	s_nop 0
	global_load_lds_dwordx4 v[156:157], off
	s_add_i32 s38, 0, 0x10000
	v_add_u32_e32 v152, s38, v137
	ds_read_b128 v[140:143], v152
	ds_read_b128 v[144:147], v152 offset:1024
	ds_read_b128 v[148:151], v152 offset:2048
	ds_read_b128 v[152:155], v152 offset:3072
	ds_read_b128 v[160:163], v139
	ds_read_b128 v[164:167], v139 offset:1024
	ds_read_b128 v[168:171], v139 offset:2048
	ds_read_b128 v[172:175], v139 offset:3072
	ds_read_b128 v[176:179], v139 offset:4096
	ds_read_b128 v[180:183], v139 offset:5120
	ds_read_b128 v[184:187], v139 offset:6144
	ds_read_b128 v[188:191], v139 offset:7168
	s_add_i32 s52, 0, 0x14000
	v_add_u32_e32 v156, s52, v137
	ds_read_b128 v[192:195], v156
	ds_read_b128 v[196:199], v156 offset:1024
	ds_read_b128 v[200:203], v156 offset:2048
	ds_read_b128 v[204:207], v156 offset:3072
	s_waitcnt lgkmcnt(4)
	s_barrier
	s_waitcnt lgkmcnt(0)
	s_setprio 1
	v_mfma_f32_16x16x32_bf16 v[126:129], v[140:143], v[160:163], v[126:129]
	v_mfma_f32_16x16x32_bf16 v[122:125], v[148:151], v[160:163], v[122:125]
	v_mfma_f32_16x16x32_bf16 v[118:121], v[140:143], v[168:171], v[118:121]
	v_mfma_f32_16x16x32_bf16 v[114:117], v[148:151], v[168:171], v[114:117]
	v_mfma_f32_16x16x32_bf16 v[106:109], v[140:143], v[176:179], v[106:109]
	v_mfma_f32_16x16x32_bf16 v[98:101], v[148:151], v[176:179], v[98:101]
	v_mfma_f32_16x16x32_bf16 v[90:93], v[140:143], v[184:187], v[90:93]
	v_mfma_f32_16x16x32_bf16 v[82:85], v[148:151], v[184:187], v[82:85]
	v_mfma_f32_16x16x32_bf16 v[126:129], v[144:147], v[164:167], v[126:129]
	v_mfma_f32_16x16x32_bf16 v[122:125], v[152:155], v[164:167], v[122:125]
	v_mfma_f32_16x16x32_bf16 v[118:121], v[144:147], v[172:175], v[118:121]
	v_mfma_f32_16x16x32_bf16 v[114:117], v[152:155], v[172:175], v[114:117]
	v_mfma_f32_16x16x32_bf16 v[106:109], v[144:147], v[180:183], v[106:109]
	v_mfma_f32_16x16x32_bf16 v[98:101], v[152:155], v[180:183], v[98:101]
	v_mfma_f32_16x16x32_bf16 v[90:93], v[144:147], v[188:191], v[90:93]
	v_mfma_f32_16x16x32_bf16 v[82:85], v[152:155], v[188:191], v[82:85]
	v_mfma_f32_16x16x32_bf16 v[110:113], v[192:195], v[160:163], v[110:113]
	v_mfma_f32_16x16x32_bf16 v[102:105], v[200:203], v[160:163], v[102:105]
	v_mfma_f32_16x16x32_bf16 v[94:97], v[192:195], v[168:171], v[94:97]
	v_mfma_f32_16x16x32_bf16 v[86:89], v[200:203], v[168:171], v[86:89]
	v_mfma_f32_16x16x32_bf16 v[78:81], v[192:195], v[176:179], v[78:81]
	v_mfma_f32_16x16x32_bf16 v[74:77], v[200:203], v[176:179], v[74:77]
	v_mfma_f32_16x16x32_bf16 v[70:73], v[192:195], v[184:187], v[70:73]
	v_mfma_f32_16x16x32_bf16 v[66:69], v[200:203], v[184:187], v[66:69]
	v_mfma_f32_16x16x32_bf16 v[110:113], v[196:199], v[164:167], v[110:113]
	v_mfma_f32_16x16x32_bf16 v[102:105], v[204:207], v[164:167], v[102:105]
	v_mfma_f32_16x16x32_bf16 v[94:97], v[196:199], v[172:175], v[94:97]
	v_mfma_f32_16x16x32_bf16 v[86:89], v[204:207], v[172:175], v[86:89]
	v_mfma_f32_16x16x32_bf16 v[78:81], v[196:199], v[180:183], v[78:81]
	v_mfma_f32_16x16x32_bf16 v[74:77], v[204:207], v[180:183], v[74:77]
	v_mfma_f32_16x16x32_bf16 v[70:73], v[196:199], v[188:191], v[70:73]
	v_mfma_f32_16x16x32_bf16 v[66:69], v[204:207], v[188:191], v[66:69]
	s_setprio 0
	s_barrier
	s_add_i32 s38, s38, s65
	v_lshl_add_u64 v[156:157], s[56:57], 0, v[0:1]
	s_mov_b32 m0, s38
	v_lshl_add_u64 v[210:211], s[56:57], 0, v[130:131]
	global_load_lds_dwordx4 v[156:157], off
	s_add_i32 m0, s38, 0x2000
	s_nop 0
	global_load_lds_dwordx4 v[210:211], off
	s_mov_b32 m0, s25
	v_lshl_add_u64 v[212:213], s[58:59], 0, v[0:1]
	global_load_lds_dwordx4 v[212:213], off
	v_lshl_add_u64 v[214:215], s[58:59], 0, v[130:131]
	s_mov_b32 m0, s27
	s_nop 0
	global_load_lds_dwordx4 v[214:215], off
	ds_read_b128 v[160:163], v139 offset:16384
	ds_read_b128 v[164:167], v139 offset:17408
	ds_read_b128 v[168:171], v139 offset:18432
	ds_read_b128 v[172:175], v139 offset:19456
	ds_read_b128 v[176:179], v139 offset:20480
	ds_read_b128 v[180:183], v139 offset:21504
	ds_read_b128 v[184:187], v139 offset:22528
	ds_read_b128 v[188:191], v139 offset:23552
	s_waitcnt vmcnt(4)
	s_waitcnt lgkmcnt(0)
	s_barrier
; #define PG8_STAGE(bufoff, gbase, voff) do { _Pragma("unroll") for (int _i = 0; _i < 2; ++_i) \
;         __builtin_amdgcn_global_load_lds((const unsigned*)((const char*)(gbase) + (voff)[_i]), (LAS unsigned*)(lds + (bufoff) + ldsw + _i * 8192), 16, 0, 0); } while (0)
; #define PG8_LDA(dst, b, h) do { _Pragma("unroll") for (int m = 0; m < 4; ++m) _Pragma("unroll") for (int k = 0; k < 2; ++k) dst[m][k] = *(const LAS bf16x8*)(lds + PG8_SA(b, h) + aoff + m * 2048 + k * 1024); } while (0)
; #define PG8_LDB(dst, b, h) do { _Pragma("unroll") for (int n = 0; n < 2; ++n) _Pragma("unroll") for (int k = 0; k < 2; ++k) dst[n][k] = *(const LAS bf16x8*)(lds + PG8_SB(b, h) + boff + n * 2048 + k * 1024); } while (0)
; #define PG8_MMA(ai, bj, At, Bt) do { __builtin_amdgcn_s_setprio(1); _Pragma("unroll") for (int m = 0; m < 4; ++m) _Pragma("unroll") for (int n = 0; n < 2; ++n) _Pragma("unroll") for (int k = 0; k < 2; ++k) \
;         acc[ai][bj][m][n] = __builtin_amdgcn_mfma_f32_16x16x32_bf16(Bt[n][k], At[m][k], acc[ai][bj][m][n], 0, 0, 0); __builtin_amdgcn_s_setprio(0); } while (0)
; #define PG8_WAIT_V(n) asm volatile("s_waitcnt vmcnt(" #n ")" ::: "memory")
; #define PG8_WAIT_L(n) asm volatile("s_waitcnt lgkmcnt(" #n ")" ::: "memory")
; #define PG8_BAR __builtin_amdgcn_s_barrier()
; #define PG8_SCHED __builtin_amdgcn_sched_barrier(0)
; template <class Epi, class Sched>
; __device__ __forceinline__ void gemm_phase(LAS unsigned char* lds, const Gemm g, const Sched& S, const Epi& E) {
;     ...
;             PG8_BAR; PG8_WAIT_L(0); PG8_MMA(0, 1, At, B1); PG8_BAR;
;             PG8_LDA(At, 0, 1); PG8_STAGE(PG8_SA(0, 0), a2, voffA);
;             PG8_BAR; PG8_WAIT_L(0); PG8_MMA(1, 0, At, B0); PG8_BAR; PG8_SCHED;
;             PG8_STAGE(PG8_SB(0, 1), b2 + hstep, voffB);
;             PG8_WAIT_V(6); PG8_BAR; PG8_MMA(1, 1, At, B1); PG8_BAR;
;             PG8_LDB(B0, 1, 0); PG8_SCHED; PG8_LDA(At, 1, 0); PG8_STAGE(PG8_SA(0, 1), a2 + hstep, voffA);
;             PG8_WAIT_L(8); PG8_BAR; PG8_WAIT_L(0); PG8_MMA(0, 0, At, B0); PG8_BAR; PG8_SCHED;
;             PG8_LDB(B1, 1, 1); PG8_STAGE(PG8_SB(1, 0), b3, voffB);
;             PG8_BAR; PG8_WAIT_L(0); PG8_MMA(0, 1, At, B1); PG8_BAR;
	s_setprio 1
	v_mfma_f32_16x16x32_bf16 v[62:65], v[140:143], v[160:163], v[62:65]
	v_mfma_f32_16x16x32_bf16 v[58:61], v[148:151], v[160:163], v[58:61]
	v_mfma_f32_16x16x32_bf16 v[54:57], v[140:143], v[168:171], v[54:57]
	v_mfma_f32_16x16x32_bf16 v[50:53], v[148:151], v[168:171], v[50:53]
	v_mfma_f32_16x16x32_bf16 v[38:41], v[140:143], v[176:179], v[38:41]
	v_mfma_f32_16x16x32_bf16 v[34:37], v[148:151], v[176:179], v[34:37]
	v_mfma_f32_16x16x32_bf16 v[22:25], v[140:143], v[184:187], v[22:25]
	v_mfma_f32_16x16x32_bf16 v[18:21], v[148:151], v[184:187], v[18:21]
	v_mfma_f32_16x16x32_bf16 v[62:65], v[144:147], v[164:167], v[62:65]
	v_mfma_f32_16x16x32_bf16 v[58:61], v[152:155], v[164:167], v[58:61]
	v_mfma_f32_16x16x32_bf16 v[54:57], v[144:147], v[172:175], v[54:57]
	v_mfma_f32_16x16x32_bf16 v[50:53], v[152:155], v[172:175], v[50:53]
	v_mfma_f32_16x16x32_bf16 v[38:41], v[144:147], v[180:183], v[38:41]
	v_mfma_f32_16x16x32_bf16 v[34:37], v[152:155], v[180:183], v[34:37]
	v_mfma_f32_16x16x32_bf16 v[22:25], v[144:147], v[188:191], v[22:25]
	v_mfma_f32_16x16x32_bf16 v[18:21], v[152:155], v[188:191], v[18:21]
	s_add_u32 s38, s56, 0x80000
	s_addc_u32 s39, s57, 0
	s_add_i32 s52, s52, s65
	v_lshl_add_u64 v[140:141], s[38:39], 0, v[0:1]
	s_mov_b32 m0, s52
	s_nop 0
	global_load_lds_dwordx4 v[140:141], off
	v_lshl_add_u64 v[140:141], s[38:39], 0, v[130:131]
	s_add_i32 m0, s52, 0x2000
	s_nop 0
	global_load_lds_dwordx4 v[140:141], off
	v_mfma_f32_16x16x32_bf16 v[46:49], v[192:195], v[160:163], v[46:49]
	v_mfma_f32_16x16x32_bf16 v[42:45], v[200:203], v[160:163], v[42:45]
	v_mfma_f32_16x16x32_bf16 v[30:33], v[192:195], v[168:171], v[30:33]
	v_mfma_f32_16x16x32_bf16 v[26:29], v[200:203], v[168:171], v[26:29]
	v_mfma_f32_16x16x32_bf16 v[14:17], v[192:195], v[176:179], v[14:17]
	v_mfma_f32_16x16x32_bf16 v[10:13], v[200:203], v[176:179], v[10:13]
	v_mfma_f32_16x16x32_bf16 v[6:9], v[192:195], v[184:187], v[6:9]
	v_mfma_f32_16x16x32_bf16 v[2:5], v[200:203], v[184:187], v[2:5]
	v_mfma_f32_16x16x32_bf16 v[46:49], v[196:199], v[164:167], v[46:49]
	v_mfma_f32_16x16x32_bf16 v[42:45], v[204:207], v[164:167], v[42:45]
	v_mfma_f32_16x16x32_bf16 v[30:33], v[196:199], v[172:175], v[30:33]
	v_mfma_f32_16x16x32_bf16 v[26:29], v[204:207], v[172:175], v[26:29]
	v_mfma_f32_16x16x32_bf16 v[14:17], v[196:199], v[180:183], v[14:17]
	v_mfma_f32_16x16x32_bf16 v[10:13], v[204:207], v[180:183], v[10:13]
	v_mfma_f32_16x16x32_bf16 v[6:9], v[196:199], v[188:191], v[6:9]
	v_mfma_f32_16x16x32_bf16 v[2:5], v[204:207], v[188:191], v[2:5]
	s_setprio 0
	s_barrier
	s_add_u32 s38, s58, 0x80000
	s_addc_u32 s39, s59, 0
	s_mov_b32 m0, s66
	v_lshl_add_u64 v[192:193], s[38:39], 0, v[0:1]
	global_load_lds_dwordx4 v[192:193], off
	v_lshl_add_u64 v[192:193], s[38:39], 0, v[130:131]
	s_mov_b32 m0, s67
	s_nop 0
	global_load_lds_dwordx4 v[192:193], off
	s_add_i32 s52, 0, 0x18000
	v_add_u32_e32 v152, s52, v137
	ds_read_b128 v[140:143], v152
	ds_read_b128 v[144:147], v152 offset:1024
	ds_read_b128 v[148:151], v152 offset:2048
	ds_read_b128 v[152:155], v152 offset:3072
	ds_read_b128 v[160:163], v139 offset:32768
	ds_read_b128 v[164:167], v139 offset:33792
	ds_read_b128 v[168:171], v139 offset:34816
	ds_read_b128 v[172:175], v139 offset:35840
	ds_read_b128 v[176:179], v139 offset:36864
	ds_read_b128 v[180:183], v139 offset:37888
	ds_read_b128 v[184:187], v139 offset:38912
	ds_read_b128 v[188:191], v139 offset:39936
	s_add_i32 s53, 0, 0x1c000
	v_add_u32_e32 v204, s53, v137
	ds_read_b128 v[192:195], v204
	ds_read_b128 v[196:199], v204 offset:1024
	ds_read_b128 v[200:203], v204 offset:2048
	ds_read_b128 v[204:207], v204 offset:3072
	s_waitcnt lgkmcnt(4)
	s_barrier
	s_waitcnt lgkmcnt(0)
	s_setprio 1
	v_mfma_f32_16x16x32_bf16 v[126:129], v[140:143], v[160:163], v[126:129]
	v_mfma_f32_16x16x32_bf16 v[122:125], v[148:151], v[160:163], v[122:125]
	v_mfma_f32_16x16x32_bf16 v[118:121], v[140:143], v[168:171], v[118:121]
	v_mfma_f32_16x16x32_bf16 v[114:117], v[148:151], v[168:171], v[114:117]
	v_mfma_f32_16x16x32_bf16 v[106:109], v[140:143], v[176:179], v[106:109]
	v_mfma_f32_16x16x32_bf16 v[98:101], v[148:151], v[176:179], v[98:101]
	v_mfma_f32_16x16x32_bf16 v[90:93], v[140:143], v[184:187], v[90:93]
	v_mfma_f32_16x16x32_bf16 v[82:85], v[148:151], v[184:187], v[82:85]
	v_mfma_f32_16x16x32_bf16 v[126:129], v[144:147], v[164:167], v[126:129]
	v_mfma_f32_16x16x32_bf16 v[122:125], v[152:155], v[164:167], v[122:125]
	v_mfma_f32_16x16x32_bf16 v[118:121], v[144:147], v[172:175], v[118:121]
	v_mfma_f32_16x16x32_bf16 v[114:117], v[152:155], v[172:175], v[114:117]
	v_mfma_f32_16x16x32_bf16 v[106:109], v[144:147], v[180:183], v[106:109]
	v_mfma_f32_16x16x32_bf16 v[98:101], v[152:155], v[180:183], v[98:101]
	v_mfma_f32_16x16x32_bf16 v[90:93], v[144:147], v[188:191], v[90:93]
	v_mfma_f32_16x16x32_bf16 v[82:85], v[152:155], v[188:191], v[82:85]
	v_mfma_f32_16x16x32_bf16 v[110:113], v[192:195], v[160:163], v[110:113]
	v_mfma_f32_16x16x32_bf16 v[102:105], v[200:203], v[160:163], v[102:105]
	v_mfma_f32_16x16x32_bf16 v[94:97], v[192:195], v[168:171], v[94:97]
	v_mfma_f32_16x16x32_bf16 v[86:89], v[200:203], v[168:171], v[86:89]
	v_mfma_f32_16x16x32_bf16 v[78:81], v[192:195], v[176:179], v[78:81]
	v_mfma_f32_16x16x32_bf16 v[74:77], v[200:203], v[176:179], v[74:77]
	v_mfma_f32_16x16x32_bf16 v[70:73], v[192:195], v[184:187], v[70:73]
	v_mfma_f32_16x16x32_bf16 v[66:69], v[200:203], v[184:187], v[66:69]
	v_mfma_f32_16x16x32_bf16 v[110:113], v[196:199], v[164:167], v[110:113]
	v_mfma_f32_16x16x32_bf16 v[102:105], v[204:207], v[164:167], v[102:105]
	v_mfma_f32_16x16x32_bf16 v[94:97], v[196:199], v[172:175], v[94:97]
	v_mfma_f32_16x16x32_bf16 v[86:89], v[204:207], v[172:175], v[86:89]
	v_mfma_f32_16x16x32_bf16 v[78:81], v[196:199], v[180:183], v[78:81]
	v_mfma_f32_16x16x32_bf16 v[74:77], v[204:207], v[180:183], v[74:77]
	v_mfma_f32_16x16x32_bf16 v[70:73], v[196:199], v[188:191], v[70:73]
	v_mfma_f32_16x16x32_bf16 v[66:69], v[204:207], v[188:191], v[66:69]
	s_setprio 0
	s_barrier
; #define PG8_STAGE(bufoff, gbase, voff) do { _Pragma("unroll") for (int _i = 0; _i < 2; ++_i) \
;         __builtin_amdgcn_global_load_lds((const unsigned*)((const char*)(gbase) + (voff)[_i]), (LAS unsigned*)(lds + (bufoff) + ldsw + _i * 8192), 16, 0, 0); } while (0)
; #define PG8_LDA(dst, b, h) do { _Pragma("unroll") for (int m = 0; m < 4; ++m) _Pragma("unroll") for (int k = 0; k < 2; ++k) dst[m][k] = *(const LAS bf16x8*)(lds + PG8_SA(b, h) + aoff + m * 2048 + k * 1024); } while (0)
; #define PG8_LDB(dst, b, h) do { _Pragma("unroll") for (int n = 0; n < 2; ++n) _Pragma("unroll") for (int k = 0; k < 2; ++k) dst[n][k] = *(const LAS bf16x8*)(lds + PG8_SB(b, h) + boff + n * 2048 + k * 1024); } while (0)
; #define PG8_MMA(ai, bj, At, Bt) do { __builtin_amdgcn_s_setprio(1); _Pragma("unroll") for (int m = 0; m < 4; ++m) _Pragma("unroll") for (int n = 0; n < 2; ++n) _Pragma("unroll") for (int k = 0; k < 2; ++k) \
;         acc[ai][bj][m][n] = __builtin_amdgcn_mfma_f32_16x16x32_bf16(Bt[n][k], At[m][k], acc[ai][bj][m][n], 0, 0, 0); __builtin_amdgcn_s_setprio(0); } while (0)
; #define PG8_WAIT_V(n) asm volatile("s_waitcnt vmcnt(" #n ")" ::: "memory")
; #define PG8_WAIT_L(n) asm volatile("s_waitcnt lgkmcnt(" #n ")" ::: "memory")
; #define PG8_BAR __builtin_amdgcn_s_barrier()
; #define PG8_SCHED __builtin_amdgcn_sched_barrier(0)
; template <class Epi, class Sched>
; __device__ __forceinline__ void gemm_phase(LAS unsigned char* lds, const Gemm g, const Sched& S, const Epi& E) {
;     ...
;             PG8_LDB(B1, 1, 1); PG8_STAGE(PG8_SB(1, 0), b3, voffB);
;             PG8_BAR; PG8_WAIT_L(0); PG8_MMA(0, 1, At, B1); PG8_BAR;
;             PG8_LDA(At, 1, 1); PG8_STAGE(PG8_SA(1, 0), a3, voffA);
;             PG8_BAR; PG8_WAIT_L(0); PG8_MMA(1, 0, At, B0); PG8_BAR; PG8_SCHED;
;             PG8_STAGE(PG8_SB(1, 1), b3 + hstep, voffB);
;             PG8_WAIT_V(6); PG8_BAR; PG8_MMA(1, 1, At, B1); PG8_BAR;
;         }
	s_add_i32 s38, s52, s65
	v_lshl_add_u64 v[156:157], v[156:157], 0, s[36:37]
	s_mov_b32 m0, s38
	s_nop 0
	global_load_lds_dwordx4 v[156:157], off
	v_lshl_add_u64 v[156:157], v[210:211], 0, s[36:37]
	s_add_i32 m0, s38, 0x2000
	s_nop 0
	global_load_lds_dwordx4 v[156:157], off
	s_mov_b32 m0, s68
	v_lshl_add_u64 v[156:157], v[212:213], 0, s[36:37]
	global_load_lds_dwordx4 v[156:157], off
	v_lshl_add_u64 v[156:157], v[214:215], 0, s[36:37]
	s_mov_b32 m0, s69
	s_nop 0
	global_load_lds_dwordx4 v[156:157], off
	ds_read_b128 v[160:163], v139 offset:49152
	ds_read_b128 v[164:167], v139 offset:50176
	ds_read_b128 v[168:171], v139 offset:51200
	ds_read_b128 v[172:175], v139 offset:52224
	ds_read_b128 v[176:179], v139 offset:53248
	ds_read_b128 v[180:183], v139 offset:54272
	ds_read_b128 v[184:187], v139 offset:55296
	ds_read_b128 v[188:191], v139 offset:56320
	s_waitcnt vmcnt(4)
	s_waitcnt lgkmcnt(0)
	s_barrier
	s_setprio 1
	v_mfma_f32_16x16x32_bf16 v[62:65], v[140:143], v[160:163], v[62:65]
	v_mfma_f32_16x16x32_bf16 v[58:61], v[148:151], v[160:163], v[58:61]
	v_mfma_f32_16x16x32_bf16 v[54:57], v[140:143], v[168:171], v[54:57]
	v_mfma_f32_16x16x32_bf16 v[50:53], v[148:151], v[168:171], v[50:53]
	v_mfma_f32_16x16x32_bf16 v[38:41], v[140:143], v[176:179], v[38:41]
	v_mfma_f32_16x16x32_bf16 v[34:37], v[148:151], v[176:179], v[34:37]
	v_mfma_f32_16x16x32_bf16 v[22:25], v[140:143], v[184:187], v[22:25]
	v_mfma_f32_16x16x32_bf16 v[18:21], v[148:151], v[184:187], v[18:21]
	v_mfma_f32_16x16x32_bf16 v[62:65], v[144:147], v[164:167], v[62:65]
	v_mfma_f32_16x16x32_bf16 v[58:61], v[152:155], v[164:167], v[58:61]
	v_mfma_f32_16x16x32_bf16 v[54:57], v[144:147], v[172:175], v[54:57]
	v_mfma_f32_16x16x32_bf16 v[50:53], v[152:155], v[172:175], v[50:53]
	v_mfma_f32_16x16x32_bf16 v[38:41], v[144:147], v[180:183], v[38:41]
	v_mfma_f32_16x16x32_bf16 v[34:37], v[152:155], v[180:183], v[34:37]
	v_mfma_f32_16x16x32_bf16 v[22:25], v[144:147], v[188:191], v[22:25]
	v_mfma_f32_16x16x32_bf16 v[18:21], v[152:155], v[188:191], v[18:21]
	s_add_u32 s38, s56, 0x80080
	s_addc_u32 s39, s57, 0
	s_add_i32 s52, s53, s65
	v_lshl_add_u64 v[140:141], s[38:39], 0, v[0:1]
	s_mov_b32 m0, s52
	s_nop 0
	global_load_lds_dwordx4 v[140:141], off
	v_lshl_add_u64 v[140:141], s[38:39], 0, v[130:131]
	s_add_i32 m0, s52, 0x2000
	s_nop 0
	global_load_lds_dwordx4 v[140:141], off
	v_mfma_f32_16x16x32_bf16 v[46:49], v[192:195], v[160:163], v[46:49]
	v_mfma_f32_16x16x32_bf16 v[42:45], v[200:203], v[160:163], v[42:45]
	v_mfma_f32_16x16x32_bf16 v[30:33], v[192:195], v[168:171], v[30:33]
	v_mfma_f32_16x16x32_bf16 v[26:29], v[200:203], v[168:171], v[26:29]
	v_mfma_f32_16x16x32_bf16 v[14:17], v[192:195], v[176:179], v[14:17]
	v_mfma_f32_16x16x32_bf16 v[10:13], v[200:203], v[176:179], v[10:13]
	v_mfma_f32_16x16x32_bf16 v[6:9], v[192:195], v[184:187], v[6:9]
	v_mfma_f32_16x16x32_bf16 v[2:5], v[200:203], v[184:187], v[2:5]
	v_mfma_f32_16x16x32_bf16 v[46:49], v[196:199], v[164:167], v[46:49]
	v_mfma_f32_16x16x32_bf16 v[42:45], v[204:207], v[164:167], v[42:45]
	v_mfma_f32_16x16x32_bf16 v[30:33], v[196:199], v[172:175], v[30:33]
	v_mfma_f32_16x16x32_bf16 v[26:29], v[204:207], v[172:175], v[26:29]
	v_mfma_f32_16x16x32_bf16 v[14:17], v[196:199], v[180:183], v[14:17]
	v_mfma_f32_16x16x32_bf16 v[10:13], v[204:207], v[180:183], v[10:13]
	v_mfma_f32_16x16x32_bf16 v[6:9], v[196:199], v[188:191], v[6:9]
	v_mfma_f32_16x16x32_bf16 v[2:5], v[204:207], v[188:191], v[2:5]
	s_setprio 0
	s_add_i32 s73, s73, 2
	s_add_u32 s71, s71, 0x100
	s_addc_u32 s72, s72, 0
	s_cmp_gt_u32 s73, 5
	s_mov_b64 s[52:53], s[54:55]
	s_barrier
	s_cbranch_scc0 .LBB0_113
;     __device__ __forceinline__ void operator()(const f32x4 (&acc)[2][2][4][2], const Unit& u, int wr, int wc, int fr, int fq) const {
;         const int row0 = u.pm * BM + wr * 64 + fr, col0 = u.pn * BM + wc * 32 + 4 * fq;
;         float* base = part + (size_t)u.ks * Mp * ldc;
; #pragma unroll
;         for (int ai = 0; ai < 2; ++ai)
; #pragma unroll
;             for (int m = 0; m < 4; ++m) { float* rowp = base + (size_t)(row0 + ai * HALF + m * 16) * ldc + col0;
; #pragma unroll
;                 for (int bj = 0; bj < 2; ++bj)
; #pragma unroll
;                     for (int n = 0; n < 2; ++n) *(f32x4*)(rowp + bj * HALF + n * 16) = acc[ai][bj][m][n]; }
;     }
	s_ashr_i32 s11, s10, 31
	s_lshl_b64 s[10:11], s[10:11], 24
	v_lshl_or_b32 v140, s26, 8, v138
	s_add_u32 s10, s8, s10
	v_lshl_add_u32 v142, s24, 8, v136
	s_addc_u32 s11, s9, s11
	v_ashrrev_i32_e32 v141, 31, v140
	v_ashrrev_i32_e32 v143, 31, v142
	v_lshl_add_u64 v[140:141], v[140:141], 2, s[10:11]
	v_lshlrev_b64 v[144:145], 13, v[142:143]
	v_lshl_add_u64 v[144:145], v[140:141], 0, v[144:145]
	global_store_dwordx4 v[144:145], v[126:129], off
	global_store_dwordx4 v[144:145], v[122:125], off offset:64
	global_store_dwordx4 v[144:145], v[110:113], off offset:512
	global_store_dwordx4 v[144:145], v[102:105], off offset:576
	s_mov_b64 s[10:11], 0x100000
	s_mov_b32 s26, s40
	v_or_b32_e32 v102, 16, v142
	v_ashrrev_i32_e32 v103, 31, v102
	v_lshlrev_b64 v[102:103], 13, v[102:103]
	v_lshl_add_u64 v[102:103], v[140:141], 0, v[102:103]
	global_store_dwordx4 v[102:103], v[118:121], off
	global_store_dwordx4 v[102:103], v[114:117], off offset:64
	global_store_dwordx4 v[102:103], v[94:97], off offset:512
	global_store_dwordx4 v[102:103], v[86:89], off offset:576
	s_mov_b32 s24, s44
	s_mov_b64 s[54:55], s[50:51]
	v_or_b32_e32 v86, 32, v142
	v_ashrrev_i32_e32 v87, 31, v86
	v_lshlrev_b64 v[86:87], 13, v[86:87]
	v_lshl_add_u64 v[86:87], v[140:141], 0, v[86:87]
	global_store_dwordx4 v[86:87], v[106:109], off
	global_store_dwordx4 v[86:87], v[98:101], off offset:64
	global_store_dwordx4 v[86:87], v[78:81], off offset:512
	global_store_dwordx4 v[86:87], v[74:77], off offset:576
	s_mov_b64 s[52:53], s[48:49]
	s_nop 0
	v_or_b32_e32 v74, 48, v142
	v_ashrrev_i32_e32 v75, 31, v74
	v_lshlrev_b64 v[74:75], 13, v[74:75]
	v_lshl_add_u64 v[74:75], v[140:141], 0, v[74:75]
	global_store_dwordx4 v[74:75], v[90:93], off
	global_store_dwordx4 v[74:75], v[82:85], off offset:64
	global_store_dwordx4 v[74:75], v[70:73], off offset:512
	global_store_dwordx4 v[74:75], v[66:69], off offset:576
	s_nop 1
	v_add_co_u32_e32 v68, vcc, s93, v144
	v_lshl_add_u64 v[66:67], v[144:145], 0, s[10:11]
	s_nop 0
	v_addc_co_u32_e32 v69, vcc, 0, v145, vcc
	s_mov_b64 s[10:11], 0x120000
	global_store_dwordx4 v[68:69], v[62:65], off
	global_store_dwordx4 v[66:67], v[58:61], off offset:64
	global_store_dwordx4 v[66:67], v[46:49], off offset:512
	global_store_dwordx4 v[66:67], v[42:45], off offset:576
	s_nop 1
	v_lshl_add_u64 v[42:43], v[144:145], 0, s[10:11]
	s_mov_b32 s10, 0x120000
	v_add_co_u32_e32 v44, vcc, s10, v144
	s_mov_b64 s[10:11], 0x140000
	s_nop 0
	v_addc_co_u32_e32 v45, vcc, 0, v145, vcc
	global_store_dwordx4 v[44:45], v[54:57], off
	global_store_dwordx4 v[42:43], v[50:53], off offset:64
	global_store_dwordx4 v[42:43], v[30:33], off offset:512
	global_store_dwordx4 v[42:43], v[26:29], off offset:576
	s_nop 1
	v_lshl_add_u64 v[26:27], v[144:145], 0, s[10:11]
	s_mov_b32 s10, 0x140000
	v_add_co_u32_e32 v28, vcc, s10, v144
	s_mov_b64 s[10:11], 0x160000
	s_nop 0
	v_addc_co_u32_e32 v29, vcc, 0, v145, vcc
	global_store_dwordx4 v[28:29], v[38:41], off
	global_store_dwordx4 v[26:27], v[34:37], off offset:64
	global_store_dwordx4 v[26:27], v[14:17], off offset:512
	global_store_dwordx4 v[26:27], v[10:13], off offset:576
	s_nop 1
	v_add_co_u32_e32 v12, vcc, 0x160000, v144
	v_lshl_add_u64 v[10:11], v[144:145], 0, s[10:11]
	s_nop 0
	v_addc_co_u32_e32 v13, vcc, 0, v145, vcc
	s_and_b64 vcc, exec, s[46:47]
	s_mov_b32 s10, s28
	global_store_dwordx4 v[12:13], v[22:25], off
	global_store_dwordx4 v[10:11], v[18:21], off offset:64
	global_store_dwordx4 v[10:11], v[6:9], off offset:512
	global_store_dwordx4 v[10:11], v[2:5], off offset:576
	s_cbranch_vccz .LBB0_110
	s_waitcnt vmcnt(0)
	s_cmpk_gt_u32 s60, 0xff
	s_cbranch_scc1 .LBB0_117
	s_barrier

; #define PG8_STAGE(bufoff, gbase, voff) do { _Pragma("unroll") for (int _i = 0; _i < 2; ++_i) \
;         __builtin_amdgcn_global_load_lds((const unsigned*)((const char*)(gbase) + (voff)[_i]), (LAS unsigned*)(lds + (bufoff) + ldsw + _i * 8192), 16, 0, 0); } while (0)
; #define PG8_LDA(dst, b, h) do { _Pragma("unroll") for (int m = 0; m < 4; ++m) _Pragma("unroll") for (int k = 0; k < 2; ++k) dst[m][k] = *(const LAS bf16x8*)(lds + PG8_SA(b, h) + aoff + m * 2048 + k * 1024); } while (0)
; #define PG8_LDB(dst, b, h) do { _Pragma("unroll") for (int n = 0; n < 2; ++n) _Pragma("unroll") for (int k = 0; k < 2; ++k) dst[n][k] = *(const LAS bf16x8*)(lds + PG8_SB(b, h) + boff + n * 2048 + k * 1024); } while (0)
; #define PG8_MMA(ai, bj, At, Bt) do { __builtin_amdgcn_s_setprio(1); _Pragma("unroll") for (int m = 0; m < 4; ++m) _Pragma("unroll") for (int n = 0; n < 2; ++n) _Pragma("unroll") for (int k = 0; k < 2; ++k) \
;         acc[ai][bj][m][n] = __builtin_amdgcn_mfma_f32_16x16x32_bf16(Bt[n][k], At[m][k], acc[ai][bj][m][n], 0, 0, 0); __builtin_amdgcn_s_setprio(0); } while (0)
; #define PG8_WAIT_L(n) asm volatile("s_waitcnt lgkmcnt(" #n ")" ::: "memory")
; #define PG8_BAR __builtin_amdgcn_s_barrier()
; #define PG8_SCHED __builtin_amdgcn_sched_barrier(0)
; template <class Epi, class Sched>
; __device__ __forceinline__ void gemm_phase(LAS unsigned char* lds, const Gemm g, const Sched& S, const Epi& E) {
;     ...
;             const bool last = (t == nt - 2);
;             const char* a1 = cA + (size_t)(t + 1) * kstep;
;             const char* a2 = last ? nA : cA + (size_t)(t + 2) * kstep; const char* b2 = last ? nB : cB + (size_t)(t + 2) * kstep;
;             const char* a3 = a2 + kstep; const char* b3 = b2 + kstep;
;             PG8_LDB(B0, 0, 0); PG8_SCHED; PG8_LDA(At, 0, 0); PG8_STAGE(PG8_SA(1, 1), a1 + hstep, voffA);
;             PG8_WAIT_L(8); PG8_BAR; PG8_WAIT_L(0); PG8_MMA(0, 0, At, B0); PG8_BAR; PG8_SCHED;
;             PG8_LDB(B1, 0, 1); PG8_STAGE(PG8_SB(0, 0), b2, voffB);
;             PG8_BAR; PG8_WAIT_L(0); PG8_MMA(0, 1, At, B1); PG8_BAR;
;             PG8_LDA(At, 0, 1); PG8_STAGE(PG8_SA(0, 0), a2, voffA);
;             PG8_BAR; PG8_WAIT_L(0); PG8_MMA(1, 0, At, B0); PG8_BAR; PG8_SCHED;
;             PG8_STAGE(PG8_SB(0, 1), b2 + hstep, voffB);
.LBB0_354:
	s_add_u32 s38, s50, 0xfff80080
	s_addc_u32 s39, s51, -1
	s_cmp_eq_u32 s70, 28
	s_cselect_b32 s55, s9, s39
	s_cselect_b32 s54, s66, s38
	s_cselect_b32 s53, s43, s69
	s_cselect_b32 s52, s67, s68
	v_lshl_add_u64 v[156:157], s[50:51], 0, v[138:139]
	s_add_i32 m0, s29, 0xc000
	s_nop 0
	global_load_lds_dwordx4 v[156:157], off
	v_lshl_add_u64 v[156:157], s[50:51], 0, v[136:137]
	s_add_i32 m0, s29, 0xe000
	s_nop 0
	global_load_lds_dwordx4 v[156:157], off
	s_add_i32 s71, 0, 0x10000
	v_add_u32_e32 v156, s71, v145
	ds_read_b128 v[140:143], v156
	ds_read_b128 v[148:151], v156 offset:1024
	ds_read_b128 v[152:155], v156 offset:2048
	ds_read_b128 v[160:163], v156 offset:3072
	ds_read_b128 v[164:167], v147
	ds_read_b128 v[168:171], v147 offset:1024
	ds_read_b128 v[172:175], v147 offset:2048
	ds_read_b128 v[176:179], v147 offset:3072
	ds_read_b128 v[180:183], v147 offset:4096
	ds_read_b128 v[184:187], v147 offset:5120
	ds_read_b128 v[188:191], v147 offset:6144
	ds_read_b128 v[192:195], v147 offset:7168
	s_add_i32 s38, 0, 0x14000
	v_add_u32_e32 v156, s38, v145
	ds_read_b128 v[196:199], v156
	ds_read_b128 v[200:203], v156 offset:1024
	ds_read_b128 v[204:207], v156 offset:2048
	ds_read_b128 v[210:213], v156 offset:3072
	s_waitcnt lgkmcnt(4)
	s_barrier
	s_waitcnt lgkmcnt(0)
	s_setprio 1
	v_mfma_f32_16x16x32_bf16 v[126:129], v[140:143], v[164:167], v[126:129]
	v_mfma_f32_16x16x32_bf16 v[122:125], v[152:155], v[164:167], v[122:125]
	v_mfma_f32_16x16x32_bf16 v[118:121], v[140:143], v[172:175], v[118:121]
	v_mfma_f32_16x16x32_bf16 v[110:113], v[152:155], v[172:175], v[110:113]
	v_mfma_f32_16x16x32_bf16 v[102:105], v[140:143], v[180:183], v[102:105]
	v_mfma_f32_16x16x32_bf16 v[94:97], v[152:155], v[180:183], v[94:97]
	v_mfma_f32_16x16x32_bf16 v[86:89], v[140:143], v[188:191], v[86:89]
	v_mfma_f32_16x16x32_bf16 v[78:81], v[152:155], v[188:191], v[78:81]
	v_mfma_f32_16x16x32_bf16 v[126:129], v[148:151], v[168:171], v[126:129]
	v_mfma_f32_16x16x32_bf16 v[122:125], v[160:163], v[168:171], v[122:125]
	v_mfma_f32_16x16x32_bf16 v[118:121], v[148:151], v[176:179], v[118:121]
	v_mfma_f32_16x16x32_bf16 v[110:113], v[160:163], v[176:179], v[110:113]
	v_mfma_f32_16x16x32_bf16 v[102:105], v[148:151], v[184:187], v[102:105]
	v_mfma_f32_16x16x32_bf16 v[94:97], v[160:163], v[184:187], v[94:97]
	v_mfma_f32_16x16x32_bf16 v[86:89], v[148:151], v[192:195], v[86:89]
	v_mfma_f32_16x16x32_bf16 v[78:81], v[160:163], v[192:195], v[78:81]
	v_mfma_f32_16x16x32_bf16 v[114:117], v[196:199], v[164:167], v[114:117]
	v_mfma_f32_16x16x32_bf16 v[106:109], v[204:207], v[164:167], v[106:109]
	v_mfma_f32_16x16x32_bf16 v[98:101], v[196:199], v[172:175], v[98:101]
	v_mfma_f32_16x16x32_bf16 v[90:93], v[204:207], v[172:175], v[90:93]
	v_mfma_f32_16x16x32_bf16 v[82:85], v[196:199], v[180:183], v[82:85]
	v_mfma_f32_16x16x32_bf16 v[74:77], v[204:207], v[180:183], v[74:77]
	v_mfma_f32_16x16x32_bf16 v[70:73], v[196:199], v[188:191], v[70:73]
	v_mfma_f32_16x16x32_bf16 v[66:69], v[204:207], v[188:191], v[66:69]
	v_mfma_f32_16x16x32_bf16 v[114:117], v[200:203], v[168:171], v[114:117]
	v_mfma_f32_16x16x32_bf16 v[106:109], v[210:213], v[168:171], v[106:109]
	v_mfma_f32_16x16x32_bf16 v[98:101], v[200:203], v[176:179], v[98:101]
	v_mfma_f32_16x16x32_bf16 v[90:93], v[210:213], v[176:179], v[90:93]
	v_mfma_f32_16x16x32_bf16 v[82:85], v[200:203], v[184:187], v[82:85]
	v_mfma_f32_16x16x32_bf16 v[74:77], v[210:213], v[184:187], v[74:77]
	v_mfma_f32_16x16x32_bf16 v[70:73], v[200:203], v[192:195], v[70:73]
	v_mfma_f32_16x16x32_bf16 v[66:69], v[210:213], v[192:195], v[66:69]
	s_setprio 0
	s_barrier
	s_add_i32 s39, s71, s56
	v_lshl_add_u64 v[156:157], s[52:53], 0, v[0:1]
	s_mov_b32 m0, s39
	v_lshl_add_u64 v[214:215], s[52:53], 0, v[134:135]
	global_load_lds_dwordx4 v[156:157], off
	s_add_i32 m0, s39, 0x2000
	s_nop 0
	global_load_lds_dwordx4 v[214:215], off
	s_mov_b32 m0, s29
	v_lshl_add_u64 v[216:217], s[54:55], 0, v[130:131]
	global_load_lds_dwordx4 v[216:217], off
	v_lshl_add_u64 v[224:225], s[54:55], 0, v[132:133]
	s_mov_b32 m0, s41
	s_nop 0
	global_load_lds_dwordx4 v[224:225], off
	ds_read_b128 v[164:167], v147 offset:16384
	ds_read_b128 v[168:171], v147 offset:17408
	ds_read_b128 v[172:175], v147 offset:18432
	ds_read_b128 v[176:179], v147 offset:19456
	ds_read_b128 v[180:183], v147 offset:20480
	ds_read_b128 v[184:187], v147 offset:21504
	ds_read_b128 v[188:191], v147 offset:22528
	ds_read_b128 v[192:195], v147 offset:23552
	s_waitcnt vmcnt(4)
	s_waitcnt lgkmcnt(0)
	s_barrier
; #define PG8_STAGE(bufoff, gbase, voff) do { _Pragma("unroll") for (int _i = 0; _i < 2; ++_i) \
;         __builtin_amdgcn_global_load_lds((const unsigned*)((const char*)(gbase) + (voff)[_i]), (LAS unsigned*)(lds + (bufoff) + ldsw + _i * 8192), 16, 0, 0); } while (0)
; #define PG8_LDA(dst, b, h) do { _Pragma("unroll") for (int m = 0; m < 4; ++m) _Pragma("unroll") for (int k = 0; k < 2; ++k) dst[m][k] = *(const LAS bf16x8*)(lds + PG8_SA(b, h) + aoff + m * 2048 + k * 1024); } while (0)
; #define PG8_LDB(dst, b, h) do { _Pragma("unroll") for (int n = 0; n < 2; ++n) _Pragma("unroll") for (int k = 0; k < 2; ++k) dst[n][k] = *(const LAS bf16x8*)(lds + PG8_SB(b, h) + boff + n * 2048 + k * 1024); } while (0)
; #define PG8_MMA(ai, bj, At, Bt) do { __builtin_amdgcn_s_setprio(1); _Pragma("unroll") for (int m = 0; m < 4; ++m) _Pragma("unroll") for (int n = 0; n < 2; ++n) _Pragma("unroll") for (int k = 0; k < 2; ++k) \
;         acc[ai][bj][m][n] = __builtin_amdgcn_mfma_f32_16x16x32_bf16(Bt[n][k], At[m][k], acc[ai][bj][m][n], 0, 0, 0); __builtin_amdgcn_s_setprio(0); } while (0)
; #define PG8_WAIT_V(n) asm volatile("s_waitcnt vmcnt(" #n ")" ::: "memory")
; #define PG8_WAIT_L(n) asm volatile("s_waitcnt lgkmcnt(" #n ")" ::: "memory")
; #define PG8_BAR __builtin_amdgcn_s_barrier()
; #define PG8_SCHED __builtin_amdgcn_sched_barrier(0)
; template <class Epi, class Sched>
; __device__ __forceinline__ void gemm_phase(LAS unsigned char* lds, const Gemm g, const Sched& S, const Epi& E) {
;     ...
;             PG8_BAR; PG8_WAIT_L(0); PG8_MMA(0, 1, At, B1); PG8_BAR;
;             PG8_LDA(At, 0, 1); PG8_STAGE(PG8_SA(0, 0), a2, voffA);
;             PG8_BAR; PG8_WAIT_L(0); PG8_MMA(1, 0, At, B0); PG8_BAR; PG8_SCHED;
;             PG8_STAGE(PG8_SB(0, 1), b2 + hstep, voffB);
;             PG8_WAIT_V(6); PG8_BAR; PG8_MMA(1, 1, At, B1); PG8_BAR;
;             PG8_LDB(B0, 1, 0); PG8_SCHED; PG8_LDA(At, 1, 0); PG8_STAGE(PG8_SA(0, 1), a2 + hstep, voffA);
;             PG8_WAIT_L(8); PG8_BAR; PG8_WAIT_L(0); PG8_MMA(0, 0, At, B0); PG8_BAR; PG8_SCHED;
;             PG8_LDB(B1, 1, 1); PG8_STAGE(PG8_SB(1, 0), b3, voffB);
;             PG8_BAR; PG8_WAIT_L(0); PG8_MMA(0, 1, At, B1); PG8_BAR;
	s_setprio 1
	v_mfma_f32_16x16x32_bf16 v[62:65], v[140:143], v[164:167], v[62:65]
	v_mfma_f32_16x16x32_bf16 v[58:61], v[152:155], v[164:167], v[58:61]
	v_mfma_f32_16x16x32_bf16 v[54:57], v[140:143], v[172:175], v[54:57]
	v_mfma_f32_16x16x32_bf16 v[46:49], v[152:155], v[172:175], v[46:49]
	v_mfma_f32_16x16x32_bf16 v[38:41], v[140:143], v[180:183], v[38:41]
	v_mfma_f32_16x16x32_bf16 v[30:33], v[152:155], v[180:183], v[30:33]
	v_mfma_f32_16x16x32_bf16 v[22:25], v[140:143], v[188:191], v[22:25]
	v_mfma_f32_16x16x32_bf16 v[14:17], v[152:155], v[188:191], v[14:17]
	v_mfma_f32_16x16x32_bf16 v[62:65], v[148:151], v[168:171], v[62:65]
	v_mfma_f32_16x16x32_bf16 v[58:61], v[160:163], v[168:171], v[58:61]
	v_mfma_f32_16x16x32_bf16 v[54:57], v[148:151], v[176:179], v[54:57]
	v_mfma_f32_16x16x32_bf16 v[46:49], v[160:163], v[176:179], v[46:49]
	v_mfma_f32_16x16x32_bf16 v[38:41], v[148:151], v[184:187], v[38:41]
	v_mfma_f32_16x16x32_bf16 v[30:33], v[160:163], v[184:187], v[30:33]
	v_mfma_f32_16x16x32_bf16 v[22:25], v[148:151], v[192:195], v[22:25]
	v_mfma_f32_16x16x32_bf16 v[14:17], v[160:163], v[192:195], v[14:17]
	s_add_u32 s72, s52, 0x80000
	s_addc_u32 s73, s53, 0
	s_add_i32 s38, s38, s56
	v_lshl_add_u64 v[140:141], s[72:73], 0, v[0:1]
	s_mov_b32 m0, s38
	s_nop 0
	global_load_lds_dwordx4 v[140:141], off
	v_lshl_add_u64 v[140:141], s[72:73], 0, v[134:135]
	s_add_i32 m0, s38, 0x2000
	s_nop 0
	global_load_lds_dwordx4 v[140:141], off
	v_mfma_f32_16x16x32_bf16 v[50:53], v[196:199], v[164:167], v[50:53]
	v_mfma_f32_16x16x32_bf16 v[42:45], v[204:207], v[164:167], v[42:45]
	v_mfma_f32_16x16x32_bf16 v[34:37], v[196:199], v[172:175], v[34:37]
	v_mfma_f32_16x16x32_bf16 v[26:29], v[204:207], v[172:175], v[26:29]
	v_mfma_f32_16x16x32_bf16 v[18:21], v[196:199], v[180:183], v[18:21]
	v_mfma_f32_16x16x32_bf16 v[10:13], v[204:207], v[180:183], v[10:13]
	v_mfma_f32_16x16x32_bf16 v[6:9], v[196:199], v[188:191], v[6:9]
	v_mfma_f32_16x16x32_bf16 v[2:5], v[204:207], v[188:191], v[2:5]
	v_mfma_f32_16x16x32_bf16 v[50:53], v[200:203], v[168:171], v[50:53]
	v_mfma_f32_16x16x32_bf16 v[42:45], v[210:213], v[168:171], v[42:45]
	v_mfma_f32_16x16x32_bf16 v[34:37], v[200:203], v[176:179], v[34:37]
	v_mfma_f32_16x16x32_bf16 v[26:29], v[210:213], v[176:179], v[26:29]
	v_mfma_f32_16x16x32_bf16 v[18:21], v[200:203], v[184:187], v[18:21]
	v_mfma_f32_16x16x32_bf16 v[10:13], v[210:213], v[184:187], v[10:13]
	v_mfma_f32_16x16x32_bf16 v[6:9], v[200:203], v[192:195], v[6:9]
	v_mfma_f32_16x16x32_bf16 v[2:5], v[210:213], v[192:195], v[2:5]
	s_setprio 0
	s_barrier
	s_add_u32 s54, s54, 0x80000
	s_addc_u32 s55, s55, 0
	s_mov_b32 m0, s57
	v_lshl_add_u64 v[196:197], s[54:55], 0, v[130:131]
	global_load_lds_dwordx4 v[196:197], off
	v_lshl_add_u64 v[196:197], s[54:55], 0, v[132:133]
	s_mov_b32 m0, s58
	s_nop 0
	global_load_lds_dwordx4 v[196:197], off
	s_add_i32 s38, 0, 0x18000
	v_add_u32_e32 v160, s38, v145
	ds_read_b128 v[140:143], v160
	ds_read_b128 v[148:151], v160 offset:1024
	ds_read_b128 v[152:155], v160 offset:2048
	ds_read_b128 v[160:163], v160 offset:3072
	ds_read_b128 v[164:167], v147 offset:32768
	ds_read_b128 v[168:171], v147 offset:33792
	ds_read_b128 v[172:175], v147 offset:34816
	ds_read_b128 v[176:179], v147 offset:35840
	ds_read_b128 v[180:183], v147 offset:36864
	ds_read_b128 v[184:187], v147 offset:37888
	ds_read_b128 v[188:191], v147 offset:38912
	ds_read_b128 v[192:195], v147 offset:39936
	s_add_i32 s39, 0, 0x1c000
	v_add_u32_e32 v210, s39, v145
	ds_read_b128 v[196:199], v210
	ds_read_b128 v[200:203], v210 offset:1024
	ds_read_b128 v[204:207], v210 offset:2048
	ds_read_b128 v[210:213], v210 offset:3072
	s_waitcnt lgkmcnt(4)
	s_barrier
	s_waitcnt lgkmcnt(0)
	s_setprio 1
	v_mfma_f32_16x16x32_bf16 v[126:129], v[140:143], v[164:167], v[126:129]
	v_mfma_f32_16x16x32_bf16 v[122:125], v[152:155], v[164:167], v[122:125]
	v_mfma_f32_16x16x32_bf16 v[118:121], v[140:143], v[172:175], v[118:121]
	v_mfma_f32_16x16x32_bf16 v[110:113], v[152:155], v[172:175], v[110:113]
	v_mfma_f32_16x16x32_bf16 v[102:105], v[140:143], v[180:183], v[102:105]
	v_mfma_f32_16x16x32_bf16 v[94:97], v[152:155], v[180:183], v[94:97]
	v_mfma_f32_16x16x32_bf16 v[86:89], v[140:143], v[188:191], v[86:89]
	v_mfma_f32_16x16x32_bf16 v[78:81], v[152:155], v[188:191], v[78:81]
	v_mfma_f32_16x16x32_bf16 v[126:129], v[148:151], v[168:171], v[126:129]
	v_mfma_f32_16x16x32_bf16 v[122:125], v[160:163], v[168:171], v[122:125]
	v_mfma_f32_16x16x32_bf16 v[118:121], v[148:151], v[176:179], v[118:121]
	v_mfma_f32_16x16x32_bf16 v[110:113], v[160:163], v[176:179], v[110:113]
	v_mfma_f32_16x16x32_bf16 v[102:105], v[148:151], v[184:187], v[102:105]
	v_mfma_f32_16x16x32_bf16 v[94:97], v[160:163], v[184:187], v[94:97]
	v_mfma_f32_16x16x32_bf16 v[86:89], v[148:151], v[192:195], v[86:89]
	v_mfma_f32_16x16x32_bf16 v[78:81], v[160:163], v[192:195], v[78:81]
	v_mfma_f32_16x16x32_bf16 v[114:117], v[196:199], v[164:167], v[114:117]
	v_mfma_f32_16x16x32_bf16 v[106:109], v[204:207], v[164:167], v[106:109]
	v_mfma_f32_16x16x32_bf16 v[98:101], v[196:199], v[172:175], v[98:101]
	v_mfma_f32_16x16x32_bf16 v[90:93], v[204:207], v[172:175], v[90:93]
	v_mfma_f32_16x16x32_bf16 v[82:85], v[196:199], v[180:183], v[82:85]
	v_mfma_f32_16x16x32_bf16 v[74:77], v[204:207], v[180:183], v[74:77]
	v_mfma_f32_16x16x32_bf16 v[70:73], v[196:199], v[188:191], v[70:73]
	v_mfma_f32_16x16x32_bf16 v[66:69], v[204:207], v[188:191], v[66:69]
	v_mfma_f32_16x16x32_bf16 v[114:117], v[200:203], v[168:171], v[114:117]
	v_mfma_f32_16x16x32_bf16 v[106:109], v[210:213], v[168:171], v[106:109]
	v_mfma_f32_16x16x32_bf16 v[98:101], v[200:203], v[176:179], v[98:101]
	v_mfma_f32_16x16x32_bf16 v[90:93], v[210:213], v[176:179], v[90:93]
	v_mfma_f32_16x16x32_bf16 v[82:85], v[200:203], v[184:187], v[82:85]
	v_mfma_f32_16x16x32_bf16 v[74:77], v[210:213], v[184:187], v[74:77]
	v_mfma_f32_16x16x32_bf16 v[70:73], v[200:203], v[192:195], v[70:73]
	v_mfma_f32_16x16x32_bf16 v[66:69], v[210:213], v[192:195], v[66:69]
	s_setprio 0
	s_barrier
; #define PG8_STAGE(bufoff, gbase, voff) do { _Pragma("unroll") for (int _i = 0; _i < 2; ++_i) \
;         __builtin_amdgcn_global_load_lds((const unsigned*)((const char*)(gbase) + (voff)[_i]), (LAS unsigned*)(lds + (bufoff) + ldsw + _i * 8192), 16, 0, 0); } while (0)
; #define PG8_LDA(dst, b, h) do { _Pragma("unroll") for (int m = 0; m < 4; ++m) _Pragma("unroll") for (int k = 0; k < 2; ++k) dst[m][k] = *(const LAS bf16x8*)(lds + PG8_SA(b, h) + aoff + m * 2048 + k * 1024); } while (0)
; #define PG8_LDB(dst, b, h) do { _Pragma("unroll") for (int n = 0; n < 2; ++n) _Pragma("unroll") for (int k = 0; k < 2; ++k) dst[n][k] = *(const LAS bf16x8*)(lds + PG8_SB(b, h) + boff + n * 2048 + k * 1024); } while (0)
; #define PG8_MMA(ai, bj, At, Bt) do { __builtin_amdgcn_s_setprio(1); _Pragma("unroll") for (int m = 0; m < 4; ++m) _Pragma("unroll") for (int n = 0; n < 2; ++n) _Pragma("unroll") for (int k = 0; k < 2; ++k) \
;         acc[ai][bj][m][n] = __builtin_amdgcn_mfma_f32_16x16x32_bf16(Bt[n][k], At[m][k], acc[ai][bj][m][n], 0, 0, 0); __builtin_amdgcn_s_setprio(0); } while (0)
; #define PG8_WAIT_V(n) asm volatile("s_waitcnt vmcnt(" #n ")" ::: "memory")
; #define PG8_WAIT_L(n) asm volatile("s_waitcnt lgkmcnt(" #n ")" ::: "memory")
; #define PG8_BAR __builtin_amdgcn_s_barrier()
; #define PG8_SCHED __builtin_amdgcn_sched_barrier(0)
; template <class Epi, class Sched>
; __device__ __forceinline__ void gemm_phase(LAS unsigned char* lds, const Gemm g, const Sched& S, const Epi& E) {
;     ...
;             PG8_LDB(B1, 1, 1); PG8_STAGE(PG8_SB(1, 0), b3, voffB);
;             PG8_BAR; PG8_WAIT_L(0); PG8_MMA(0, 1, At, B1); PG8_BAR;
;             PG8_LDA(At, 1, 1); PG8_STAGE(PG8_SA(1, 0), a3, voffA);
;             PG8_BAR; PG8_WAIT_L(0); PG8_MMA(1, 0, At, B0); PG8_BAR; PG8_SCHED;
;             PG8_STAGE(PG8_SB(1, 1), b3 + hstep, voffB);
;             PG8_WAIT_V(6); PG8_BAR; PG8_MMA(1, 1, At, B1); PG8_BAR;
;         }
	s_add_i32 s38, s38, s56
	v_lshl_add_u64 v[156:157], v[156:157], 0, s[36:37]
	s_mov_b32 m0, s38
	s_nop 0
	global_load_lds_dwordx4 v[156:157], off
	v_lshl_add_u64 v[156:157], v[214:215], 0, s[36:37]
	s_add_i32 m0, s38, 0x2000
	s_nop 0
	global_load_lds_dwordx4 v[156:157], off
	s_mov_b32 m0, s59
	v_lshl_add_u64 v[156:157], v[216:217], 0, s[36:37]
	global_load_lds_dwordx4 v[156:157], off
	v_lshl_add_u64 v[156:157], v[224:225], 0, s[36:37]
	s_mov_b32 m0, s60
	s_nop 0
	global_load_lds_dwordx4 v[156:157], off
	ds_read_b128 v[164:167], v147 offset:49152
	ds_read_b128 v[168:171], v147 offset:50176
	ds_read_b128 v[172:175], v147 offset:51200
	ds_read_b128 v[176:179], v147 offset:52224
	ds_read_b128 v[180:183], v147 offset:53248
	ds_read_b128 v[184:187], v147 offset:54272
	ds_read_b128 v[188:191], v147 offset:55296
	ds_read_b128 v[192:195], v147 offset:56320
	s_waitcnt vmcnt(4)
	s_waitcnt lgkmcnt(0)
	s_barrier
	s_setprio 1
	v_mfma_f32_16x16x32_bf16 v[62:65], v[140:143], v[164:167], v[62:65]
	v_mfma_f32_16x16x32_bf16 v[58:61], v[152:155], v[164:167], v[58:61]
	v_mfma_f32_16x16x32_bf16 v[54:57], v[140:143], v[172:175], v[54:57]
	v_mfma_f32_16x16x32_bf16 v[46:49], v[152:155], v[172:175], v[46:49]
	v_mfma_f32_16x16x32_bf16 v[38:41], v[140:143], v[180:183], v[38:41]
	v_mfma_f32_16x16x32_bf16 v[30:33], v[152:155], v[180:183], v[30:33]
	v_mfma_f32_16x16x32_bf16 v[22:25], v[140:143], v[188:191], v[22:25]
	v_mfma_f32_16x16x32_bf16 v[14:17], v[152:155], v[188:191], v[14:17]
	v_mfma_f32_16x16x32_bf16 v[62:65], v[148:151], v[168:171], v[62:65]
	v_mfma_f32_16x16x32_bf16 v[58:61], v[160:163], v[168:171], v[58:61]
	v_mfma_f32_16x16x32_bf16 v[54:57], v[148:151], v[176:179], v[54:57]
	v_mfma_f32_16x16x32_bf16 v[46:49], v[160:163], v[176:179], v[46:49]
	v_mfma_f32_16x16x32_bf16 v[38:41], v[148:151], v[184:187], v[38:41]
	v_mfma_f32_16x16x32_bf16 v[30:33], v[160:163], v[184:187], v[30:33]
	v_mfma_f32_16x16x32_bf16 v[22:25], v[148:151], v[192:195], v[22:25]
	v_mfma_f32_16x16x32_bf16 v[14:17], v[160:163], v[192:195], v[14:17]
	s_add_u32 s52, s52, 0x80080
	s_addc_u32 s53, s53, 0
	s_add_i32 s38, s39, s56
	v_lshl_add_u64 v[140:141], s[52:53], 0, v[0:1]
	s_mov_b32 m0, s38
	s_nop 0
	global_load_lds_dwordx4 v[140:141], off
	v_lshl_add_u64 v[140:141], s[52:53], 0, v[134:135]
	s_add_i32 m0, s38, 0x2000
	s_nop 0
	global_load_lds_dwordx4 v[140:141], off
	v_mfma_f32_16x16x32_bf16 v[50:53], v[196:199], v[164:167], v[50:53]
	v_mfma_f32_16x16x32_bf16 v[42:45], v[204:207], v[164:167], v[42:45]
	v_mfma_f32_16x16x32_bf16 v[34:37], v[196:199], v[172:175], v[34:37]
	v_mfma_f32_16x16x32_bf16 v[26:29], v[204:207], v[172:175], v[26:29]
	v_mfma_f32_16x16x32_bf16 v[18:21], v[196:199], v[180:183], v[18:21]
	v_mfma_f32_16x16x32_bf16 v[10:13], v[204:207], v[180:183], v[10:13]
	v_mfma_f32_16x16x32_bf16 v[6:9], v[196:199], v[188:191], v[6:9]
	v_mfma_f32_16x16x32_bf16 v[2:5], v[204:207], v[188:191], v[2:5]
	v_mfma_f32_16x16x32_bf16 v[50:53], v[200:203], v[168:171], v[50:53]
	v_mfma_f32_16x16x32_bf16 v[42:45], v[210:213], v[168:171], v[42:45]
	v_mfma_f32_16x16x32_bf16 v[34:37], v[200:203], v[176:179], v[34:37]
	v_mfma_f32_16x16x32_bf16 v[26:29], v[210:213], v[176:179], v[26:29]
	v_mfma_f32_16x16x32_bf16 v[18:21], v[200:203], v[184:187], v[18:21]
	v_mfma_f32_16x16x32_bf16 v[10:13], v[210:213], v[184:187], v[10:13]
	v_mfma_f32_16x16x32_bf16 v[6:9], v[200:203], v[192:195], v[6:9]
	v_mfma_f32_16x16x32_bf16 v[2:5], v[210:213], v[192:195], v[2:5]
	s_setprio 0
	s_add_i32 s70, s70, 2
	s_add_u32 s68, s68, 0x100
	s_addc_u32 s69, s69, 0
	s_add_u32 s50, s50, 0x100
	s_addc_u32 s51, s51, 0
	s_cmp_gt_u32 s70, 29
	s_barrier
	s_cbranch_scc0 .LBB0_354
; __device__ __forceinline__ unsigned cvt_pk_bf16(float lo, float hi) { unsigned r; asm("v_cvt_pk_bf16_f32 %0, %1, %2" : "=v"(r) : "v"(lo), "v"(hi)); return r; }
;     __device__ __forceinline__ void operator()(const f32x4 (&acc)[2][2][4][2], const Unit& u, int wr, int wc, int fr, int fq) const {
;         const int row0 = u.pm * BM + wr * 64 + fr, col0 = u.pn * BM + wc * 32 + 8 * fq;
; #pragma unroll
;         for (int ai = 0; ai < 2; ++ai)
; #pragma unroll
;             for (int m = 0; m < 4; ++m) { bf16_t* rowp = O + (size_t)(row0 + ai * HALF + m * 16) * ldc + col0;
; #pragma unroll
;                 for (int bj = 0; bj < 2; ++bj) { f32x4 v0 = acc[ai][bj][m][0], v1 = acc[ai][bj][m][1];
;                     if (ACT == 1) {
; #pragma unroll
;                         for (int j = 0; j < 4; ++j) { float a = fmaxf(v0[j], 0.f), b = fmaxf(v1[j], 0.f); v0[j] = a * a; v1[j] = b * b; } }
;                     u32x4 w; w.x = cvt_pk_bf16(v0[0], v0[1]); w.y = cvt_pk_bf16(v0[2], v0[3]); w.z = cvt_pk_bf16(v1[0], v1[1]); w.w = cvt_pk_bf16(v1[2], v1[3]);
;                     if (ACT == 1) __builtin_nontemporal_store(w, (u32x4*)(rowp + bj * HALF));
;                     else *(u32x4*)(rowp + bj * HALF) = w; } }
	s_load_dwordx2 s[50:51], s[0:1], 0xc0
	v_lshl_add_u32 v150, s28, 8, v144
	v_lshl_or_b32 v142, s40, 8, v146
	v_ashrrev_i32_e32 v143, 31, v142
	v_cvt_pk_bf16_f32 v70, v70, v71
	s_waitcnt lgkmcnt(0)
	v_mov_b64_e32 v[140:141], s[50:51]
	v_cvt_pk_bf16_f32 v71, v72, v73
	v_cvt_pk_bf16_f32 v72, v66, v67
	v_add_u32_e32 v66, 0x80, v150
	v_mad_i64_i32 v[148:149], s[50:51], v150, s17, v[140:141]
	v_lshlrev_b64 v[142:143], 1, v[142:143]
	v_cvt_pk_bf16_f32 v114, v114, v115
	v_cvt_pk_bf16_f32 v115, v116, v117
	v_cvt_pk_bf16_f32 v116, v106, v107
	v_or_b32_e32 v106, 16, v150
	v_mad_i64_i32 v[66:67], s[50:51], v66, s17, v[140:141]
	v_cvt_pk_bf16_f32 v50, v50, v51
	v_cvt_pk_bf16_f32 v51, v52, v53
	v_cvt_pk_bf16_f32 v52, v42, v43
	v_add_u32_e32 v42, 0x90, v150
	v_lshl_add_u64 v[148:149], v[148:149], 0, v[142:143]
	v_mad_i64_i32 v[106:107], s[50:51], v106, s17, v[140:141]
	v_cvt_pk_bf16_f32 v98, v98, v99
	v_cvt_pk_bf16_f32 v99, v100, v101
	v_cvt_pk_bf16_f32 v100, v90, v91
	v_or_b32_e32 v90, 32, v150
	v_lshl_add_u64 v[66:67], v[66:67], 0, v[142:143]
	v_mad_i64_i32 v[42:43], s[50:51], v42, s17, v[140:141]
	v_cvt_pk_bf16_f32 v34, v34, v35
	v_cvt_pk_bf16_f32 v35, v36, v37
	v_cvt_pk_bf16_f32 v36, v26, v27
	v_add_u32_e32 v26, 0xa0, v150
	v_cvt_pk_bf16_f32 v117, v108, v109
	global_store_dwordx4 v[148:149], v[114:117], off offset:256
	v_mad_i64_i32 v[90:91], s[50:51], v90, s17, v[140:141]
	s_nop 0
	v_lshl_add_u64 v[114:115], v[106:107], 0, v[142:143]
	v_cvt_pk_bf16_f32 v82, v82, v83
	v_cvt_pk_bf16_f32 v83, v84, v85
	v_cvt_pk_bf16_f32 v84, v74, v75
	v_or_b32_e32 v74, 48, v150
	v_cvt_pk_bf16_f32 v53, v44, v45
	global_store_dwordx4 v[66:67], v[50:53], off offset:256
	v_mad_i64_i32 v[26:27], s[50:51], v26, s17, v[140:141]
	s_nop 0
	v_lshl_add_u64 v[50:51], v[42:43], 0, v[142:143]
	v_cvt_pk_bf16_f32 v18, v18, v19
	v_cvt_pk_bf16_f32 v19, v20, v21
	v_cvt_pk_bf16_f32 v20, v10, v11
	v_add_u32_e32 v10, 0xb0, v150
	v_cvt_pk_bf16_f32 v101, v92, v93
	global_store_dwordx4 v[114:115], v[98:101], off offset:256
	v_mad_i64_i32 v[74:75], s[50:51], v74, s17, v[140:141]
	s_nop 0
	v_lshl_add_u64 v[98:99], v[90:91], 0, v[142:143]
	v_cvt_pk_bf16_f32 v37, v28, v29
	global_store_dwordx4 v[50:51], v[34:37], off offset:256
	v_mad_i64_i32 v[10:11], s[50:51], v10, s17, v[140:141]
	s_nop 0
	v_lshl_add_u64 v[34:35], v[26:27], 0, v[142:143]
	v_cvt_pk_bf16_f32 v85, v76, v77
	global_store_dwordx4 v[98:99], v[82:85], off offset:256
	v_cvt_pk_bf16_f32 v21, v12, v13
	global_store_dwordx4 v[34:35], v[18:21], off offset:256
	s_and_b64 vcc, exec, s[46:47]
	v_lshl_add_u64 v[82:83], v[74:75], 0, v[142:143]
	v_lshl_add_u64 v[18:19], v[10:11], 0, v[142:143]
	s_mov_b32 s40, s42
	s_mov_b32 s28, s8
	s_mov_b32 s43, s42
	s_mov_b32 s46, s8
	s_mov_b64 s[50:51], s[48:49]
	s_mov_b64 s[52:53], s[44:45]
	v_cvt_pk_bf16_f32 v126, v126, v127
	v_cvt_pk_bf16_f32 v127, v128, v129
	v_cvt_pk_bf16_f32 v128, v122, v123
	v_cvt_pk_bf16_f32 v129, v124, v125
	global_store_dwordx4 v[148:149], v[126:129], off
	v_cvt_pk_bf16_f32 v106, v118, v119
	v_cvt_pk_bf16_f32 v107, v120, v121
	v_cvt_pk_bf16_f32 v108, v110, v111
	v_cvt_pk_bf16_f32 v109, v112, v113
	global_store_dwordx4 v[114:115], v[106:109], off
	v_cvt_pk_bf16_f32 v90, v102, v103
	v_cvt_pk_bf16_f32 v91, v104, v105
	v_cvt_pk_bf16_f32 v92, v94, v95
	v_cvt_pk_bf16_f32 v93, v96, v97
	global_store_dwordx4 v[98:99], v[90:93], off
	v_cvt_pk_bf16_f32 v74, v86, v87
	v_cvt_pk_bf16_f32 v75, v88, v89
	v_cvt_pk_bf16_f32 v76, v78, v79
	v_cvt_pk_bf16_f32 v77, v80, v81
	global_store_dwordx4 v[82:83], v[74:77], off
	v_cvt_pk_bf16_f32 v73, v68, v69
	global_store_dwordx4 v[82:83], v[70:73], off offset:256
	v_cvt_pk_bf16_f32 v62, v62, v63
	v_cvt_pk_bf16_f32 v63, v64, v65
	v_cvt_pk_bf16_f32 v64, v58, v59
	v_cvt_pk_bf16_f32 v65, v60, v61
	global_store_dwordx4 v[66:67], v[62:65], off
	v_cvt_pk_bf16_f32 v42, v54, v55
	v_cvt_pk_bf16_f32 v43, v56, v57
	v_cvt_pk_bf16_f32 v44, v46, v47
	v_cvt_pk_bf16_f32 v45, v48, v49
	global_store_dwordx4 v[50:51], v[42:45], off
	v_cvt_pk_bf16_f32 v26, v38, v39
	v_cvt_pk_bf16_f32 v27, v40, v41
	v_cvt_pk_bf16_f32 v28, v30, v31
	v_cvt_pk_bf16_f32 v29, v32, v33
	global_store_dwordx4 v[34:35], v[26:29], off
	v_cvt_pk_bf16_f32 v10, v22, v23
	v_cvt_pk_bf16_f32 v11, v24, v25
	v_cvt_pk_bf16_f32 v12, v14, v15
	v_cvt_pk_bf16_f32 v13, v16, v17
	global_store_dwordx4 v[18:19], v[10:13], off
	v_cvt_pk_bf16_f32 v6, v6, v7
	v_cvt_pk_bf16_f32 v7, v8, v9
	v_cvt_pk_bf16_f32 v8, v2, v3
	v_cvt_pk_bf16_f32 v9, v4, v5
	global_store_dwordx4 v[18:19], v[6:9], off offset:256
	s_cbranch_vccz .LBB0_346
	s_waitcnt vmcnt(0)
	s_cmpk_gt_u32 s25, 0xff
	s_cbranch_scc1 .LBB0_358
	s_barrier
